# code placement (asm guide 9.3): every MFMA block of the five hot K-loops and the three peeled iterations starts at byte offset 0 mod 8 (one s_nop 0 pad in front of the preceding barrier where needed)
# baseline (speedup 1.0000x reference)
; #define PG8_STAGE(bufoff, gbase, voff) do { _Pragma("unroll") for (int _i = 0; _i < 2; ++_i) \
;         __builtin_amdgcn_global_load_lds((const unsigned*)((const char*)(gbase) + (voff)[_i]), (LAS unsigned*)(lds + (bufoff) + ldsw + _i * 8192), 16, 0, 0); } while (0)
; #define PG8_LDA(dst, b, h) do { _Pragma("unroll") for (int m = 0; m < 4; ++m) _Pragma("unroll") for (int k = 0; k < 2; ++k) dst[m][k] = *(const LAS bf16x8*)(lds + PG8_SA(b, h) + aoff + m * 2048 + k * 1024); } while (0)
; #define PG8_LDB(dst, b, h) do { _Pragma("unroll") for (int n = 0; n < 2; ++n) _Pragma("unroll") for (int k = 0; k < 2; ++k) dst[n][k] = *(const LAS bf16x8*)(lds + PG8_SB(b, h) + boff + n * 2048 + k * 1024); } while (0)
; #define PG8_MMA(ai, bj, At, Bt) do { __builtin_amdgcn_s_setprio(1); _Pragma("unroll") for (int m = 0; m < 4; ++m) _Pragma("unroll") for (int n = 0; n < 2; ++n) _Pragma("unroll") for (int k = 0; k < 2; ++k) \
;         acc[ai][bj][m][n] = __builtin_amdgcn_mfma_f32_16x16x32_bf16(Bt[n][k], At[m][k], acc[ai][bj][m][n], 0, 0, 0); __builtin_amdgcn_s_setprio(0); } while (0)
; #define PG8_WAIT_V(n) asm volatile("s_waitcnt vmcnt(" #n ")" ::: "memory")
; #define PG8_WAIT_L(n) asm volatile("s_waitcnt lgkmcnt(" #n ")" ::: "memory")
; #define PG8_BAR __builtin_amdgcn_s_barrier()
; #define PG8_SCHED __builtin_amdgcn_sched_barrier(0)
; template <class Epi, class Sched>
; __device__ __forceinline__ void gemm_phase(LAS unsigned char* lds, const Gemm g, const Sched& S, const Epi& E) {
;     ...
;             PG8_LDB(B0, 0, 0); PG8_LDB(B1, 0, 1); PG8_SCHED; PG8_LDA(At, 0, 0); PG8_STAGE(PG8_SA(1, 1), a1 + hstepA, voffA);
;             PG8_WAIT_V(8); PG8_WAIT_L(0); PG8_BAR; PG8_MMA(0, 0, At, B0); PG8_MMA(0, 1, At, B1); PG8_BAR; PG8_SCHED;
;             PG8_LDA(At, 0, 1); PG8_STAGE(PG8_SB(0, 0), b2, voffB); PG8_STAGE(PG8_SB(0, 1), b2 + hstepB, voffB); PG8_STAGE(PG8_SA(0, 0), a2, voffA);
;             PG8_WAIT_V(8); PG8_WAIT_L(0); PG8_BAR; PG8_MMA(1, 0, At, B0); PG8_MMA(1, 1, At, B1); PG8_BAR; PG8_SCHED;
.LBB0_231:
	s_ashr_i32 s83, s82, 31
	s_lshl_b64 s[36:37], s[82:83], 19
	s_add_u32 s84, s4, s36
	s_addc_u32 s85, s5, s37
	s_and_b64 s[36:37], s[70:71], exec
	s_cselect_b32 s43, s85, s19
	s_cselect_b32 s48, s84, s18
	s_ashr_i32 s81, s80, 31
	s_lshl_b64 s[36:37], s[80:81], 19
	v_readlane_b32 s12, v248, 5
	s_add_u32 s36, s12, s36
	v_readlane_b32 s12, v248, 6
	s_addc_u32 s37, s12, s37
	s_and_b64 s[86:87], s[70:71], exec
	s_cselect_b32 s49, s37, s21
	s_cselect_b32 s53, s36, s20
	s_add_u32 s18, s18, 0x40080
	s_addc_u32 s19, s19, 0
	s_add_u32 s54, s20, 0x100
	s_addc_u32 s81, s21, 0
	s_mov_b32 s83, -2
	s_add_u32 s20, s18, 0xfffc0080
	s_addc_u32 s21, s19, -1
	s_add_i32 s88, 0, 0x10000
	s_cmp_eq_u32 s83, 12
	s_cselect_b32 s21, s43, s21
	s_cselect_b32 s20, s48, s20
	s_cselect_b32 s87, s49, s81
	s_cselect_b32 s86, s53, s54
	s_add_i32 s90, 0, 0x14000
	s_add_u32 s100, s20, 0x80
	s_addc_u32 s101, s21, 0
	s_add_i32 m0, s9, 0xc000
	s_nop 0
	global_load_lds_dwordx4 v170, s[18:19]
	s_add_i32 m0, s9, 0xe000
	s_nop 0
	global_load_lds_dwordx4 v190, s[18:19]
	ds_read_b128 v[130:133], v246
	ds_read_b128 v[134:137], v246 offset:1024
	ds_read_b128 v[138:141], v246 offset:2048
	ds_read_b128 v[142:145], v246 offset:3072
	ds_read_b128 v[146:149], v246 offset:16384
	ds_read_b128 v[150:153], v246 offset:17408
	ds_read_b128 v[154:157], v246 offset:18432
	ds_read_b128 v[158:161], v246 offset:19456
	ds_read_b128 v[162:165], v222
	ds_read_b128 v[166:169], v222 offset:1024
	ds_read_b128 v[194:197], v222 offset:2048
	ds_read_b128 v[198:201], v222 offset:3072
	ds_read_b128 v[202:205], v222 offset:4096
	ds_read_b128 v[224:227], v222 offset:5120
	ds_read_b128 v[228:231], v222 offset:6144
	ds_read_b128 v[232:235], v222 offset:7168
	s_waitcnt vmcnt(8)
	s_waitcnt lgkmcnt(0)
	s_nop 0
	s_barrier
	s_waitcnt lgkmcnt(0)
	v_mfma_f32_16x16x32_bf16 v[126:129], v[130:133], v[162:165], 0
	v_mfma_f32_16x16x32_bf16 v[118:121], v[138:141], v[162:165], 0
	v_mfma_f32_16x16x32_bf16 v[110:113], v[130:133], v[194:197], 0
	v_mfma_f32_16x16x32_bf16 v[102:105], v[138:141], v[194:197], 0
	v_mfma_f32_16x16x32_bf16 v[94:97], v[130:133], v[202:205], 0
	v_mfma_f32_16x16x32_bf16 v[86:89], v[138:141], v[202:205], 0
	v_mfma_f32_16x16x32_bf16 v[78:81], v[130:133], v[228:231], 0
	v_mfma_f32_16x16x32_bf16 v[70:73], v[138:141], v[228:231], 0
	v_mfma_f32_16x16x32_bf16 v[126:129], v[134:137], v[166:169], v[126:129]
	v_mfma_f32_16x16x32_bf16 v[118:121], v[142:145], v[166:169], v[118:121]
	v_mfma_f32_16x16x32_bf16 v[110:113], v[134:137], v[198:201], v[110:113]
	v_mfma_f32_16x16x32_bf16 v[102:105], v[142:145], v[198:201], v[102:105]
	v_mfma_f32_16x16x32_bf16 v[94:97], v[134:137], v[224:227], v[94:97]
	v_mfma_f32_16x16x32_bf16 v[86:89], v[142:145], v[224:227], v[86:89]
	v_mfma_f32_16x16x32_bf16 v[78:81], v[134:137], v[232:235], v[78:81]
	v_mfma_f32_16x16x32_bf16 v[70:73], v[142:145], v[232:235], v[70:73]
	v_mfma_f32_16x16x32_bf16 v[122:125], v[146:149], v[162:165], 0
	v_mfma_f32_16x16x32_bf16 v[114:117], v[154:157], v[162:165], 0
	v_mfma_f32_16x16x32_bf16 v[106:109], v[146:149], v[194:197], 0
	v_mfma_f32_16x16x32_bf16 v[98:101], v[154:157], v[194:197], 0
	v_mfma_f32_16x16x32_bf16 v[90:93], v[146:149], v[202:205], 0
	v_mfma_f32_16x16x32_bf16 v[82:85], v[154:157], v[202:205], 0
	v_mfma_f32_16x16x32_bf16 v[74:77], v[146:149], v[228:231], 0
	v_mfma_f32_16x16x32_bf16 v[66:69], v[154:157], v[228:231], 0
	v_mfma_f32_16x16x32_bf16 v[122:125], v[150:153], v[166:169], v[122:125]
	v_mfma_f32_16x16x32_bf16 v[114:117], v[158:161], v[166:169], v[114:117]
	v_mfma_f32_16x16x32_bf16 v[106:109], v[150:153], v[198:201], v[106:109]
	v_mfma_f32_16x16x32_bf16 v[98:101], v[158:161], v[198:201], v[98:101]
	v_mfma_f32_16x16x32_bf16 v[90:93], v[150:153], v[224:227], v[90:93]
	v_mfma_f32_16x16x32_bf16 v[82:85], v[158:161], v[224:227], v[82:85]
	v_mfma_f32_16x16x32_bf16 v[74:77], v[150:153], v[232:235], v[74:77]
	v_mfma_f32_16x16x32_bf16 v[66:69], v[158:161], v[232:235], v[66:69]
	s_barrier
	s_add_i32 s88, s88, s8
	s_mov_b32 m0, s88
	s_nop 0
	global_load_lds_dwordx4 v172, s[86:87]
	s_add_i32 m0, s88, 0x2000
	s_add_u32 s88, s86, 0x40000
	s_addc_u32 s89, s87, 0
	s_add_i32 s90, s90, s8
	global_load_lds_dwordx4 v192, s[86:87]
	s_mov_b32 m0, s90
	s_nop 0
	global_load_lds_dwordx4 v172, s[88:89]
	s_add_i32 m0, s90, 0x2000
	s_nop 0
	global_load_lds_dwordx4 v192, s[88:89]
	s_mov_b32 m0, s9
	s_nop 0
	global_load_lds_dwordx4 v170, s[20:21]
	s_mov_b32 m0, s28
	s_nop 0
	global_load_lds_dwordx4 v190, s[20:21]
	ds_read_b128 v[162:165], v222 offset:16384
	ds_read_b128 v[166:169], v222 offset:17408
	ds_read_b128 v[194:197], v222 offset:18432
	ds_read_b128 v[198:201], v222 offset:19456
	ds_read_b128 v[202:205], v222 offset:20480
	ds_read_b128 v[224:227], v222 offset:21504
	ds_read_b128 v[228:231], v222 offset:22528
	ds_read_b128 v[232:235], v222 offset:23552
	s_waitcnt vmcnt(8)
	s_waitcnt lgkmcnt(0)
	s_nop 0
	s_barrier
; #define PG8_STAGE(bufoff, gbase, voff) do { _Pragma("unroll") for (int _i = 0; _i < 2; ++_i) \
;         __builtin_amdgcn_global_load_lds((const unsigned*)((const char*)(gbase) + (voff)[_i]), (LAS unsigned*)(lds + (bufoff) + ldsw + _i * 8192), 16, 0, 0); } while (0)
; #define PG8_LDA(dst, b, h) do { _Pragma("unroll") for (int m = 0; m < 4; ++m) _Pragma("unroll") for (int k = 0; k < 2; ++k) dst[m][k] = *(const LAS bf16x8*)(lds + PG8_SA(b, h) + aoff + m * 2048 + k * 1024); } while (0)
; #define PG8_LDB(dst, b, h) do { _Pragma("unroll") for (int n = 0; n < 2; ++n) _Pragma("unroll") for (int k = 0; k < 2; ++k) dst[n][k] = *(const LAS bf16x8*)(lds + PG8_SB(b, h) + boff + n * 2048 + k * 1024); } while (0)
; #define PG8_MMA(ai, bj, At, Bt) do { __builtin_amdgcn_s_setprio(1); _Pragma("unroll") for (int m = 0; m < 4; ++m) _Pragma("unroll") for (int n = 0; n < 2; ++n) _Pragma("unroll") for (int k = 0; k < 2; ++k) \
;         acc[ai][bj][m][n] = __builtin_amdgcn_mfma_f32_16x16x32_bf16(Bt[n][k], At[m][k], acc[ai][bj][m][n], 0, 0, 0); __builtin_amdgcn_s_setprio(0); } while (0)
; #define PG8_WAIT_V(n) asm volatile("s_waitcnt vmcnt(" #n ")" ::: "memory")
; #define PG8_WAIT_L(n) asm volatile("s_waitcnt lgkmcnt(" #n ")" ::: "memory")
; #define PG8_BAR __builtin_amdgcn_s_barrier()
; #define PG8_SCHED __builtin_amdgcn_sched_barrier(0)
; template <class Epi, class Sched>
; __device__ __forceinline__ void gemm_phase(LAS unsigned char* lds, const Gemm g, const Sched& S, const Epi& E) {
;     ...
;             PG8_WAIT_V(8); PG8_WAIT_L(0); PG8_BAR; PG8_MMA(1, 0, At, B0); PG8_MMA(1, 1, At, B1); PG8_BAR; PG8_SCHED;
;             PG8_LDB(B0, 1, 0); PG8_LDB(B1, 1, 1); PG8_SCHED; PG8_LDA(At, 1, 0); PG8_STAGE(PG8_SA(0, 1), a2 + hstepA, voffA);
;             PG8_WAIT_V(8); PG8_WAIT_L(0); PG8_BAR; PG8_MMA(0, 0, At, B0); PG8_MMA(0, 1, At, B1); PG8_BAR; PG8_SCHED;
;             PG8_LDA(At, 1, 1); PG8_STAGE(PG8_SB(1, 0), b3, voffB); PG8_STAGE(PG8_SB(1, 1), b3 + hstepB, voffB); PG8_STAGE(PG8_SA(1, 0), a3, voffA);
;             PG8_WAIT_V(8); PG8_WAIT_L(0); PG8_BAR; PG8_MMA(1, 0, At, B0); PG8_MMA(1, 1, At, B1); PG8_BAR; PG8_SCHED;
	s_waitcnt lgkmcnt(0)
	v_mfma_f32_16x16x32_bf16 v[62:65], v[130:133], v[162:165], 0
	v_mfma_f32_16x16x32_bf16 v[54:57], v[138:141], v[162:165], 0
	v_mfma_f32_16x16x32_bf16 v[46:49], v[130:133], v[194:197], 0
	v_mfma_f32_16x16x32_bf16 v[38:41], v[138:141], v[194:197], 0
	v_mfma_f32_16x16x32_bf16 v[30:33], v[130:133], v[202:205], 0
	v_mfma_f32_16x16x32_bf16 v[22:25], v[138:141], v[202:205], 0
	v_mfma_f32_16x16x32_bf16 v[14:17], v[130:133], v[228:231], 0
	v_mfma_f32_16x16x32_bf16 v[6:9], v[138:141], v[228:231], 0
	v_mfma_f32_16x16x32_bf16 v[62:65], v[134:137], v[166:169], v[62:65]
	v_mfma_f32_16x16x32_bf16 v[54:57], v[142:145], v[166:169], v[54:57]
	v_mfma_f32_16x16x32_bf16 v[46:49], v[134:137], v[198:201], v[46:49]
	v_mfma_f32_16x16x32_bf16 v[38:41], v[142:145], v[198:201], v[38:41]
	v_mfma_f32_16x16x32_bf16 v[30:33], v[134:137], v[224:227], v[30:33]
	v_mfma_f32_16x16x32_bf16 v[22:25], v[142:145], v[224:227], v[22:25]
	v_mfma_f32_16x16x32_bf16 v[14:17], v[134:137], v[232:235], v[14:17]
	v_mfma_f32_16x16x32_bf16 v[6:9], v[142:145], v[232:235], v[6:9]
	v_mfma_f32_16x16x32_bf16 v[58:61], v[146:149], v[162:165], 0
	v_mfma_f32_16x16x32_bf16 v[50:53], v[154:157], v[162:165], 0
	v_mfma_f32_16x16x32_bf16 v[42:45], v[146:149], v[194:197], 0
	v_mfma_f32_16x16x32_bf16 v[34:37], v[154:157], v[194:197], 0
	v_mfma_f32_16x16x32_bf16 v[26:29], v[146:149], v[202:205], 0
	v_mfma_f32_16x16x32_bf16 v[18:21], v[154:157], v[202:205], 0
	v_mfma_f32_16x16x32_bf16 v[10:13], v[146:149], v[228:231], 0
	v_mfma_f32_16x16x32_bf16 v[2:5], v[154:157], v[228:231], 0
	v_mfma_f32_16x16x32_bf16 v[58:61], v[150:153], v[166:169], v[58:61]
	v_mfma_f32_16x16x32_bf16 v[50:53], v[158:161], v[166:169], v[50:53]
	v_mfma_f32_16x16x32_bf16 v[42:45], v[150:153], v[198:201], v[42:45]
	v_mfma_f32_16x16x32_bf16 v[34:37], v[158:161], v[198:201], v[34:37]
	v_mfma_f32_16x16x32_bf16 v[26:29], v[150:153], v[224:227], v[26:29]
	v_mfma_f32_16x16x32_bf16 v[18:21], v[158:161], v[224:227], v[18:21]
	v_mfma_f32_16x16x32_bf16 v[10:13], v[150:153], v[232:235], v[10:13]
	v_mfma_f32_16x16x32_bf16 v[2:5], v[158:161], v[232:235], v[2:5]
	s_barrier
	s_add_i32 s88, 0, 0x18000
	s_add_i32 s89, 0, 0x1c000
	s_add_u32 s20, s20, 0x40000
	s_addc_u32 s21, s21, 0
	s_mov_b32 m0, s29
	s_nop 0
	global_load_lds_dwordx4 v170, s[20:21]
	s_mov_b32 m0, s30
	s_nop 0
	global_load_lds_dwordx4 v190, s[20:21]
	ds_read_b128 v[130:133], v246 offset:32768
	ds_read_b128 v[134:137], v246 offset:33792
	ds_read_b128 v[138:141], v246 offset:34816
	ds_read_b128 v[142:145], v246 offset:35840
	ds_read_b128 v[146:149], v246 offset:49152
	ds_read_b128 v[150:153], v246 offset:50176
	ds_read_b128 v[154:157], v246 offset:51200
	ds_read_b128 v[158:161], v246 offset:52224
	ds_read_b128 v[162:165], v222 offset:32768
	ds_read_b128 v[166:169], v222 offset:33792
	ds_read_b128 v[194:197], v222 offset:34816
	ds_read_b128 v[198:201], v222 offset:35840
	ds_read_b128 v[202:205], v222 offset:36864
	ds_read_b128 v[224:227], v222 offset:37888
	ds_read_b128 v[228:231], v222 offset:38912
	ds_read_b128 v[232:235], v222 offset:39936
	s_waitcnt vmcnt(8)
	s_waitcnt lgkmcnt(0)
	s_barrier
	s_waitcnt lgkmcnt(0)
	v_mfma_f32_16x16x32_bf16 v[126:129], v[130:133], v[162:165], v[126:129]
	v_mfma_f32_16x16x32_bf16 v[118:121], v[138:141], v[162:165], v[118:121]
	v_mfma_f32_16x16x32_bf16 v[110:113], v[130:133], v[194:197], v[110:113]
	v_mfma_f32_16x16x32_bf16 v[102:105], v[138:141], v[194:197], v[102:105]
	v_mfma_f32_16x16x32_bf16 v[94:97], v[130:133], v[202:205], v[94:97]
	v_mfma_f32_16x16x32_bf16 v[86:89], v[138:141], v[202:205], v[86:89]
	v_mfma_f32_16x16x32_bf16 v[78:81], v[130:133], v[228:231], v[78:81]
	v_mfma_f32_16x16x32_bf16 v[70:73], v[138:141], v[228:231], v[70:73]
	v_mfma_f32_16x16x32_bf16 v[126:129], v[134:137], v[166:169], v[126:129]
	v_mfma_f32_16x16x32_bf16 v[118:121], v[142:145], v[166:169], v[118:121]
	v_mfma_f32_16x16x32_bf16 v[110:113], v[134:137], v[198:201], v[110:113]
	v_mfma_f32_16x16x32_bf16 v[102:105], v[142:145], v[198:201], v[102:105]
	v_mfma_f32_16x16x32_bf16 v[94:97], v[134:137], v[224:227], v[94:97]
	v_mfma_f32_16x16x32_bf16 v[86:89], v[142:145], v[224:227], v[86:89]
	v_mfma_f32_16x16x32_bf16 v[78:81], v[134:137], v[232:235], v[78:81]
	v_mfma_f32_16x16x32_bf16 v[70:73], v[142:145], v[232:235], v[70:73]
	v_mfma_f32_16x16x32_bf16 v[122:125], v[146:149], v[162:165], v[122:125]
	v_mfma_f32_16x16x32_bf16 v[114:117], v[154:157], v[162:165], v[114:117]
	v_mfma_f32_16x16x32_bf16 v[106:109], v[146:149], v[194:197], v[106:109]
	v_mfma_f32_16x16x32_bf16 v[98:101], v[154:157], v[194:197], v[98:101]
	v_mfma_f32_16x16x32_bf16 v[90:93], v[146:149], v[202:205], v[90:93]
	v_mfma_f32_16x16x32_bf16 v[82:85], v[154:157], v[202:205], v[82:85]
	v_mfma_f32_16x16x32_bf16 v[74:77], v[146:149], v[228:231], v[74:77]
	v_mfma_f32_16x16x32_bf16 v[66:69], v[154:157], v[228:231], v[66:69]
	v_mfma_f32_16x16x32_bf16 v[122:125], v[150:153], v[166:169], v[122:125]
	v_mfma_f32_16x16x32_bf16 v[114:117], v[158:161], v[166:169], v[114:117]
	v_mfma_f32_16x16x32_bf16 v[106:109], v[150:153], v[198:201], v[106:109]
	v_mfma_f32_16x16x32_bf16 v[98:101], v[158:161], v[198:201], v[98:101]
	v_mfma_f32_16x16x32_bf16 v[90:93], v[150:153], v[224:227], v[90:93]
	v_mfma_f32_16x16x32_bf16 v[82:85], v[158:161], v[224:227], v[82:85]
	v_mfma_f32_16x16x32_bf16 v[74:77], v[150:153], v[232:235], v[74:77]
	v_mfma_f32_16x16x32_bf16 v[66:69], v[158:161], v[232:235], v[66:69]
	s_barrier
; #define PG8_STAGE(bufoff, gbase, voff) do { _Pragma("unroll") for (int _i = 0; _i < 2; ++_i) \
;         __builtin_amdgcn_global_load_lds((const unsigned*)((const char*)(gbase) + (voff)[_i]), (LAS unsigned*)(lds + (bufoff) + ldsw + _i * 8192), 16, 0, 0); } while (0)
; #define PG8_LDA(dst, b, h) do { _Pragma("unroll") for (int m = 0; m < 4; ++m) _Pragma("unroll") for (int k = 0; k < 2; ++k) dst[m][k] = *(const LAS bf16x8*)(lds + PG8_SA(b, h) + aoff + m * 2048 + k * 1024); } while (0)
; #define PG8_LDB(dst, b, h) do { _Pragma("unroll") for (int n = 0; n < 2; ++n) _Pragma("unroll") for (int k = 0; k < 2; ++k) dst[n][k] = *(const LAS bf16x8*)(lds + PG8_SB(b, h) + boff + n * 2048 + k * 1024); } while (0)
; #define PG8_MMA(ai, bj, At, Bt) do { __builtin_amdgcn_s_setprio(1); _Pragma("unroll") for (int m = 0; m < 4; ++m) _Pragma("unroll") for (int n = 0; n < 2; ++n) _Pragma("unroll") for (int k = 0; k < 2; ++k) \
;         acc[ai][bj][m][n] = __builtin_amdgcn_mfma_f32_16x16x32_bf16(Bt[n][k], At[m][k], acc[ai][bj][m][n], 0, 0, 0); __builtin_amdgcn_s_setprio(0); } while (0)
; #define PG8_WAIT_V(n) asm volatile("s_waitcnt vmcnt(" #n ")" ::: "memory")
; #define PG8_WAIT_L(n) asm volatile("s_waitcnt lgkmcnt(" #n ")" ::: "memory")
; #define PG8_BAR __builtin_amdgcn_s_barrier()
; #define PG8_SCHED __builtin_amdgcn_sched_barrier(0)
; template <class Epi, class Sched>
; __device__ __forceinline__ void gemm_phase(LAS unsigned char* lds, const Gemm g, const Sched& S, const Epi& E) {
;     ...
;             PG8_LDB(B0, 0, 0); PG8_LDB(B1, 0, 1); PG8_SCHED; PG8_LDA(At, 0, 0); PG8_STAGE(PG8_SA(1, 1), a1 + hstepA, voffA);
;             PG8_WAIT_V(8); PG8_WAIT_L(0); PG8_BAR; PG8_MMA(0, 0, At, B0); PG8_MMA(0, 1, At, B1); PG8_BAR; PG8_SCHED;
;     ...
;             PG8_LDA(At, 1, 1); PG8_STAGE(PG8_SB(1, 0), b3, voffB); PG8_STAGE(PG8_SB(1, 1), b3 + hstepB, voffB); PG8_STAGE(PG8_SA(1, 0), a3, voffA);
;             PG8_WAIT_V(8); PG8_WAIT_L(0); PG8_BAR; PG8_MMA(1, 0, At, B0); PG8_MMA(1, 1, At, B1); PG8_BAR; PG8_SCHED;
	s_add_i32 s20, s8, 0x18000
	s_add_u32 s88, s86, 0x80
	s_addc_u32 s89, s87, 0
	s_mov_b32 m0, s20
	s_nop 0
	global_load_lds_dwordx4 v172, s[88:89]
	s_add_i32 m0, s20, 0x2000
	s_add_u32 s20, s86, 0x40080
	s_addc_u32 s21, s87, 0
	s_add_i32 s12, s8, 0x1c000
	global_load_lds_dwordx4 v192, s[88:89]
	s_mov_b32 m0, s12
	s_nop 0
	global_load_lds_dwordx4 v172, s[20:21]
	s_add_i32 m0, s12, 0x2000
	s_nop 0
	global_load_lds_dwordx4 v192, s[20:21]
	s_mov_b32 m0, s31
	s_nop 0
	global_load_lds_dwordx4 v170, s[100:101]
	s_mov_b32 m0, s34
	s_nop 0
	global_load_lds_dwordx4 v190, s[100:101]
	ds_read_b128 v[162:165], v222 offset:49152
	ds_read_b128 v[166:169], v222 offset:50176
	ds_read_b128 v[194:197], v222 offset:51200
	ds_read_b128 v[198:201], v222 offset:52224
	ds_read_b128 v[202:205], v222 offset:53248
	ds_read_b128 v[224:227], v222 offset:54272
	ds_read_b128 v[228:231], v222 offset:55296
	ds_read_b128 v[232:235], v222 offset:56320
	s_waitcnt vmcnt(8)
	s_waitcnt lgkmcnt(0)
	s_barrier
	s_waitcnt lgkmcnt(0)
	v_mfma_f32_16x16x32_bf16 v[62:65], v[130:133], v[162:165], v[62:65]
	v_mfma_f32_16x16x32_bf16 v[54:57], v[138:141], v[162:165], v[54:57]
	v_mfma_f32_16x16x32_bf16 v[46:49], v[130:133], v[194:197], v[46:49]
	v_mfma_f32_16x16x32_bf16 v[38:41], v[138:141], v[194:197], v[38:41]
	v_mfma_f32_16x16x32_bf16 v[30:33], v[130:133], v[202:205], v[30:33]
	v_mfma_f32_16x16x32_bf16 v[22:25], v[138:141], v[202:205], v[22:25]
	v_mfma_f32_16x16x32_bf16 v[14:17], v[130:133], v[228:231], v[14:17]
	v_mfma_f32_16x16x32_bf16 v[6:9], v[138:141], v[228:231], v[6:9]
	v_mfma_f32_16x16x32_bf16 v[62:65], v[134:137], v[166:169], v[62:65]
	v_mfma_f32_16x16x32_bf16 v[54:57], v[142:145], v[166:169], v[54:57]
	v_mfma_f32_16x16x32_bf16 v[46:49], v[134:137], v[198:201], v[46:49]
	v_mfma_f32_16x16x32_bf16 v[38:41], v[142:145], v[198:201], v[38:41]
	v_mfma_f32_16x16x32_bf16 v[30:33], v[134:137], v[224:227], v[30:33]
	v_mfma_f32_16x16x32_bf16 v[22:25], v[142:145], v[224:227], v[22:25]
	v_mfma_f32_16x16x32_bf16 v[14:17], v[134:137], v[232:235], v[14:17]
	v_mfma_f32_16x16x32_bf16 v[6:9], v[142:145], v[232:235], v[6:9]
	v_mfma_f32_16x16x32_bf16 v[58:61], v[146:149], v[162:165], v[58:61]
	v_mfma_f32_16x16x32_bf16 v[50:53], v[154:157], v[162:165], v[50:53]
	v_mfma_f32_16x16x32_bf16 v[42:45], v[146:149], v[194:197], v[42:45]
	v_mfma_f32_16x16x32_bf16 v[34:37], v[154:157], v[194:197], v[34:37]
	v_mfma_f32_16x16x32_bf16 v[26:29], v[146:149], v[202:205], v[26:29]
	v_mfma_f32_16x16x32_bf16 v[18:21], v[154:157], v[202:205], v[18:21]
	v_mfma_f32_16x16x32_bf16 v[10:13], v[146:149], v[228:231], v[10:13]
	v_mfma_f32_16x16x32_bf16 v[2:5], v[154:157], v[228:231], v[2:5]
	v_mfma_f32_16x16x32_bf16 v[58:61], v[150:153], v[166:169], v[58:61]
	v_mfma_f32_16x16x32_bf16 v[50:53], v[158:161], v[166:169], v[50:53]
	v_mfma_f32_16x16x32_bf16 v[42:45], v[150:153], v[198:201], v[42:45]
	v_mfma_f32_16x16x32_bf16 v[34:37], v[158:161], v[198:201], v[34:37]
	v_mfma_f32_16x16x32_bf16 v[26:29], v[150:153], v[224:227], v[26:29]
	v_mfma_f32_16x16x32_bf16 v[18:21], v[158:161], v[224:227], v[18:21]
	v_mfma_f32_16x16x32_bf16 v[10:13], v[150:153], v[232:235], v[10:13]
	v_mfma_f32_16x16x32_bf16 v[2:5], v[158:161], v[232:235], v[2:5]
	s_barrier
	s_add_i32 s83, s83, 2
	s_add_u32 s18, s18, 0x100
	s_addc_u32 s19, s19, 0
	s_add_u32 s54, s54, 0x100
	s_addc_u32 s81, s81, 0
	s_cmp_gt_u32 s83, 13
.LBB0_232:
	s_add_u32 s20, s18, 0xfffc0080
	s_addc_u32 s21, s19, -1
	s_add_i32 s88, 0, 0x10000
	s_cmp_eq_u32 s83, 12
	s_cselect_b32 s21, s43, s21
	s_cselect_b32 s20, s48, s20
	s_cselect_b32 s87, s49, s81
	s_cselect_b32 s86, s53, s54
	s_add_i32 s90, 0, 0x14000
	s_add_u32 s100, s20, 0x80
	s_addc_u32 s101, s21, 0
	s_add_i32 m0, s9, 0xc000
	s_nop 0
	global_load_lds_dwordx4 v170, s[18:19]
	s_add_i32 m0, s9, 0xe000
	s_nop 0
	global_load_lds_dwordx4 v190, s[18:19]
	ds_read_b128 v[130:133], v246
	ds_read_b128 v[134:137], v246 offset:1024
	ds_read_b128 v[138:141], v246 offset:2048
	ds_read_b128 v[142:145], v246 offset:3072
	ds_read_b128 v[146:149], v246 offset:16384
	ds_read_b128 v[150:153], v246 offset:17408
	ds_read_b128 v[154:157], v246 offset:18432
	ds_read_b128 v[158:161], v246 offset:19456
	ds_read_b128 v[162:165], v222
	ds_read_b128 v[166:169], v222 offset:1024
	ds_read_b128 v[194:197], v222 offset:2048
	ds_read_b128 v[198:201], v222 offset:3072
	ds_read_b128 v[202:205], v222 offset:4096
	ds_read_b128 v[224:227], v222 offset:5120
	ds_read_b128 v[228:231], v222 offset:6144
	ds_read_b128 v[232:235], v222 offset:7168
	s_waitcnt vmcnt(8)
	s_waitcnt lgkmcnt(0)
	s_barrier
; #define PG8_STAGE(bufoff, gbase, voff) do { _Pragma("unroll") for (int _i = 0; _i < 2; ++_i) \
;         __builtin_amdgcn_global_load_lds((const unsigned*)((const char*)(gbase) + (voff)[_i]), (LAS unsigned*)(lds + (bufoff) + ldsw + _i * 8192), 16, 0, 0); } while (0)
; #define PG8_LDA(dst, b, h) do { _Pragma("unroll") for (int m = 0; m < 4; ++m) _Pragma("unroll") for (int k = 0; k < 2; ++k) dst[m][k] = *(const LAS bf16x8*)(lds + PG8_SA(b, h) + aoff + m * 2048 + k * 1024); } while (0)
; #define PG8_MMA(ai, bj, At, Bt) do { __builtin_amdgcn_s_setprio(1); _Pragma("unroll") for (int m = 0; m < 4; ++m) _Pragma("unroll") for (int n = 0; n < 2; ++n) _Pragma("unroll") for (int k = 0; k < 2; ++k) \
;         acc[ai][bj][m][n] = __builtin_amdgcn_mfma_f32_16x16x32_bf16(Bt[n][k], At[m][k], acc[ai][bj][m][n], 0, 0, 0); __builtin_amdgcn_s_setprio(0); } while (0)
; #define PG8_WAIT_V(n) asm volatile("s_waitcnt vmcnt(" #n ")" ::: "memory")
; #define PG8_WAIT_L(n) asm volatile("s_waitcnt lgkmcnt(" #n ")" ::: "memory")
; #define PG8_BAR __builtin_amdgcn_s_barrier()
; #define PG8_SCHED __builtin_amdgcn_sched_barrier(0)
; template <class Epi, class Sched>
; __device__ __forceinline__ void gemm_phase(LAS unsigned char* lds, const Gemm g, const Sched& S, const Epi& E) {
;     ...
;             PG8_WAIT_V(8); PG8_WAIT_L(0); PG8_BAR; PG8_MMA(0, 0, At, B0); PG8_MMA(0, 1, At, B1); PG8_BAR; PG8_SCHED;
;             PG8_LDA(At, 0, 1); PG8_STAGE(PG8_SB(0, 0), b2, voffB); PG8_STAGE(PG8_SB(0, 1), b2 + hstepB, voffB); PG8_STAGE(PG8_SA(0, 0), a2, voffA);
;             PG8_WAIT_V(8); PG8_WAIT_L(0); PG8_BAR; PG8_MMA(1, 0, At, B0); PG8_MMA(1, 1, At, B1); PG8_BAR; PG8_SCHED;
	s_waitcnt lgkmcnt(0)
	v_mfma_f32_16x16x32_bf16 v[126:129], v[130:133], v[162:165], v[126:129]
	v_mfma_f32_16x16x32_bf16 v[118:121], v[138:141], v[162:165], v[118:121]
	v_mfma_f32_16x16x32_bf16 v[110:113], v[130:133], v[194:197], v[110:113]
	v_mfma_f32_16x16x32_bf16 v[102:105], v[138:141], v[194:197], v[102:105]
	v_mfma_f32_16x16x32_bf16 v[94:97], v[130:133], v[202:205], v[94:97]
	v_mfma_f32_16x16x32_bf16 v[86:89], v[138:141], v[202:205], v[86:89]
	v_mfma_f32_16x16x32_bf16 v[78:81], v[130:133], v[228:231], v[78:81]
	v_mfma_f32_16x16x32_bf16 v[70:73], v[138:141], v[228:231], v[70:73]
	v_mfma_f32_16x16x32_bf16 v[126:129], v[134:137], v[166:169], v[126:129]
	v_mfma_f32_16x16x32_bf16 v[118:121], v[142:145], v[166:169], v[118:121]
	v_mfma_f32_16x16x32_bf16 v[110:113], v[134:137], v[198:201], v[110:113]
	v_mfma_f32_16x16x32_bf16 v[102:105], v[142:145], v[198:201], v[102:105]
	v_mfma_f32_16x16x32_bf16 v[94:97], v[134:137], v[224:227], v[94:97]
	v_mfma_f32_16x16x32_bf16 v[86:89], v[142:145], v[224:227], v[86:89]
	v_mfma_f32_16x16x32_bf16 v[78:81], v[134:137], v[232:235], v[78:81]
	v_mfma_f32_16x16x32_bf16 v[70:73], v[142:145], v[232:235], v[70:73]
	v_mfma_f32_16x16x32_bf16 v[122:125], v[146:149], v[162:165], v[122:125]
	v_mfma_f32_16x16x32_bf16 v[114:117], v[154:157], v[162:165], v[114:117]
	v_mfma_f32_16x16x32_bf16 v[106:109], v[146:149], v[194:197], v[106:109]
	v_mfma_f32_16x16x32_bf16 v[98:101], v[154:157], v[194:197], v[98:101]
	v_mfma_f32_16x16x32_bf16 v[90:93], v[146:149], v[202:205], v[90:93]
	v_mfma_f32_16x16x32_bf16 v[82:85], v[154:157], v[202:205], v[82:85]
	v_mfma_f32_16x16x32_bf16 v[74:77], v[146:149], v[228:231], v[74:77]
	v_mfma_f32_16x16x32_bf16 v[66:69], v[154:157], v[228:231], v[66:69]
	v_mfma_f32_16x16x32_bf16 v[122:125], v[150:153], v[166:169], v[122:125]
	v_mfma_f32_16x16x32_bf16 v[114:117], v[158:161], v[166:169], v[114:117]
	v_mfma_f32_16x16x32_bf16 v[106:109], v[150:153], v[198:201], v[106:109]
	v_mfma_f32_16x16x32_bf16 v[98:101], v[158:161], v[198:201], v[98:101]
	v_mfma_f32_16x16x32_bf16 v[90:93], v[150:153], v[224:227], v[90:93]
	v_mfma_f32_16x16x32_bf16 v[82:85], v[158:161], v[224:227], v[82:85]
	v_mfma_f32_16x16x32_bf16 v[74:77], v[150:153], v[232:235], v[74:77]
	v_mfma_f32_16x16x32_bf16 v[66:69], v[158:161], v[232:235], v[66:69]
	s_barrier
	s_add_i32 s88, s88, s8
	s_mov_b32 m0, s88
	s_nop 0
	global_load_lds_dwordx4 v172, s[86:87]
	s_add_i32 m0, s88, 0x2000
	s_add_u32 s88, s86, 0x40000
	s_addc_u32 s89, s87, 0
	s_add_i32 s90, s90, s8
	global_load_lds_dwordx4 v192, s[86:87]
	s_mov_b32 m0, s90
	s_nop 0
	global_load_lds_dwordx4 v172, s[88:89]
	s_add_i32 m0, s90, 0x2000
	s_nop 0
	global_load_lds_dwordx4 v192, s[88:89]
	s_mov_b32 m0, s9
	s_nop 0
	global_load_lds_dwordx4 v170, s[20:21]
	s_mov_b32 m0, s28
	s_nop 0
	global_load_lds_dwordx4 v190, s[20:21]
	ds_read_b128 v[162:165], v222 offset:16384
	ds_read_b128 v[166:169], v222 offset:17408
	ds_read_b128 v[194:197], v222 offset:18432
	ds_read_b128 v[198:201], v222 offset:19456
	ds_read_b128 v[202:205], v222 offset:20480
	ds_read_b128 v[224:227], v222 offset:21504
	ds_read_b128 v[228:231], v222 offset:22528
	ds_read_b128 v[232:235], v222 offset:23552
	s_waitcnt vmcnt(8)
	s_waitcnt lgkmcnt(0)
	s_nop 0
	s_barrier
	s_waitcnt lgkmcnt(0)
	v_mfma_f32_16x16x32_bf16 v[62:65], v[130:133], v[162:165], v[62:65]
	v_mfma_f32_16x16x32_bf16 v[54:57], v[138:141], v[162:165], v[54:57]
	v_mfma_f32_16x16x32_bf16 v[46:49], v[130:133], v[194:197], v[46:49]
	v_mfma_f32_16x16x32_bf16 v[38:41], v[138:141], v[194:197], v[38:41]
	v_mfma_f32_16x16x32_bf16 v[30:33], v[130:133], v[202:205], v[30:33]
	v_mfma_f32_16x16x32_bf16 v[22:25], v[138:141], v[202:205], v[22:25]
	v_mfma_f32_16x16x32_bf16 v[14:17], v[130:133], v[228:231], v[14:17]
	v_mfma_f32_16x16x32_bf16 v[6:9], v[138:141], v[228:231], v[6:9]
	v_mfma_f32_16x16x32_bf16 v[62:65], v[134:137], v[166:169], v[62:65]
	v_mfma_f32_16x16x32_bf16 v[54:57], v[142:145], v[166:169], v[54:57]
	v_mfma_f32_16x16x32_bf16 v[46:49], v[134:137], v[198:201], v[46:49]
	v_mfma_f32_16x16x32_bf16 v[38:41], v[142:145], v[198:201], v[38:41]
	v_mfma_f32_16x16x32_bf16 v[30:33], v[134:137], v[224:227], v[30:33]
	v_mfma_f32_16x16x32_bf16 v[22:25], v[142:145], v[224:227], v[22:25]
	v_mfma_f32_16x16x32_bf16 v[14:17], v[134:137], v[232:235], v[14:17]
	v_mfma_f32_16x16x32_bf16 v[6:9], v[142:145], v[232:235], v[6:9]
	v_mfma_f32_16x16x32_bf16 v[58:61], v[146:149], v[162:165], v[58:61]
	v_mfma_f32_16x16x32_bf16 v[50:53], v[154:157], v[162:165], v[50:53]
	v_mfma_f32_16x16x32_bf16 v[42:45], v[146:149], v[194:197], v[42:45]
	v_mfma_f32_16x16x32_bf16 v[34:37], v[154:157], v[194:197], v[34:37]
	v_mfma_f32_16x16x32_bf16 v[26:29], v[146:149], v[202:205], v[26:29]
	v_mfma_f32_16x16x32_bf16 v[18:21], v[154:157], v[202:205], v[18:21]
	v_mfma_f32_16x16x32_bf16 v[10:13], v[146:149], v[228:231], v[10:13]
	v_mfma_f32_16x16x32_bf16 v[2:5], v[154:157], v[228:231], v[2:5]
	v_mfma_f32_16x16x32_bf16 v[58:61], v[150:153], v[166:169], v[58:61]
	v_mfma_f32_16x16x32_bf16 v[50:53], v[158:161], v[166:169], v[50:53]
	v_mfma_f32_16x16x32_bf16 v[42:45], v[150:153], v[198:201], v[42:45]
	v_mfma_f32_16x16x32_bf16 v[34:37], v[158:161], v[198:201], v[34:37]
	v_mfma_f32_16x16x32_bf16 v[26:29], v[150:153], v[224:227], v[26:29]
	v_mfma_f32_16x16x32_bf16 v[18:21], v[158:161], v[224:227], v[18:21]
	v_mfma_f32_16x16x32_bf16 v[10:13], v[150:153], v[232:235], v[10:13]
	v_mfma_f32_16x16x32_bf16 v[2:5], v[158:161], v[232:235], v[2:5]
	s_barrier
; #define PG8_STAGE(bufoff, gbase, voff) do { _Pragma("unroll") for (int _i = 0; _i < 2; ++_i) \
;         __builtin_amdgcn_global_load_lds((const unsigned*)((const char*)(gbase) + (voff)[_i]), (LAS unsigned*)(lds + (bufoff) + ldsw + _i * 8192), 16, 0, 0); } while (0)
; #define PG8_LDA(dst, b, h) do { _Pragma("unroll") for (int m = 0; m < 4; ++m) _Pragma("unroll") for (int k = 0; k < 2; ++k) dst[m][k] = *(const LAS bf16x8*)(lds + PG8_SA(b, h) + aoff + m * 2048 + k * 1024); } while (0)
; #define PG8_LDB(dst, b, h) do { _Pragma("unroll") for (int n = 0; n < 2; ++n) _Pragma("unroll") for (int k = 0; k < 2; ++k) dst[n][k] = *(const LAS bf16x8*)(lds + PG8_SB(b, h) + boff + n * 2048 + k * 1024); } while (0)
; #define PG8_MMA(ai, bj, At, Bt) do { __builtin_amdgcn_s_setprio(1); _Pragma("unroll") for (int m = 0; m < 4; ++m) _Pragma("unroll") for (int n = 0; n < 2; ++n) _Pragma("unroll") for (int k = 0; k < 2; ++k) \
;         acc[ai][bj][m][n] = __builtin_amdgcn_mfma_f32_16x16x32_bf16(Bt[n][k], At[m][k], acc[ai][bj][m][n], 0, 0, 0); __builtin_amdgcn_s_setprio(0); } while (0)
; #define PG8_WAIT_V(n) asm volatile("s_waitcnt vmcnt(" #n ")" ::: "memory")
; #define PG8_WAIT_L(n) asm volatile("s_waitcnt lgkmcnt(" #n ")" ::: "memory")
; #define PG8_BAR __builtin_amdgcn_s_barrier()
; #define PG8_SCHED __builtin_amdgcn_sched_barrier(0)
; template <class Epi, class Sched>
; __device__ __forceinline__ void gemm_phase(LAS unsigned char* lds, const Gemm g, const Sched& S, const Epi& E) {
;     ...
;             PG8_LDB(B0, 1, 0); PG8_LDB(B1, 1, 1); PG8_SCHED; PG8_LDA(At, 1, 0); PG8_STAGE(PG8_SA(0, 1), a2 + hstepA, voffA);
;             PG8_WAIT_V(8); PG8_WAIT_L(0); PG8_BAR; PG8_MMA(0, 0, At, B0); PG8_MMA(0, 1, At, B1); PG8_BAR; PG8_SCHED;
;             PG8_LDA(At, 1, 1); PG8_STAGE(PG8_SB(1, 0), b3, voffB); PG8_STAGE(PG8_SB(1, 1), b3 + hstepB, voffB); PG8_STAGE(PG8_SA(1, 0), a3, voffA);
;             PG8_WAIT_V(8); PG8_WAIT_L(0); PG8_BAR; PG8_MMA(1, 0, At, B0); PG8_MMA(1, 1, At, B1); PG8_BAR; PG8_SCHED;
;         }
;         if (wr == 0) PG8_BAR;
	s_add_i32 s88, 0, 0x18000
	s_add_i32 s89, 0, 0x1c000
	s_add_u32 s20, s20, 0x40000
	s_addc_u32 s21, s21, 0
	s_mov_b32 m0, s29
	s_nop 0
	global_load_lds_dwordx4 v170, s[20:21]
	s_mov_b32 m0, s30
	s_nop 0
	global_load_lds_dwordx4 v190, s[20:21]
	ds_read_b128 v[130:133], v246 offset:32768
	ds_read_b128 v[134:137], v246 offset:33792
	ds_read_b128 v[138:141], v246 offset:34816
	ds_read_b128 v[142:145], v246 offset:35840
	ds_read_b128 v[146:149], v246 offset:49152
	ds_read_b128 v[150:153], v246 offset:50176
	ds_read_b128 v[154:157], v246 offset:51200
	ds_read_b128 v[158:161], v246 offset:52224
	ds_read_b128 v[162:165], v222 offset:32768
	ds_read_b128 v[166:169], v222 offset:33792
	ds_read_b128 v[194:197], v222 offset:34816
	ds_read_b128 v[198:201], v222 offset:35840
	ds_read_b128 v[202:205], v222 offset:36864
	ds_read_b128 v[224:227], v222 offset:37888
	ds_read_b128 v[228:231], v222 offset:38912
	ds_read_b128 v[232:235], v222 offset:39936
	s_waitcnt vmcnt(8)
	s_waitcnt lgkmcnt(0)
	s_barrier
	s_waitcnt lgkmcnt(0)
	v_mfma_f32_16x16x32_bf16 v[126:129], v[130:133], v[162:165], v[126:129]
	v_mfma_f32_16x16x32_bf16 v[118:121], v[138:141], v[162:165], v[118:121]
	v_mfma_f32_16x16x32_bf16 v[110:113], v[130:133], v[194:197], v[110:113]
	v_mfma_f32_16x16x32_bf16 v[102:105], v[138:141], v[194:197], v[102:105]
	v_mfma_f32_16x16x32_bf16 v[94:97], v[130:133], v[202:205], v[94:97]
	v_mfma_f32_16x16x32_bf16 v[86:89], v[138:141], v[202:205], v[86:89]
	v_mfma_f32_16x16x32_bf16 v[78:81], v[130:133], v[228:231], v[78:81]
	v_mfma_f32_16x16x32_bf16 v[70:73], v[138:141], v[228:231], v[70:73]
	v_mfma_f32_16x16x32_bf16 v[126:129], v[134:137], v[166:169], v[126:129]
	v_mfma_f32_16x16x32_bf16 v[118:121], v[142:145], v[166:169], v[118:121]
	v_mfma_f32_16x16x32_bf16 v[110:113], v[134:137], v[198:201], v[110:113]
	v_mfma_f32_16x16x32_bf16 v[102:105], v[142:145], v[198:201], v[102:105]
	v_mfma_f32_16x16x32_bf16 v[94:97], v[134:137], v[224:227], v[94:97]
	v_mfma_f32_16x16x32_bf16 v[86:89], v[142:145], v[224:227], v[86:89]
	v_mfma_f32_16x16x32_bf16 v[78:81], v[134:137], v[232:235], v[78:81]
	v_mfma_f32_16x16x32_bf16 v[70:73], v[142:145], v[232:235], v[70:73]
	v_mfma_f32_16x16x32_bf16 v[122:125], v[146:149], v[162:165], v[122:125]
	v_mfma_f32_16x16x32_bf16 v[114:117], v[154:157], v[162:165], v[114:117]
	v_mfma_f32_16x16x32_bf16 v[106:109], v[146:149], v[194:197], v[106:109]
	v_mfma_f32_16x16x32_bf16 v[98:101], v[154:157], v[194:197], v[98:101]
	v_mfma_f32_16x16x32_bf16 v[90:93], v[146:149], v[202:205], v[90:93]
	v_mfma_f32_16x16x32_bf16 v[82:85], v[154:157], v[202:205], v[82:85]
	v_mfma_f32_16x16x32_bf16 v[74:77], v[146:149], v[228:231], v[74:77]
	v_mfma_f32_16x16x32_bf16 v[66:69], v[154:157], v[228:231], v[66:69]
	v_mfma_f32_16x16x32_bf16 v[122:125], v[150:153], v[166:169], v[122:125]
	v_mfma_f32_16x16x32_bf16 v[114:117], v[158:161], v[166:169], v[114:117]
	v_mfma_f32_16x16x32_bf16 v[106:109], v[150:153], v[198:201], v[106:109]
	v_mfma_f32_16x16x32_bf16 v[98:101], v[158:161], v[198:201], v[98:101]
	v_mfma_f32_16x16x32_bf16 v[90:93], v[150:153], v[224:227], v[90:93]
	v_mfma_f32_16x16x32_bf16 v[82:85], v[158:161], v[224:227], v[82:85]
	v_mfma_f32_16x16x32_bf16 v[74:77], v[150:153], v[232:235], v[74:77]
	v_mfma_f32_16x16x32_bf16 v[66:69], v[158:161], v[232:235], v[66:69]
	s_barrier
	s_add_i32 s20, s8, 0x18000
	s_add_u32 s88, s86, 0x80
	s_addc_u32 s89, s87, 0
	s_mov_b32 m0, s20
	s_nop 0
	global_load_lds_dwordx4 v172, s[88:89]
	s_add_i32 m0, s20, 0x2000
	s_add_u32 s20, s86, 0x40080
	s_addc_u32 s21, s87, 0
	s_add_i32 s12, s8, 0x1c000
	global_load_lds_dwordx4 v192, s[88:89]
	s_mov_b32 m0, s12
	s_nop 0
	global_load_lds_dwordx4 v172, s[20:21]
	s_add_i32 m0, s12, 0x2000
	s_nop 0
	global_load_lds_dwordx4 v192, s[20:21]
	s_mov_b32 m0, s31
	s_nop 0
	global_load_lds_dwordx4 v170, s[100:101]
	s_mov_b32 m0, s34
	s_nop 0
	global_load_lds_dwordx4 v190, s[100:101]
	ds_read_b128 v[162:165], v222 offset:49152
	ds_read_b128 v[166:169], v222 offset:50176
	ds_read_b128 v[194:197], v222 offset:51200
	ds_read_b128 v[198:201], v222 offset:52224
	ds_read_b128 v[202:205], v222 offset:53248
	ds_read_b128 v[224:227], v222 offset:54272
	ds_read_b128 v[228:231], v222 offset:55296
	ds_read_b128 v[232:235], v222 offset:56320
	s_waitcnt vmcnt(8)
	s_waitcnt lgkmcnt(0)
	s_barrier
	s_waitcnt lgkmcnt(0)
	v_mfma_f32_16x16x32_bf16 v[62:65], v[130:133], v[162:165], v[62:65]
	v_mfma_f32_16x16x32_bf16 v[54:57], v[138:141], v[162:165], v[54:57]
	v_mfma_f32_16x16x32_bf16 v[46:49], v[130:133], v[194:197], v[46:49]
	v_mfma_f32_16x16x32_bf16 v[38:41], v[138:141], v[194:197], v[38:41]
	v_mfma_f32_16x16x32_bf16 v[30:33], v[130:133], v[202:205], v[30:33]
	v_mfma_f32_16x16x32_bf16 v[22:25], v[138:141], v[202:205], v[22:25]
	v_mfma_f32_16x16x32_bf16 v[14:17], v[130:133], v[228:231], v[14:17]
	v_mfma_f32_16x16x32_bf16 v[6:9], v[138:141], v[228:231], v[6:9]
	v_mfma_f32_16x16x32_bf16 v[62:65], v[134:137], v[166:169], v[62:65]
	v_mfma_f32_16x16x32_bf16 v[54:57], v[142:145], v[166:169], v[54:57]
	v_mfma_f32_16x16x32_bf16 v[46:49], v[134:137], v[198:201], v[46:49]
	v_mfma_f32_16x16x32_bf16 v[38:41], v[142:145], v[198:201], v[38:41]
	v_mfma_f32_16x16x32_bf16 v[30:33], v[134:137], v[224:227], v[30:33]
	v_mfma_f32_16x16x32_bf16 v[22:25], v[142:145], v[224:227], v[22:25]
	v_mfma_f32_16x16x32_bf16 v[14:17], v[134:137], v[232:235], v[14:17]
	v_mfma_f32_16x16x32_bf16 v[6:9], v[142:145], v[232:235], v[6:9]
	v_mfma_f32_16x16x32_bf16 v[58:61], v[146:149], v[162:165], v[58:61]
	v_mfma_f32_16x16x32_bf16 v[50:53], v[154:157], v[162:165], v[50:53]
	v_mfma_f32_16x16x32_bf16 v[42:45], v[146:149], v[194:197], v[42:45]
	v_mfma_f32_16x16x32_bf16 v[34:37], v[154:157], v[194:197], v[34:37]
	v_mfma_f32_16x16x32_bf16 v[26:29], v[146:149], v[202:205], v[26:29]
	v_mfma_f32_16x16x32_bf16 v[18:21], v[154:157], v[202:205], v[18:21]
	v_mfma_f32_16x16x32_bf16 v[10:13], v[146:149], v[228:231], v[10:13]
	v_mfma_f32_16x16x32_bf16 v[2:5], v[154:157], v[228:231], v[2:5]
	v_mfma_f32_16x16x32_bf16 v[58:61], v[150:153], v[166:169], v[58:61]
	v_mfma_f32_16x16x32_bf16 v[50:53], v[158:161], v[166:169], v[50:53]
	v_mfma_f32_16x16x32_bf16 v[42:45], v[150:153], v[198:201], v[42:45]
	v_mfma_f32_16x16x32_bf16 v[34:37], v[158:161], v[198:201], v[34:37]
	v_mfma_f32_16x16x32_bf16 v[26:29], v[150:153], v[224:227], v[26:29]
	v_mfma_f32_16x16x32_bf16 v[18:21], v[158:161], v[224:227], v[18:21]
	v_mfma_f32_16x16x32_bf16 v[10:13], v[150:153], v[232:235], v[10:13]
	v_mfma_f32_16x16x32_bf16 v[2:5], v[158:161], v[232:235], v[2:5]
	s_barrier
	s_add_i32 s83, s83, 2
	s_add_u32 s18, s18, 0x100
	s_addc_u32 s19, s19, 0
	s_add_u32 s54, s54, 0x100
	s_addc_u32 s81, s81, 0
	s_cmp_gt_u32 s83, 13
	s_cbranch_scc0 .LBB0_232
	s_and_b64 vcc, exec, s[72:73]
	s_cbranch_vccz .LBB0_235
	s_barrier

; #define PG8_STAGE(bufoff, gbase, voff) do { _Pragma("unroll") for (int _i = 0; _i < 2; ++_i) \
;         __builtin_amdgcn_global_load_lds((const unsigned*)((const char*)(gbase) + (voff)[_i]), (LAS unsigned*)(lds + (bufoff) + ldsw + _i * 8192), 16, 0, 0); } while (0)
; #define PG8_LDA(dst, b, h) do { _Pragma("unroll") for (int m = 0; m < 4; ++m) _Pragma("unroll") for (int k = 0; k < 2; ++k) dst[m][k] = *(const LAS bf16x8*)(lds + PG8_SA(b, h) + aoff + m * 2048 + k * 1024); } while (0)
; #define PG8_LDB(dst, b, h) do { _Pragma("unroll") for (int n = 0; n < 2; ++n) _Pragma("unroll") for (int k = 0; k < 2; ++k) dst[n][k] = *(const LAS bf16x8*)(lds + PG8_SB(b, h) + boff + n * 2048 + k * 1024); } while (0)
; #define PG8_MMA(ai, bj, At, Bt) do { __builtin_amdgcn_s_setprio(1); _Pragma("unroll") for (int m = 0; m < 4; ++m) _Pragma("unroll") for (int n = 0; n < 2; ++n) _Pragma("unroll") for (int k = 0; k < 2; ++k) \
;         acc[ai][bj][m][n] = __builtin_amdgcn_mfma_f32_16x16x32_bf16(Bt[n][k], At[m][k], acc[ai][bj][m][n], 0, 0, 0); __builtin_amdgcn_s_setprio(0); } while (0)
; #define PG8_WAIT_V(n) asm volatile("s_waitcnt vmcnt(" #n ")" ::: "memory")
; #define PG8_WAIT_L(n) asm volatile("s_waitcnt lgkmcnt(" #n ")" ::: "memory")
; #define PG8_BAR __builtin_amdgcn_s_barrier()
; #define PG8_SCHED __builtin_amdgcn_sched_barrier(0)
; template <class Epi, class Sched>
; __device__ __forceinline__ void gemm_phase(LAS unsigned char* lds, const Gemm g, const Sched& S, const Epi& E) {
;     ...
;             PG8_LDB(B0, 0, 0); PG8_LDB(B1, 0, 1); PG8_SCHED; PG8_LDA(At, 0, 0); PG8_STAGE(PG8_SA(1, 1), a1 + hstepA, voffA);
;             PG8_WAIT_V(8); PG8_WAIT_L(0); PG8_BAR; PG8_MMA(0, 0, At, B0); PG8_MMA(0, 1, At, B1); PG8_BAR; PG8_SCHED;
;             PG8_LDA(At, 0, 1); PG8_STAGE(PG8_SB(0, 0), b2, voffB); PG8_STAGE(PG8_SB(0, 1), b2 + hstepB, voffB); PG8_STAGE(PG8_SA(0, 0), a2, voffA);
;             PG8_WAIT_V(8); PG8_WAIT_L(0); PG8_BAR; PG8_MMA(1, 0, At, B0); PG8_MMA(1, 1, At, B1); PG8_BAR; PG8_SCHED;
.LBB0_348:
	s_ashr_i32 s71, s70, 31
	s_lshl_b64 s[48:49], s[70:71], 19
	s_add_u32 s72, s4, s48
	s_addc_u32 s73, s5, s49
	s_and_b64 s[48:49], s[66:67], exec
	s_cselect_b32 s48, s73, s19
	s_cselect_b32 s49, s72, s18
	s_ashr_i32 s69, s68, 31
	s_lshl_b64 s[74:75], s[68:69], 19
	v_readlane_b32 s12, v248, 13
	s_add_u32 s74, s12, s74
	v_readlane_b32 s12, v248, 14
	s_addc_u32 s75, s12, s75
	s_and_b64 s[76:77], s[66:67], exec
	s_cselect_b32 s53, s75, s21
	s_cselect_b32 s54, s74, s20
	s_add_u32 s18, s18, 0x40080
	s_addc_u32 s19, s19, 0
	s_add_u32 s69, s20, 0x100
	s_addc_u32 s71, s21, 0
	s_mov_b32 s78, -2
	s_waitcnt vmcnt(0)
	v_add_u32_e32 v255, 0x10000, v139
	s_add_u32 s20, s18, 0xfffc0080
	s_addc_u32 s21, s19, -1
	s_add_i32 s79, 0, 0x10000
	s_cmp_eq_u32 s78, 12
	s_cselect_b32 s21, s48, s21
	s_cselect_b32 s20, s49, s20
	s_cselect_b32 s77, s53, s71
	s_cselect_b32 s76, s54, s69
	s_add_u32 s100, s20, 0x80
	s_addc_u32 s101, s21, 0
	s_add_i32 s82, 0, 0x14000
	s_add_i32 m0, s9, 0xc000
	s_nop 0
	global_load_lds_dwordx4 v130, s[18:19]
	s_add_i32 m0, s9, 0xe000
	s_nop 0
	global_load_lds_dwordx4 v134, s[18:19]
	ds_read_b128 v[150:153], v255
	ds_read_b128 v[154:157], v255 offset:1024
	ds_read_b128 v[158:161], v255 offset:2048
	ds_read_b128 v[162:165], v255 offset:3072
	ds_read_b128 v[166:169], v255 offset:16384
	ds_read_b128 v[170:173], v255 offset:17408
	ds_read_b128 v[190:193], v255 offset:18432
	ds_read_b128 v[194:197], v255 offset:19456
	ds_read_b128 v[198:201], v148
	ds_read_b128 v[202:205], v148 offset:1024
	ds_read_b128 v[206:209], v148 offset:2048
	ds_read_b128 v[218:221], v148 offset:3072
	ds_read_b128 v[222:225], v148 offset:4096
	ds_read_b128 v[226:229], v148 offset:5120
	ds_read_b128 v[230:233], v148 offset:6144
	ds_read_b128 v[234:237], v148 offset:7168
	s_waitcnt vmcnt(8)
	s_waitcnt lgkmcnt(0)
	s_barrier
	s_waitcnt lgkmcnt(0)
	v_mfma_f32_16x16x32_bf16 v[126:129], v[150:153], v[198:201], 0
	v_mfma_f32_16x16x32_bf16 v[122:125], v[158:161], v[198:201], 0
	v_mfma_f32_16x16x32_bf16 v[110:113], v[150:153], v[206:209], 0
	v_mfma_f32_16x16x32_bf16 v[106:109], v[158:161], v[206:209], 0
	v_mfma_f32_16x16x32_bf16 v[94:97], v[150:153], v[222:225], 0
	v_mfma_f32_16x16x32_bf16 v[90:93], v[158:161], v[222:225], 0
	v_mfma_f32_16x16x32_bf16 v[82:85], v[150:153], v[230:233], 0
	v_mfma_f32_16x16x32_bf16 v[74:77], v[158:161], v[230:233], 0
	v_mfma_f32_16x16x32_bf16 v[126:129], v[154:157], v[202:205], v[126:129]
	v_mfma_f32_16x16x32_bf16 v[122:125], v[162:165], v[202:205], v[122:125]
	v_mfma_f32_16x16x32_bf16 v[110:113], v[154:157], v[218:221], v[110:113]
	v_mfma_f32_16x16x32_bf16 v[106:109], v[162:165], v[218:221], v[106:109]
	v_mfma_f32_16x16x32_bf16 v[94:97], v[154:157], v[226:229], v[94:97]
	v_mfma_f32_16x16x32_bf16 v[90:93], v[162:165], v[226:229], v[90:93]
	v_mfma_f32_16x16x32_bf16 v[82:85], v[154:157], v[234:237], v[82:85]
	v_mfma_f32_16x16x32_bf16 v[74:77], v[162:165], v[234:237], v[74:77]
	v_mfma_f32_16x16x32_bf16 v[118:121], v[166:169], v[198:201], 0
	v_mfma_f32_16x16x32_bf16 v[114:117], v[190:193], v[198:201], 0
	v_mfma_f32_16x16x32_bf16 v[102:105], v[166:169], v[206:209], 0
	v_mfma_f32_16x16x32_bf16 v[98:101], v[190:193], v[206:209], 0
	v_mfma_f32_16x16x32_bf16 v[86:89], v[166:169], v[222:225], 0
	v_mfma_f32_16x16x32_bf16 v[78:81], v[190:193], v[222:225], 0
	v_mfma_f32_16x16x32_bf16 v[70:73], v[166:169], v[230:233], 0
	v_mfma_f32_16x16x32_bf16 v[66:69], v[190:193], v[230:233], 0
	v_mfma_f32_16x16x32_bf16 v[118:121], v[170:173], v[202:205], v[118:121]
	v_mfma_f32_16x16x32_bf16 v[114:117], v[194:197], v[202:205], v[114:117]
	v_mfma_f32_16x16x32_bf16 v[102:105], v[170:173], v[218:221], v[102:105]
	v_mfma_f32_16x16x32_bf16 v[98:101], v[194:197], v[218:221], v[98:101]
	v_mfma_f32_16x16x32_bf16 v[86:89], v[170:173], v[226:229], v[86:89]
	v_mfma_f32_16x16x32_bf16 v[78:81], v[194:197], v[226:229], v[78:81]
	v_mfma_f32_16x16x32_bf16 v[70:73], v[170:173], v[234:237], v[70:73]
	v_mfma_f32_16x16x32_bf16 v[66:69], v[194:197], v[234:237], v[66:69]
	s_barrier
	s_add_i32 s79, s79, s8
	s_mov_b32 m0, s79
	s_nop 0
	global_load_lds_dwordx4 v132, s[76:77]
	s_add_i32 m0, s79, 0x2000
	s_add_u32 s80, s76, 0x40000
	s_addc_u32 s81, s77, 0
	s_add_i32 s79, s82, s8
	global_load_lds_dwordx4 v136, s[76:77]
	s_mov_b32 m0, s79
	s_nop 0
	global_load_lds_dwordx4 v132, s[80:81]
	s_add_i32 m0, s79, 0x2000
	s_nop 0
	global_load_lds_dwordx4 v136, s[80:81]
	s_mov_b32 m0, s9
	s_nop 0
	global_load_lds_dwordx4 v130, s[20:21]
	s_mov_b32 m0, s28
	s_nop 0
	global_load_lds_dwordx4 v134, s[20:21]
	ds_read_b128 v[198:201], v148 offset:16384
	ds_read_b128 v[202:205], v148 offset:17408
	ds_read_b128 v[206:209], v148 offset:18432
	ds_read_b128 v[218:221], v148 offset:19456
	ds_read_b128 v[222:225], v148 offset:20480
	ds_read_b128 v[226:229], v148 offset:21504
	ds_read_b128 v[230:233], v148 offset:22528
	ds_read_b128 v[234:237], v148 offset:23552
	s_waitcnt vmcnt(8)
	s_waitcnt lgkmcnt(0)
	s_nop 0
	s_barrier
; #define PG8_STAGE(bufoff, gbase, voff) do { _Pragma("unroll") for (int _i = 0; _i < 2; ++_i) \
;         __builtin_amdgcn_global_load_lds((const unsigned*)((const char*)(gbase) + (voff)[_i]), (LAS unsigned*)(lds + (bufoff) + ldsw + _i * 8192), 16, 0, 0); } while (0)
; #define PG8_LDA(dst, b, h) do { _Pragma("unroll") for (int m = 0; m < 4; ++m) _Pragma("unroll") for (int k = 0; k < 2; ++k) dst[m][k] = *(const LAS bf16x8*)(lds + PG8_SA(b, h) + aoff + m * 2048 + k * 1024); } while (0)
; #define PG8_LDB(dst, b, h) do { _Pragma("unroll") for (int n = 0; n < 2; ++n) _Pragma("unroll") for (int k = 0; k < 2; ++k) dst[n][k] = *(const LAS bf16x8*)(lds + PG8_SB(b, h) + boff + n * 2048 + k * 1024); } while (0)
; #define PG8_MMA(ai, bj, At, Bt) do { __builtin_amdgcn_s_setprio(1); _Pragma("unroll") for (int m = 0; m < 4; ++m) _Pragma("unroll") for (int n = 0; n < 2; ++n) _Pragma("unroll") for (int k = 0; k < 2; ++k) \
;         acc[ai][bj][m][n] = __builtin_amdgcn_mfma_f32_16x16x32_bf16(Bt[n][k], At[m][k], acc[ai][bj][m][n], 0, 0, 0); __builtin_amdgcn_s_setprio(0); } while (0)
; #define PG8_WAIT_V(n) asm volatile("s_waitcnt vmcnt(" #n ")" ::: "memory")
; #define PG8_WAIT_L(n) asm volatile("s_waitcnt lgkmcnt(" #n ")" ::: "memory")
; #define PG8_BAR __builtin_amdgcn_s_barrier()
; #define PG8_SCHED __builtin_amdgcn_sched_barrier(0)
; template <class Epi, class Sched>
; __device__ __forceinline__ void gemm_phase(LAS unsigned char* lds, const Gemm g, const Sched& S, const Epi& E) {
;     ...
;             PG8_WAIT_V(8); PG8_WAIT_L(0); PG8_BAR; PG8_MMA(1, 0, At, B0); PG8_MMA(1, 1, At, B1); PG8_BAR; PG8_SCHED;
;             PG8_LDB(B0, 1, 0); PG8_LDB(B1, 1, 1); PG8_SCHED; PG8_LDA(At, 1, 0); PG8_STAGE(PG8_SA(0, 1), a2 + hstepA, voffA);
;             PG8_WAIT_V(8); PG8_WAIT_L(0); PG8_BAR; PG8_MMA(0, 0, At, B0); PG8_MMA(0, 1, At, B1); PG8_BAR; PG8_SCHED;
;             PG8_LDA(At, 1, 1); PG8_STAGE(PG8_SB(1, 0), b3, voffB); PG8_STAGE(PG8_SB(1, 1), b3 + hstepB, voffB); PG8_STAGE(PG8_SA(1, 0), a3, voffA);
;             PG8_WAIT_V(8); PG8_WAIT_L(0); PG8_BAR; PG8_MMA(1, 0, At, B0); PG8_MMA(1, 1, At, B1); PG8_BAR; PG8_SCHED;
	s_waitcnt lgkmcnt(0)
	v_mfma_f32_16x16x32_bf16 v[62:65], v[150:153], v[198:201], 0
	v_mfma_f32_16x16x32_bf16 v[58:61], v[158:161], v[198:201], 0
	v_mfma_f32_16x16x32_bf16 v[50:53], v[150:153], v[206:209], 0
	v_mfma_f32_16x16x32_bf16 v[42:45], v[158:161], v[206:209], 0
	v_mfma_f32_16x16x32_bf16 v[30:33], v[150:153], v[222:225], 0
	v_mfma_f32_16x16x32_bf16 v[26:29], v[158:161], v[222:225], 0
	v_mfma_f32_16x16x32_bf16 v[18:21], v[150:153], v[230:233], 0
	v_mfma_f32_16x16x32_bf16 v[10:13], v[158:161], v[230:233], 0
	v_mfma_f32_16x16x32_bf16 v[62:65], v[154:157], v[202:205], v[62:65]
	v_mfma_f32_16x16x32_bf16 v[58:61], v[162:165], v[202:205], v[58:61]
	v_mfma_f32_16x16x32_bf16 v[50:53], v[154:157], v[218:221], v[50:53]
	v_mfma_f32_16x16x32_bf16 v[42:45], v[162:165], v[218:221], v[42:45]
	v_mfma_f32_16x16x32_bf16 v[30:33], v[154:157], v[226:229], v[30:33]
	v_mfma_f32_16x16x32_bf16 v[26:29], v[162:165], v[226:229], v[26:29]
	v_mfma_f32_16x16x32_bf16 v[18:21], v[154:157], v[234:237], v[18:21]
	v_mfma_f32_16x16x32_bf16 v[10:13], v[162:165], v[234:237], v[10:13]
	v_mfma_f32_16x16x32_bf16 v[54:57], v[166:169], v[198:201], 0
	v_mfma_f32_16x16x32_bf16 v[46:49], v[190:193], v[198:201], 0
	v_mfma_f32_16x16x32_bf16 v[38:41], v[166:169], v[206:209], 0
	v_mfma_f32_16x16x32_bf16 v[34:37], v[190:193], v[206:209], 0
	v_mfma_f32_16x16x32_bf16 v[22:25], v[166:169], v[222:225], 0
	v_mfma_f32_16x16x32_bf16 v[14:17], v[190:193], v[222:225], 0
	v_mfma_f32_16x16x32_bf16 v[6:9], v[166:169], v[230:233], 0
	v_mfma_f32_16x16x32_bf16 v[2:5], v[190:193], v[230:233], 0
	v_mfma_f32_16x16x32_bf16 v[54:57], v[170:173], v[202:205], v[54:57]
	v_mfma_f32_16x16x32_bf16 v[46:49], v[194:197], v[202:205], v[46:49]
	v_mfma_f32_16x16x32_bf16 v[38:41], v[170:173], v[218:221], v[38:41]
	v_mfma_f32_16x16x32_bf16 v[34:37], v[194:197], v[218:221], v[34:37]
	v_mfma_f32_16x16x32_bf16 v[22:25], v[170:173], v[226:229], v[22:25]
	v_mfma_f32_16x16x32_bf16 v[14:17], v[194:197], v[226:229], v[14:17]
	v_mfma_f32_16x16x32_bf16 v[6:9], v[170:173], v[234:237], v[6:9]
	v_mfma_f32_16x16x32_bf16 v[2:5], v[194:197], v[234:237], v[2:5]
	s_barrier
	s_add_i32 s79, 0, 0x18000
	s_add_i32 s80, 0, 0x1c000
	s_add_u32 s20, s20, 0x40000
	s_addc_u32 s21, s21, 0
	s_mov_b32 m0, s29
	s_nop 0
	global_load_lds_dwordx4 v130, s[20:21]
	s_mov_b32 m0, s30
	s_nop 0
	global_load_lds_dwordx4 v134, s[20:21]
	ds_read_b128 v[150:153], v255 offset:32768
	ds_read_b128 v[154:157], v255 offset:33792
	ds_read_b128 v[158:161], v255 offset:34816
	ds_read_b128 v[162:165], v255 offset:35840
	ds_read_b128 v[166:169], v255 offset:49152
	ds_read_b128 v[170:173], v255 offset:50176
	ds_read_b128 v[190:193], v255 offset:51200
	ds_read_b128 v[194:197], v255 offset:52224
	ds_read_b128 v[198:201], v148 offset:32768
	ds_read_b128 v[202:205], v148 offset:33792
	ds_read_b128 v[206:209], v148 offset:34816
	ds_read_b128 v[218:221], v148 offset:35840
	ds_read_b128 v[222:225], v148 offset:36864
	ds_read_b128 v[226:229], v148 offset:37888
	ds_read_b128 v[230:233], v148 offset:38912
	ds_read_b128 v[234:237], v148 offset:39936
	s_waitcnt vmcnt(8)
	s_waitcnt lgkmcnt(0)
	s_barrier
	s_waitcnt lgkmcnt(0)
	v_mfma_f32_16x16x32_bf16 v[126:129], v[150:153], v[198:201], v[126:129]
	v_mfma_f32_16x16x32_bf16 v[122:125], v[158:161], v[198:201], v[122:125]
	v_mfma_f32_16x16x32_bf16 v[110:113], v[150:153], v[206:209], v[110:113]
	v_mfma_f32_16x16x32_bf16 v[106:109], v[158:161], v[206:209], v[106:109]
	v_mfma_f32_16x16x32_bf16 v[94:97], v[150:153], v[222:225], v[94:97]
	v_mfma_f32_16x16x32_bf16 v[90:93], v[158:161], v[222:225], v[90:93]
	v_mfma_f32_16x16x32_bf16 v[82:85], v[150:153], v[230:233], v[82:85]
	v_mfma_f32_16x16x32_bf16 v[74:77], v[158:161], v[230:233], v[74:77]
	v_mfma_f32_16x16x32_bf16 v[126:129], v[154:157], v[202:205], v[126:129]
	v_mfma_f32_16x16x32_bf16 v[122:125], v[162:165], v[202:205], v[122:125]
	v_mfma_f32_16x16x32_bf16 v[110:113], v[154:157], v[218:221], v[110:113]
	v_mfma_f32_16x16x32_bf16 v[106:109], v[162:165], v[218:221], v[106:109]
	v_mfma_f32_16x16x32_bf16 v[94:97], v[154:157], v[226:229], v[94:97]
	v_mfma_f32_16x16x32_bf16 v[90:93], v[162:165], v[226:229], v[90:93]
	v_mfma_f32_16x16x32_bf16 v[82:85], v[154:157], v[234:237], v[82:85]
	v_mfma_f32_16x16x32_bf16 v[74:77], v[162:165], v[234:237], v[74:77]
	v_mfma_f32_16x16x32_bf16 v[118:121], v[166:169], v[198:201], v[118:121]
	v_mfma_f32_16x16x32_bf16 v[114:117], v[190:193], v[198:201], v[114:117]
	v_mfma_f32_16x16x32_bf16 v[102:105], v[166:169], v[206:209], v[102:105]
	v_mfma_f32_16x16x32_bf16 v[98:101], v[190:193], v[206:209], v[98:101]
	v_mfma_f32_16x16x32_bf16 v[86:89], v[166:169], v[222:225], v[86:89]
	v_mfma_f32_16x16x32_bf16 v[78:81], v[190:193], v[222:225], v[78:81]
	v_mfma_f32_16x16x32_bf16 v[70:73], v[166:169], v[230:233], v[70:73]
	v_mfma_f32_16x16x32_bf16 v[66:69], v[190:193], v[230:233], v[66:69]
	v_mfma_f32_16x16x32_bf16 v[118:121], v[170:173], v[202:205], v[118:121]
	v_mfma_f32_16x16x32_bf16 v[114:117], v[194:197], v[202:205], v[114:117]
	v_mfma_f32_16x16x32_bf16 v[102:105], v[170:173], v[218:221], v[102:105]
	v_mfma_f32_16x16x32_bf16 v[98:101], v[194:197], v[218:221], v[98:101]
	v_mfma_f32_16x16x32_bf16 v[86:89], v[170:173], v[226:229], v[86:89]
	v_mfma_f32_16x16x32_bf16 v[78:81], v[194:197], v[226:229], v[78:81]
	v_mfma_f32_16x16x32_bf16 v[70:73], v[170:173], v[234:237], v[70:73]
	v_mfma_f32_16x16x32_bf16 v[66:69], v[194:197], v[234:237], v[66:69]
	s_barrier
; #define PG8_STAGE(bufoff, gbase, voff) do { _Pragma("unroll") for (int _i = 0; _i < 2; ++_i) \
;         __builtin_amdgcn_global_load_lds((const unsigned*)((const char*)(gbase) + (voff)[_i]), (LAS unsigned*)(lds + (bufoff) + ldsw + _i * 8192), 16, 0, 0); } while (0)
; #define PG8_LDA(dst, b, h) do { _Pragma("unroll") for (int m = 0; m < 4; ++m) _Pragma("unroll") for (int k = 0; k < 2; ++k) dst[m][k] = *(const LAS bf16x8*)(lds + PG8_SA(b, h) + aoff + m * 2048 + k * 1024); } while (0)
; #define PG8_LDB(dst, b, h) do { _Pragma("unroll") for (int n = 0; n < 2; ++n) _Pragma("unroll") for (int k = 0; k < 2; ++k) dst[n][k] = *(const LAS bf16x8*)(lds + PG8_SB(b, h) + boff + n * 2048 + k * 1024); } while (0)
; #define PG8_MMA(ai, bj, At, Bt) do { __builtin_amdgcn_s_setprio(1); _Pragma("unroll") for (int m = 0; m < 4; ++m) _Pragma("unroll") for (int n = 0; n < 2; ++n) _Pragma("unroll") for (int k = 0; k < 2; ++k) \
;         acc[ai][bj][m][n] = __builtin_amdgcn_mfma_f32_16x16x32_bf16(Bt[n][k], At[m][k], acc[ai][bj][m][n], 0, 0, 0); __builtin_amdgcn_s_setprio(0); } while (0)
; #define PG8_WAIT_V(n) asm volatile("s_waitcnt vmcnt(" #n ")" ::: "memory")
; #define PG8_WAIT_L(n) asm volatile("s_waitcnt lgkmcnt(" #n ")" ::: "memory")
; #define PG8_BAR __builtin_amdgcn_s_barrier()
; #define PG8_SCHED __builtin_amdgcn_sched_barrier(0)
; template <class Epi, class Sched>
; __device__ __forceinline__ void gemm_phase(LAS unsigned char* lds, const Gemm g, const Sched& S, const Epi& E) {
;     ...
;             PG8_LDB(B0, 0, 0); PG8_LDB(B1, 0, 1); PG8_SCHED; PG8_LDA(At, 0, 0); PG8_STAGE(PG8_SA(1, 1), a1 + hstepA, voffA);
;             PG8_WAIT_V(8); PG8_WAIT_L(0); PG8_BAR; PG8_MMA(0, 0, At, B0); PG8_MMA(0, 1, At, B1); PG8_BAR; PG8_SCHED;
;     ...
;             PG8_LDA(At, 1, 1); PG8_STAGE(PG8_SB(1, 0), b3, voffB); PG8_STAGE(PG8_SB(1, 1), b3 + hstepB, voffB); PG8_STAGE(PG8_SA(1, 0), a3, voffA);
;             PG8_WAIT_V(8); PG8_WAIT_L(0); PG8_BAR; PG8_MMA(1, 0, At, B0); PG8_MMA(1, 1, At, B1); PG8_BAR; PG8_SCHED;
	s_add_i32 s20, s8, 0x18000
	s_add_u32 s80, s76, 0x80
	s_addc_u32 s81, s77, 0
	s_mov_b32 m0, s20
	s_nop 0
	global_load_lds_dwordx4 v132, s[80:81]
	s_add_i32 m0, s20, 0x2000
	s_add_u32 s20, s76, 0x40080
	s_addc_u32 s21, s77, 0
	s_add_i32 s12, s8, 0x1c000
	global_load_lds_dwordx4 v136, s[80:81]
	s_mov_b32 m0, s12
	s_nop 0
	global_load_lds_dwordx4 v132, s[20:21]
	s_add_i32 m0, s12, 0x2000
	s_nop 0
	global_load_lds_dwordx4 v136, s[20:21]
	s_mov_b32 m0, s31
	s_nop 0
	global_load_lds_dwordx4 v130, s[100:101]
	s_mov_b32 m0, s34
	s_nop 0
	global_load_lds_dwordx4 v134, s[100:101]
	ds_read_b128 v[198:201], v148 offset:49152
	ds_read_b128 v[202:205], v148 offset:50176
	ds_read_b128 v[206:209], v148 offset:51200
	ds_read_b128 v[218:221], v148 offset:52224
	ds_read_b128 v[222:225], v148 offset:53248
	ds_read_b128 v[226:229], v148 offset:54272
	ds_read_b128 v[230:233], v148 offset:55296
	ds_read_b128 v[234:237], v148 offset:56320
	s_waitcnt vmcnt(8)
	s_waitcnt lgkmcnt(0)
	s_barrier
	s_waitcnt lgkmcnt(0)
	v_mfma_f32_16x16x32_bf16 v[62:65], v[150:153], v[198:201], v[62:65]
	v_mfma_f32_16x16x32_bf16 v[58:61], v[158:161], v[198:201], v[58:61]
	v_mfma_f32_16x16x32_bf16 v[50:53], v[150:153], v[206:209], v[50:53]
	v_mfma_f32_16x16x32_bf16 v[42:45], v[158:161], v[206:209], v[42:45]
	v_mfma_f32_16x16x32_bf16 v[30:33], v[150:153], v[222:225], v[30:33]
	v_mfma_f32_16x16x32_bf16 v[26:29], v[158:161], v[222:225], v[26:29]
	v_mfma_f32_16x16x32_bf16 v[18:21], v[150:153], v[230:233], v[18:21]
	v_mfma_f32_16x16x32_bf16 v[10:13], v[158:161], v[230:233], v[10:13]
	v_mfma_f32_16x16x32_bf16 v[62:65], v[154:157], v[202:205], v[62:65]
	v_mfma_f32_16x16x32_bf16 v[58:61], v[162:165], v[202:205], v[58:61]
	v_mfma_f32_16x16x32_bf16 v[50:53], v[154:157], v[218:221], v[50:53]
	v_mfma_f32_16x16x32_bf16 v[42:45], v[162:165], v[218:221], v[42:45]
	v_mfma_f32_16x16x32_bf16 v[30:33], v[154:157], v[226:229], v[30:33]
	v_mfma_f32_16x16x32_bf16 v[26:29], v[162:165], v[226:229], v[26:29]
	v_mfma_f32_16x16x32_bf16 v[18:21], v[154:157], v[234:237], v[18:21]
	v_mfma_f32_16x16x32_bf16 v[10:13], v[162:165], v[234:237], v[10:13]
	v_mfma_f32_16x16x32_bf16 v[54:57], v[166:169], v[198:201], v[54:57]
	v_mfma_f32_16x16x32_bf16 v[46:49], v[190:193], v[198:201], v[46:49]
	v_mfma_f32_16x16x32_bf16 v[38:41], v[166:169], v[206:209], v[38:41]
	v_mfma_f32_16x16x32_bf16 v[34:37], v[190:193], v[206:209], v[34:37]
	v_mfma_f32_16x16x32_bf16 v[22:25], v[166:169], v[222:225], v[22:25]
	v_mfma_f32_16x16x32_bf16 v[14:17], v[190:193], v[222:225], v[14:17]
	v_mfma_f32_16x16x32_bf16 v[6:9], v[166:169], v[230:233], v[6:9]
	v_mfma_f32_16x16x32_bf16 v[2:5], v[190:193], v[230:233], v[2:5]
	v_mfma_f32_16x16x32_bf16 v[54:57], v[170:173], v[202:205], v[54:57]
	v_mfma_f32_16x16x32_bf16 v[46:49], v[194:197], v[202:205], v[46:49]
	v_mfma_f32_16x16x32_bf16 v[38:41], v[170:173], v[218:221], v[38:41]
	v_mfma_f32_16x16x32_bf16 v[34:37], v[194:197], v[218:221], v[34:37]
	v_mfma_f32_16x16x32_bf16 v[22:25], v[170:173], v[226:229], v[22:25]
	v_mfma_f32_16x16x32_bf16 v[14:17], v[194:197], v[226:229], v[14:17]
	v_mfma_f32_16x16x32_bf16 v[6:9], v[170:173], v[234:237], v[6:9]
	v_mfma_f32_16x16x32_bf16 v[2:5], v[194:197], v[234:237], v[2:5]
	s_barrier
	s_add_i32 s78, s78, 2
	s_add_u32 s18, s18, 0x100
	s_addc_u32 s19, s19, 0
	s_add_u32 s69, s69, 0x100
	s_addc_u32 s71, s71, 0
	s_cmp_gt_u32 s78, 13
.LBB0_349:
	s_add_u32 s20, s18, 0xfffc0080
	s_addc_u32 s21, s19, -1
	s_add_i32 s79, 0, 0x10000
	s_cmp_eq_u32 s78, 12
	s_cselect_b32 s21, s48, s21
	s_cselect_b32 s20, s49, s20
	s_cselect_b32 s77, s53, s71
	s_cselect_b32 s76, s54, s69
	s_add_u32 s100, s20, 0x80
	s_addc_u32 s101, s21, 0
	s_add_i32 s82, 0, 0x14000
	s_add_i32 m0, s9, 0xc000
	s_nop 0
	global_load_lds_dwordx4 v130, s[18:19]
	s_add_i32 m0, s9, 0xe000
	s_nop 0
	global_load_lds_dwordx4 v134, s[18:19]
	ds_read_b128 v[150:153], v255
	ds_read_b128 v[154:157], v255 offset:1024
	ds_read_b128 v[158:161], v255 offset:2048
	ds_read_b128 v[162:165], v255 offset:3072
	ds_read_b128 v[166:169], v255 offset:16384
	ds_read_b128 v[170:173], v255 offset:17408
	ds_read_b128 v[190:193], v255 offset:18432
	ds_read_b128 v[194:197], v255 offset:19456
	ds_read_b128 v[198:201], v148
	ds_read_b128 v[202:205], v148 offset:1024
	ds_read_b128 v[206:209], v148 offset:2048
	ds_read_b128 v[218:221], v148 offset:3072
	ds_read_b128 v[222:225], v148 offset:4096
	ds_read_b128 v[226:229], v148 offset:5120
	ds_read_b128 v[230:233], v148 offset:6144
	ds_read_b128 v[234:237], v148 offset:7168
	s_waitcnt vmcnt(8)
	s_waitcnt lgkmcnt(0)
	s_barrier
; #define PG8_STAGE(bufoff, gbase, voff) do { _Pragma("unroll") for (int _i = 0; _i < 2; ++_i) \
;         __builtin_amdgcn_global_load_lds((const unsigned*)((const char*)(gbase) + (voff)[_i]), (LAS unsigned*)(lds + (bufoff) + ldsw + _i * 8192), 16, 0, 0); } while (0)
; #define PG8_LDA(dst, b, h) do { _Pragma("unroll") for (int m = 0; m < 4; ++m) _Pragma("unroll") for (int k = 0; k < 2; ++k) dst[m][k] = *(const LAS bf16x8*)(lds + PG8_SA(b, h) + aoff + m * 2048 + k * 1024); } while (0)
; #define PG8_MMA(ai, bj, At, Bt) do { __builtin_amdgcn_s_setprio(1); _Pragma("unroll") for (int m = 0; m < 4; ++m) _Pragma("unroll") for (int n = 0; n < 2; ++n) _Pragma("unroll") for (int k = 0; k < 2; ++k) \
;         acc[ai][bj][m][n] = __builtin_amdgcn_mfma_f32_16x16x32_bf16(Bt[n][k], At[m][k], acc[ai][bj][m][n], 0, 0, 0); __builtin_amdgcn_s_setprio(0); } while (0)
; #define PG8_WAIT_V(n) asm volatile("s_waitcnt vmcnt(" #n ")" ::: "memory")
; #define PG8_WAIT_L(n) asm volatile("s_waitcnt lgkmcnt(" #n ")" ::: "memory")
; #define PG8_BAR __builtin_amdgcn_s_barrier()
; #define PG8_SCHED __builtin_amdgcn_sched_barrier(0)
; template <class Epi, class Sched>
; __device__ __forceinline__ void gemm_phase(LAS unsigned char* lds, const Gemm g, const Sched& S, const Epi& E) {
;     ...
;             PG8_WAIT_V(8); PG8_WAIT_L(0); PG8_BAR; PG8_MMA(0, 0, At, B0); PG8_MMA(0, 1, At, B1); PG8_BAR; PG8_SCHED;
;             PG8_LDA(At, 0, 1); PG8_STAGE(PG8_SB(0, 0), b2, voffB); PG8_STAGE(PG8_SB(0, 1), b2 + hstepB, voffB); PG8_STAGE(PG8_SA(0, 0), a2, voffA);
;             PG8_WAIT_V(8); PG8_WAIT_L(0); PG8_BAR; PG8_MMA(1, 0, At, B0); PG8_MMA(1, 1, At, B1); PG8_BAR; PG8_SCHED;
	s_waitcnt lgkmcnt(0)
	v_mfma_f32_16x16x32_bf16 v[126:129], v[150:153], v[198:201], v[126:129]
	v_mfma_f32_16x16x32_bf16 v[122:125], v[158:161], v[198:201], v[122:125]
	v_mfma_f32_16x16x32_bf16 v[110:113], v[150:153], v[206:209], v[110:113]
	v_mfma_f32_16x16x32_bf16 v[106:109], v[158:161], v[206:209], v[106:109]
	v_mfma_f32_16x16x32_bf16 v[94:97], v[150:153], v[222:225], v[94:97]
	v_mfma_f32_16x16x32_bf16 v[90:93], v[158:161], v[222:225], v[90:93]
	v_mfma_f32_16x16x32_bf16 v[82:85], v[150:153], v[230:233], v[82:85]
	v_mfma_f32_16x16x32_bf16 v[74:77], v[158:161], v[230:233], v[74:77]
	v_mfma_f32_16x16x32_bf16 v[126:129], v[154:157], v[202:205], v[126:129]
	v_mfma_f32_16x16x32_bf16 v[122:125], v[162:165], v[202:205], v[122:125]
	v_mfma_f32_16x16x32_bf16 v[110:113], v[154:157], v[218:221], v[110:113]
	v_mfma_f32_16x16x32_bf16 v[106:109], v[162:165], v[218:221], v[106:109]
	v_mfma_f32_16x16x32_bf16 v[94:97], v[154:157], v[226:229], v[94:97]
	v_mfma_f32_16x16x32_bf16 v[90:93], v[162:165], v[226:229], v[90:93]
	v_mfma_f32_16x16x32_bf16 v[82:85], v[154:157], v[234:237], v[82:85]
	v_mfma_f32_16x16x32_bf16 v[74:77], v[162:165], v[234:237], v[74:77]
	v_mfma_f32_16x16x32_bf16 v[118:121], v[166:169], v[198:201], v[118:121]
	v_mfma_f32_16x16x32_bf16 v[114:117], v[190:193], v[198:201], v[114:117]
	v_mfma_f32_16x16x32_bf16 v[102:105], v[166:169], v[206:209], v[102:105]
	v_mfma_f32_16x16x32_bf16 v[98:101], v[190:193], v[206:209], v[98:101]
	v_mfma_f32_16x16x32_bf16 v[86:89], v[166:169], v[222:225], v[86:89]
	v_mfma_f32_16x16x32_bf16 v[78:81], v[190:193], v[222:225], v[78:81]
	v_mfma_f32_16x16x32_bf16 v[70:73], v[166:169], v[230:233], v[70:73]
	v_mfma_f32_16x16x32_bf16 v[66:69], v[190:193], v[230:233], v[66:69]
	v_mfma_f32_16x16x32_bf16 v[118:121], v[170:173], v[202:205], v[118:121]
	v_mfma_f32_16x16x32_bf16 v[114:117], v[194:197], v[202:205], v[114:117]
	v_mfma_f32_16x16x32_bf16 v[102:105], v[170:173], v[218:221], v[102:105]
	v_mfma_f32_16x16x32_bf16 v[98:101], v[194:197], v[218:221], v[98:101]
	v_mfma_f32_16x16x32_bf16 v[86:89], v[170:173], v[226:229], v[86:89]
	v_mfma_f32_16x16x32_bf16 v[78:81], v[194:197], v[226:229], v[78:81]
	v_mfma_f32_16x16x32_bf16 v[70:73], v[170:173], v[234:237], v[70:73]
	v_mfma_f32_16x16x32_bf16 v[66:69], v[194:197], v[234:237], v[66:69]
	s_barrier
	s_add_i32 s79, s79, s8
	s_mov_b32 m0, s79
	s_nop 0
	global_load_lds_dwordx4 v132, s[76:77]
	s_add_i32 m0, s79, 0x2000
	s_add_u32 s80, s76, 0x40000
	s_addc_u32 s81, s77, 0
	s_add_i32 s79, s82, s8
	global_load_lds_dwordx4 v136, s[76:77]
	s_mov_b32 m0, s79
	s_nop 0
	global_load_lds_dwordx4 v132, s[80:81]
	s_add_i32 m0, s79, 0x2000
	s_nop 0
	global_load_lds_dwordx4 v136, s[80:81]
	s_mov_b32 m0, s9
	s_nop 0
	global_load_lds_dwordx4 v130, s[20:21]
	s_mov_b32 m0, s28
	s_nop 0
	global_load_lds_dwordx4 v134, s[20:21]
	ds_read_b128 v[198:201], v148 offset:16384
	ds_read_b128 v[202:205], v148 offset:17408
	ds_read_b128 v[206:209], v148 offset:18432
	ds_read_b128 v[218:221], v148 offset:19456
	ds_read_b128 v[222:225], v148 offset:20480
	ds_read_b128 v[226:229], v148 offset:21504
	ds_read_b128 v[230:233], v148 offset:22528
	ds_read_b128 v[234:237], v148 offset:23552
	s_waitcnt vmcnt(8)
	s_waitcnt lgkmcnt(0)
	s_nop 0
	s_barrier
	s_waitcnt lgkmcnt(0)
	v_mfma_f32_16x16x32_bf16 v[62:65], v[150:153], v[198:201], v[62:65]
	v_mfma_f32_16x16x32_bf16 v[58:61], v[158:161], v[198:201], v[58:61]
	v_mfma_f32_16x16x32_bf16 v[50:53], v[150:153], v[206:209], v[50:53]
	v_mfma_f32_16x16x32_bf16 v[42:45], v[158:161], v[206:209], v[42:45]
	v_mfma_f32_16x16x32_bf16 v[30:33], v[150:153], v[222:225], v[30:33]
	v_mfma_f32_16x16x32_bf16 v[26:29], v[158:161], v[222:225], v[26:29]
	v_mfma_f32_16x16x32_bf16 v[18:21], v[150:153], v[230:233], v[18:21]
	v_mfma_f32_16x16x32_bf16 v[10:13], v[158:161], v[230:233], v[10:13]
	v_mfma_f32_16x16x32_bf16 v[62:65], v[154:157], v[202:205], v[62:65]
	v_mfma_f32_16x16x32_bf16 v[58:61], v[162:165], v[202:205], v[58:61]
	v_mfma_f32_16x16x32_bf16 v[50:53], v[154:157], v[218:221], v[50:53]
	v_mfma_f32_16x16x32_bf16 v[42:45], v[162:165], v[218:221], v[42:45]
	v_mfma_f32_16x16x32_bf16 v[30:33], v[154:157], v[226:229], v[30:33]
	v_mfma_f32_16x16x32_bf16 v[26:29], v[162:165], v[226:229], v[26:29]
	v_mfma_f32_16x16x32_bf16 v[18:21], v[154:157], v[234:237], v[18:21]
	v_mfma_f32_16x16x32_bf16 v[10:13], v[162:165], v[234:237], v[10:13]
	v_mfma_f32_16x16x32_bf16 v[54:57], v[166:169], v[198:201], v[54:57]
	v_mfma_f32_16x16x32_bf16 v[46:49], v[190:193], v[198:201], v[46:49]
	v_mfma_f32_16x16x32_bf16 v[38:41], v[166:169], v[206:209], v[38:41]
	v_mfma_f32_16x16x32_bf16 v[34:37], v[190:193], v[206:209], v[34:37]
	v_mfma_f32_16x16x32_bf16 v[22:25], v[166:169], v[222:225], v[22:25]
	v_mfma_f32_16x16x32_bf16 v[14:17], v[190:193], v[222:225], v[14:17]
	v_mfma_f32_16x16x32_bf16 v[6:9], v[166:169], v[230:233], v[6:9]
	v_mfma_f32_16x16x32_bf16 v[2:5], v[190:193], v[230:233], v[2:5]
	v_mfma_f32_16x16x32_bf16 v[54:57], v[170:173], v[202:205], v[54:57]
	v_mfma_f32_16x16x32_bf16 v[46:49], v[194:197], v[202:205], v[46:49]
	v_mfma_f32_16x16x32_bf16 v[38:41], v[170:173], v[218:221], v[38:41]
	v_mfma_f32_16x16x32_bf16 v[34:37], v[194:197], v[218:221], v[34:37]
	v_mfma_f32_16x16x32_bf16 v[22:25], v[170:173], v[226:229], v[22:25]
	v_mfma_f32_16x16x32_bf16 v[14:17], v[194:197], v[226:229], v[14:17]
	v_mfma_f32_16x16x32_bf16 v[6:9], v[170:173], v[234:237], v[6:9]
	v_mfma_f32_16x16x32_bf16 v[2:5], v[194:197], v[234:237], v[2:5]
	s_barrier
; #define PG8_STAGE(bufoff, gbase, voff) do { _Pragma("unroll") for (int _i = 0; _i < 2; ++_i) \
;         __builtin_amdgcn_global_load_lds((const unsigned*)((const char*)(gbase) + (voff)[_i]), (LAS unsigned*)(lds + (bufoff) + ldsw + _i * 8192), 16, 0, 0); } while (0)
; #define PG8_LDA(dst, b, h) do { _Pragma("unroll") for (int m = 0; m < 4; ++m) _Pragma("unroll") for (int k = 0; k < 2; ++k) dst[m][k] = *(const LAS bf16x8*)(lds + PG8_SA(b, h) + aoff + m * 2048 + k * 1024); } while (0)
; #define PG8_LDB(dst, b, h) do { _Pragma("unroll") for (int n = 0; n < 2; ++n) _Pragma("unroll") for (int k = 0; k < 2; ++k) dst[n][k] = *(const LAS bf16x8*)(lds + PG8_SB(b, h) + boff + n * 2048 + k * 1024); } while (0)
; #define PG8_MMA(ai, bj, At, Bt) do { __builtin_amdgcn_s_setprio(1); _Pragma("unroll") for (int m = 0; m < 4; ++m) _Pragma("unroll") for (int n = 0; n < 2; ++n) _Pragma("unroll") for (int k = 0; k < 2; ++k) \
;         acc[ai][bj][m][n] = __builtin_amdgcn_mfma_f32_16x16x32_bf16(Bt[n][k], At[m][k], acc[ai][bj][m][n], 0, 0, 0); __builtin_amdgcn_s_setprio(0); } while (0)
; #define PG8_WAIT_V(n) asm volatile("s_waitcnt vmcnt(" #n ")" ::: "memory")
; #define PG8_WAIT_L(n) asm volatile("s_waitcnt lgkmcnt(" #n ")" ::: "memory")
; #define PG8_BAR __builtin_amdgcn_s_barrier()
; #define PG8_SCHED __builtin_amdgcn_sched_barrier(0)
; template <class Epi, class Sched>
; __device__ __forceinline__ void gemm_phase(LAS unsigned char* lds, const Gemm g, const Sched& S, const Epi& E) {
;     ...
;             PG8_LDB(B0, 1, 0); PG8_LDB(B1, 1, 1); PG8_SCHED; PG8_LDA(At, 1, 0); PG8_STAGE(PG8_SA(0, 1), a2 + hstepA, voffA);
;             PG8_WAIT_V(8); PG8_WAIT_L(0); PG8_BAR; PG8_MMA(0, 0, At, B0); PG8_MMA(0, 1, At, B1); PG8_BAR; PG8_SCHED;
;             PG8_LDA(At, 1, 1); PG8_STAGE(PG8_SB(1, 0), b3, voffB); PG8_STAGE(PG8_SB(1, 1), b3 + hstepB, voffB); PG8_STAGE(PG8_SA(1, 0), a3, voffA);
;             PG8_WAIT_V(8); PG8_WAIT_L(0); PG8_BAR; PG8_MMA(1, 0, At, B0); PG8_MMA(1, 1, At, B1); PG8_BAR; PG8_SCHED;
;         }
;         if (wr == 0) PG8_BAR;
	s_add_i32 s79, 0, 0x18000
	s_add_i32 s80, 0, 0x1c000
	s_add_u32 s20, s20, 0x40000
	s_addc_u32 s21, s21, 0
	s_mov_b32 m0, s29
	s_nop 0
	global_load_lds_dwordx4 v130, s[20:21]
	s_mov_b32 m0, s30
	s_nop 0
	global_load_lds_dwordx4 v134, s[20:21]
	ds_read_b128 v[150:153], v255 offset:32768
	ds_read_b128 v[154:157], v255 offset:33792
	ds_read_b128 v[158:161], v255 offset:34816
	ds_read_b128 v[162:165], v255 offset:35840
	ds_read_b128 v[166:169], v255 offset:49152
	ds_read_b128 v[170:173], v255 offset:50176
	ds_read_b128 v[190:193], v255 offset:51200
	ds_read_b128 v[194:197], v255 offset:52224
	ds_read_b128 v[198:201], v148 offset:32768
	ds_read_b128 v[202:205], v148 offset:33792
	ds_read_b128 v[206:209], v148 offset:34816
	ds_read_b128 v[218:221], v148 offset:35840
	ds_read_b128 v[222:225], v148 offset:36864
	ds_read_b128 v[226:229], v148 offset:37888
	ds_read_b128 v[230:233], v148 offset:38912
	ds_read_b128 v[234:237], v148 offset:39936
	s_waitcnt vmcnt(8)
	s_waitcnt lgkmcnt(0)
	s_barrier
	s_waitcnt lgkmcnt(0)
	v_mfma_f32_16x16x32_bf16 v[126:129], v[150:153], v[198:201], v[126:129]
	v_mfma_f32_16x16x32_bf16 v[122:125], v[158:161], v[198:201], v[122:125]
	v_mfma_f32_16x16x32_bf16 v[110:113], v[150:153], v[206:209], v[110:113]
	v_mfma_f32_16x16x32_bf16 v[106:109], v[158:161], v[206:209], v[106:109]
	v_mfma_f32_16x16x32_bf16 v[94:97], v[150:153], v[222:225], v[94:97]
	v_mfma_f32_16x16x32_bf16 v[90:93], v[158:161], v[222:225], v[90:93]
	v_mfma_f32_16x16x32_bf16 v[82:85], v[150:153], v[230:233], v[82:85]
	v_mfma_f32_16x16x32_bf16 v[74:77], v[158:161], v[230:233], v[74:77]
	v_mfma_f32_16x16x32_bf16 v[126:129], v[154:157], v[202:205], v[126:129]
	v_mfma_f32_16x16x32_bf16 v[122:125], v[162:165], v[202:205], v[122:125]
	v_mfma_f32_16x16x32_bf16 v[110:113], v[154:157], v[218:221], v[110:113]
	v_mfma_f32_16x16x32_bf16 v[106:109], v[162:165], v[218:221], v[106:109]
	v_mfma_f32_16x16x32_bf16 v[94:97], v[154:157], v[226:229], v[94:97]
	v_mfma_f32_16x16x32_bf16 v[90:93], v[162:165], v[226:229], v[90:93]
	v_mfma_f32_16x16x32_bf16 v[82:85], v[154:157], v[234:237], v[82:85]
	v_mfma_f32_16x16x32_bf16 v[74:77], v[162:165], v[234:237], v[74:77]
	v_mfma_f32_16x16x32_bf16 v[118:121], v[166:169], v[198:201], v[118:121]
	v_mfma_f32_16x16x32_bf16 v[114:117], v[190:193], v[198:201], v[114:117]
	v_mfma_f32_16x16x32_bf16 v[102:105], v[166:169], v[206:209], v[102:105]
	v_mfma_f32_16x16x32_bf16 v[98:101], v[190:193], v[206:209], v[98:101]
	v_mfma_f32_16x16x32_bf16 v[86:89], v[166:169], v[222:225], v[86:89]
	v_mfma_f32_16x16x32_bf16 v[78:81], v[190:193], v[222:225], v[78:81]
	v_mfma_f32_16x16x32_bf16 v[70:73], v[166:169], v[230:233], v[70:73]
	v_mfma_f32_16x16x32_bf16 v[66:69], v[190:193], v[230:233], v[66:69]
	v_mfma_f32_16x16x32_bf16 v[118:121], v[170:173], v[202:205], v[118:121]
	v_mfma_f32_16x16x32_bf16 v[114:117], v[194:197], v[202:205], v[114:117]
	v_mfma_f32_16x16x32_bf16 v[102:105], v[170:173], v[218:221], v[102:105]
	v_mfma_f32_16x16x32_bf16 v[98:101], v[194:197], v[218:221], v[98:101]
	v_mfma_f32_16x16x32_bf16 v[86:89], v[170:173], v[226:229], v[86:89]
	v_mfma_f32_16x16x32_bf16 v[78:81], v[194:197], v[226:229], v[78:81]
	v_mfma_f32_16x16x32_bf16 v[70:73], v[170:173], v[234:237], v[70:73]
	v_mfma_f32_16x16x32_bf16 v[66:69], v[194:197], v[234:237], v[66:69]
	s_barrier
	s_add_i32 s20, s8, 0x18000
	s_add_u32 s80, s76, 0x80
	s_addc_u32 s81, s77, 0
	s_mov_b32 m0, s20
	s_nop 0
	global_load_lds_dwordx4 v132, s[80:81]
	s_add_i32 m0, s20, 0x2000
	s_add_u32 s20, s76, 0x40080
	s_addc_u32 s21, s77, 0
	s_add_i32 s12, s8, 0x1c000
	global_load_lds_dwordx4 v136, s[80:81]
	s_mov_b32 m0, s12
	s_nop 0
	global_load_lds_dwordx4 v132, s[20:21]
	s_add_i32 m0, s12, 0x2000
	s_nop 0
	global_load_lds_dwordx4 v136, s[20:21]
	s_mov_b32 m0, s31
	s_nop 0
	global_load_lds_dwordx4 v130, s[100:101]
	s_mov_b32 m0, s34
	s_nop 0
	global_load_lds_dwordx4 v134, s[100:101]
	ds_read_b128 v[198:201], v148 offset:49152
	ds_read_b128 v[202:205], v148 offset:50176
	ds_read_b128 v[206:209], v148 offset:51200
	ds_read_b128 v[218:221], v148 offset:52224
	ds_read_b128 v[222:225], v148 offset:53248
	ds_read_b128 v[226:229], v148 offset:54272
	ds_read_b128 v[230:233], v148 offset:55296
	ds_read_b128 v[234:237], v148 offset:56320
	s_waitcnt vmcnt(8)
	s_waitcnt lgkmcnt(0)
	s_barrier
	s_waitcnt lgkmcnt(0)
	v_mfma_f32_16x16x32_bf16 v[62:65], v[150:153], v[198:201], v[62:65]
	v_mfma_f32_16x16x32_bf16 v[58:61], v[158:161], v[198:201], v[58:61]
	v_mfma_f32_16x16x32_bf16 v[50:53], v[150:153], v[206:209], v[50:53]
	v_mfma_f32_16x16x32_bf16 v[42:45], v[158:161], v[206:209], v[42:45]
	v_mfma_f32_16x16x32_bf16 v[30:33], v[150:153], v[222:225], v[30:33]
	v_mfma_f32_16x16x32_bf16 v[26:29], v[158:161], v[222:225], v[26:29]
	v_mfma_f32_16x16x32_bf16 v[18:21], v[150:153], v[230:233], v[18:21]
	v_mfma_f32_16x16x32_bf16 v[10:13], v[158:161], v[230:233], v[10:13]
	v_mfma_f32_16x16x32_bf16 v[62:65], v[154:157], v[202:205], v[62:65]
	v_mfma_f32_16x16x32_bf16 v[58:61], v[162:165], v[202:205], v[58:61]
	v_mfma_f32_16x16x32_bf16 v[50:53], v[154:157], v[218:221], v[50:53]
	v_mfma_f32_16x16x32_bf16 v[42:45], v[162:165], v[218:221], v[42:45]
	v_mfma_f32_16x16x32_bf16 v[30:33], v[154:157], v[226:229], v[30:33]
	v_mfma_f32_16x16x32_bf16 v[26:29], v[162:165], v[226:229], v[26:29]
	v_mfma_f32_16x16x32_bf16 v[18:21], v[154:157], v[234:237], v[18:21]
	v_mfma_f32_16x16x32_bf16 v[10:13], v[162:165], v[234:237], v[10:13]
	v_mfma_f32_16x16x32_bf16 v[54:57], v[166:169], v[198:201], v[54:57]
	v_mfma_f32_16x16x32_bf16 v[46:49], v[190:193], v[198:201], v[46:49]
	v_mfma_f32_16x16x32_bf16 v[38:41], v[166:169], v[206:209], v[38:41]
	v_mfma_f32_16x16x32_bf16 v[34:37], v[190:193], v[206:209], v[34:37]
	v_mfma_f32_16x16x32_bf16 v[22:25], v[166:169], v[222:225], v[22:25]
	v_mfma_f32_16x16x32_bf16 v[14:17], v[190:193], v[222:225], v[14:17]
	v_mfma_f32_16x16x32_bf16 v[6:9], v[166:169], v[230:233], v[6:9]
	v_mfma_f32_16x16x32_bf16 v[2:5], v[190:193], v[230:233], v[2:5]
	v_mfma_f32_16x16x32_bf16 v[54:57], v[170:173], v[202:205], v[54:57]
	v_mfma_f32_16x16x32_bf16 v[46:49], v[194:197], v[202:205], v[46:49]
	v_mfma_f32_16x16x32_bf16 v[38:41], v[170:173], v[218:221], v[38:41]
	v_mfma_f32_16x16x32_bf16 v[34:37], v[194:197], v[218:221], v[34:37]
	v_mfma_f32_16x16x32_bf16 v[22:25], v[170:173], v[226:229], v[22:25]
	v_mfma_f32_16x16x32_bf16 v[14:17], v[194:197], v[226:229], v[14:17]
	v_mfma_f32_16x16x32_bf16 v[6:9], v[170:173], v[234:237], v[6:9]
	v_mfma_f32_16x16x32_bf16 v[2:5], v[194:197], v[234:237], v[2:5]
	s_barrier
	s_add_i32 s78, s78, 2
	s_add_u32 s18, s18, 0x100
	s_addc_u32 s19, s19, 0
	s_add_u32 s69, s69, 0x100
	s_addc_u32 s71, s71, 0
	s_cmp_gt_u32 s78, 13
	s_cbranch_scc0 .LBB0_349
	s_and_b64 vcc, exec, s[36:37]
	s_cbranch_vccz .LBB0_352
	s_barrier

; #define PG8_STAGE(bufoff, gbase, voff) do { _Pragma("unroll") for (int _i = 0; _i < 2; ++_i) \
;         __builtin_amdgcn_global_load_lds((const unsigned*)((const char*)(gbase) + (voff)[_i]), (LAS unsigned*)(lds + (bufoff) + ldsw + _i * 8192), 16, 0, 0); } while (0)
; #define PG8_LDA(dst, b, h) do { _Pragma("unroll") for (int m = 0; m < 4; ++m) _Pragma("unroll") for (int k = 0; k < 2; ++k) dst[m][k] = *(const LAS bf16x8*)(lds + PG8_SA(b, h) + aoff + m * 2048 + k * 1024); } while (0)
; #define PG8_LDB(dst, b, h) do { _Pragma("unroll") for (int n = 0; n < 2; ++n) _Pragma("unroll") for (int k = 0; k < 2; ++k) dst[n][k] = *(const LAS bf16x8*)(lds + PG8_SB(b, h) + boff + n * 2048 + k * 1024); } while (0)
; #define PG8_MMA(ai, bj, At, Bt) do { __builtin_amdgcn_s_setprio(1); _Pragma("unroll") for (int m = 0; m < 4; ++m) _Pragma("unroll") for (int n = 0; n < 2; ++n) _Pragma("unroll") for (int k = 0; k < 2; ++k) \
;         acc[ai][bj][m][n] = __builtin_amdgcn_mfma_f32_16x16x32_bf16(Bt[n][k], At[m][k], acc[ai][bj][m][n], 0, 0, 0); __builtin_amdgcn_s_setprio(0); } while (0)
; #define PG8_WAIT_V(n) asm volatile("s_waitcnt vmcnt(" #n ")" ::: "memory")
; #define PG8_WAIT_L(n) asm volatile("s_waitcnt lgkmcnt(" #n ")" ::: "memory")
; #define PG8_BAR __builtin_amdgcn_s_barrier()
; #define PG8_SCHED __builtin_amdgcn_sched_barrier(0)
; template <class Epi, class Sched>
; __device__ __forceinline__ void gemm_phase(LAS unsigned char* lds, const Gemm g, const Sched& S, const Epi& E) {
;     ...
;             PG8_LDB(B0, 0, 0); PG8_LDB(B1, 0, 1); PG8_SCHED; PG8_LDA(At, 0, 0); PG8_STAGE(PG8_SA(1, 1), a1 + hstepA, voffA);
;             PG8_WAIT_V(8); PG8_WAIT_L(0); PG8_BAR; PG8_MMA(0, 0, At, B0); PG8_MMA(0, 1, At, B1); PG8_BAR; PG8_SCHED;
;             PG8_LDA(At, 0, 1); PG8_STAGE(PG8_SB(0, 0), b2, voffB); PG8_STAGE(PG8_SB(0, 1), b2 + hstepB, voffB); PG8_STAGE(PG8_SA(0, 0), a2, voffA);
;             PG8_WAIT_V(8); PG8_WAIT_L(0); PG8_BAR; PG8_MMA(1, 0, At, B0); PG8_MMA(1, 1, At, B1); PG8_BAR; PG8_SCHED;
.LBB0_377:
	s_ashr_i32 s71, s70, 31
	s_lshl_b64 s[48:49], s[70:71], 19
	v_readlane_b32 s12, v248, 21
	s_add_u32 s72, s12, s48
	v_readlane_b32 s12, v248, 22
	s_addc_u32 s73, s12, s49
	s_and_b64 s[48:49], s[66:67], exec
	s_cselect_b32 s43, s73, s19
	s_cselect_b32 s48, s72, s18
	s_ashr_i32 s69, s68, 31
	s_lshl_b64 s[74:75], s[68:69], 19
	s_add_u32 s74, s4, s74
	s_addc_u32 s75, s5, s75
	s_and_b64 s[76:77], s[66:67], exec
	s_cselect_b32 s49, s75, s21
	s_cselect_b32 s53, s74, s20
	s_add_u32 s18, s18, 0x40080
	s_addc_u32 s19, s19, 0
	s_add_u32 s69, s20, 0x100
	s_addc_u32 s71, s21, 0
	s_mov_b32 s78, -2
	v_add_u32_e32 v255, 0x10000, v158
	s_add_u32 s20, s18, 0xfffc0080
	s_addc_u32 s21, s19, -1
	s_add_i32 s79, 0, 0x10000
	s_cmp_eq_u32 s78, 12
	s_cselect_b32 s21, s43, s21
	s_cselect_b32 s20, s48, s20
	s_cselect_b32 s77, s49, s71
	s_cselect_b32 s76, s53, s69
	s_add_u32 s100, s20, 0x80
	s_addc_u32 s101, s21, 0
	s_add_i32 s82, 0, 0x14000
	s_add_i32 m0, s9, 0xc000
	s_nop 0
	global_load_lds_dwordx4 v146, s[18:19]
	s_add_i32 m0, s9, 0xe000
	s_nop 0
	global_load_lds_dwordx4 v150, s[18:19]
	ds_read_b128 v[130:133], v255
	ds_read_b128 v[134:137], v255 offset:1024
	ds_read_b128 v[138:141], v255 offset:2048
	ds_read_b128 v[142:145], v255 offset:3072
	ds_read_b128 v[162:165], v255 offset:16384
	ds_read_b128 v[166:169], v255 offset:17408
	ds_read_b128 v[170:173], v255 offset:18432
	ds_read_b128 v[190:193], v255 offset:19456
	ds_read_b128 v[194:197], v160
	ds_read_b128 v[198:201], v160 offset:1024
	ds_read_b128 v[202:205], v160 offset:2048
	ds_read_b128 v[206:209], v160 offset:3072
	ds_read_b128 v[218:221], v160 offset:4096
	ds_read_b128 v[222:225], v160 offset:5120
	ds_read_b128 v[226:229], v160 offset:6144
	ds_read_b128 v[230:233], v160 offset:7168
	s_waitcnt vmcnt(8)
	s_waitcnt lgkmcnt(0)
	s_barrier
	s_waitcnt lgkmcnt(0)
	v_mfma_f32_16x16x32_bf16 v[126:129], v[130:133], v[194:197], 0
	v_mfma_f32_16x16x32_bf16 v[122:125], v[138:141], v[194:197], 0
	v_mfma_f32_16x16x32_bf16 v[118:121], v[130:133], v[202:205], 0
	v_mfma_f32_16x16x32_bf16 v[110:113], v[138:141], v[202:205], 0
	v_mfma_f32_16x16x32_bf16 v[102:105], v[130:133], v[218:221], 0
	v_mfma_f32_16x16x32_bf16 v[94:97], v[138:141], v[218:221], 0
	v_mfma_f32_16x16x32_bf16 v[86:89], v[130:133], v[226:229], 0
	v_mfma_f32_16x16x32_bf16 v[78:81], v[138:141], v[226:229], 0
	v_mfma_f32_16x16x32_bf16 v[126:129], v[134:137], v[198:201], v[126:129]
	v_mfma_f32_16x16x32_bf16 v[122:125], v[142:145], v[198:201], v[122:125]
	v_mfma_f32_16x16x32_bf16 v[118:121], v[134:137], v[206:209], v[118:121]
	v_mfma_f32_16x16x32_bf16 v[110:113], v[142:145], v[206:209], v[110:113]
	v_mfma_f32_16x16x32_bf16 v[102:105], v[134:137], v[222:225], v[102:105]
	v_mfma_f32_16x16x32_bf16 v[94:97], v[142:145], v[222:225], v[94:97]
	v_mfma_f32_16x16x32_bf16 v[86:89], v[134:137], v[230:233], v[86:89]
	v_mfma_f32_16x16x32_bf16 v[78:81], v[142:145], v[230:233], v[78:81]
	v_mfma_f32_16x16x32_bf16 v[114:117], v[162:165], v[194:197], 0
	v_mfma_f32_16x16x32_bf16 v[106:109], v[170:173], v[194:197], 0
	v_mfma_f32_16x16x32_bf16 v[98:101], v[162:165], v[202:205], 0
	v_mfma_f32_16x16x32_bf16 v[90:93], v[170:173], v[202:205], 0
	v_mfma_f32_16x16x32_bf16 v[82:85], v[162:165], v[218:221], 0
	v_mfma_f32_16x16x32_bf16 v[74:77], v[170:173], v[218:221], 0
	v_mfma_f32_16x16x32_bf16 v[70:73], v[162:165], v[226:229], 0
	v_mfma_f32_16x16x32_bf16 v[66:69], v[170:173], v[226:229], 0
	v_mfma_f32_16x16x32_bf16 v[114:117], v[166:169], v[198:201], v[114:117]
	v_mfma_f32_16x16x32_bf16 v[106:109], v[190:193], v[198:201], v[106:109]
	v_mfma_f32_16x16x32_bf16 v[98:101], v[166:169], v[206:209], v[98:101]
	v_mfma_f32_16x16x32_bf16 v[90:93], v[190:193], v[206:209], v[90:93]
	v_mfma_f32_16x16x32_bf16 v[82:85], v[166:169], v[222:225], v[82:85]
	v_mfma_f32_16x16x32_bf16 v[74:77], v[190:193], v[222:225], v[74:77]
	v_mfma_f32_16x16x32_bf16 v[70:73], v[166:169], v[230:233], v[70:73]
	v_mfma_f32_16x16x32_bf16 v[66:69], v[190:193], v[230:233], v[66:69]
	s_barrier
	s_add_i32 s79, s79, s8
	s_mov_b32 m0, s79
	s_nop 0
	global_load_lds_dwordx4 v148, s[76:77]
	s_add_i32 m0, s79, 0x2000
	s_add_u32 s80, s76, 0x40000
	s_addc_u32 s81, s77, 0
	s_add_i32 s79, s82, s8
	global_load_lds_dwordx4 v152, s[76:77]
	s_mov_b32 m0, s79
	s_nop 0
	global_load_lds_dwordx4 v148, s[80:81]
	s_add_i32 m0, s79, 0x2000
	s_nop 0
	global_load_lds_dwordx4 v152, s[80:81]
	s_mov_b32 m0, s9
	s_nop 0
	global_load_lds_dwordx4 v146, s[20:21]
	s_mov_b32 m0, s28
	s_nop 0
	global_load_lds_dwordx4 v150, s[20:21]
	ds_read_b128 v[194:197], v160 offset:16384
	ds_read_b128 v[198:201], v160 offset:17408
	ds_read_b128 v[202:205], v160 offset:18432
	ds_read_b128 v[206:209], v160 offset:19456
	ds_read_b128 v[218:221], v160 offset:20480
	ds_read_b128 v[222:225], v160 offset:21504
	ds_read_b128 v[226:229], v160 offset:22528
	ds_read_b128 v[230:233], v160 offset:23552
	s_waitcnt vmcnt(8)
	s_waitcnt lgkmcnt(0)
	s_nop 0
	s_barrier
; #define PG8_STAGE(bufoff, gbase, voff) do { _Pragma("unroll") for (int _i = 0; _i < 2; ++_i) \
;         __builtin_amdgcn_global_load_lds((const unsigned*)((const char*)(gbase) + (voff)[_i]), (LAS unsigned*)(lds + (bufoff) + ldsw + _i * 8192), 16, 0, 0); } while (0)
; #define PG8_LDA(dst, b, h) do { _Pragma("unroll") for (int m = 0; m < 4; ++m) _Pragma("unroll") for (int k = 0; k < 2; ++k) dst[m][k] = *(const LAS bf16x8*)(lds + PG8_SA(b, h) + aoff + m * 2048 + k * 1024); } while (0)
; #define PG8_LDB(dst, b, h) do { _Pragma("unroll") for (int n = 0; n < 2; ++n) _Pragma("unroll") for (int k = 0; k < 2; ++k) dst[n][k] = *(const LAS bf16x8*)(lds + PG8_SB(b, h) + boff + n * 2048 + k * 1024); } while (0)
; #define PG8_MMA(ai, bj, At, Bt) do { __builtin_amdgcn_s_setprio(1); _Pragma("unroll") for (int m = 0; m < 4; ++m) _Pragma("unroll") for (int n = 0; n < 2; ++n) _Pragma("unroll") for (int k = 0; k < 2; ++k) \
;         acc[ai][bj][m][n] = __builtin_amdgcn_mfma_f32_16x16x32_bf16(Bt[n][k], At[m][k], acc[ai][bj][m][n], 0, 0, 0); __builtin_amdgcn_s_setprio(0); } while (0)
; #define PG8_WAIT_V(n) asm volatile("s_waitcnt vmcnt(" #n ")" ::: "memory")
; #define PG8_WAIT_L(n) asm volatile("s_waitcnt lgkmcnt(" #n ")" ::: "memory")
; #define PG8_BAR __builtin_amdgcn_s_barrier()
; #define PG8_SCHED __builtin_amdgcn_sched_barrier(0)
; template <class Epi, class Sched>
; __device__ __forceinline__ void gemm_phase(LAS unsigned char* lds, const Gemm g, const Sched& S, const Epi& E) {
;     ...
;             PG8_WAIT_V(8); PG8_WAIT_L(0); PG8_BAR; PG8_MMA(1, 0, At, B0); PG8_MMA(1, 1, At, B1); PG8_BAR; PG8_SCHED;
;             PG8_LDB(B0, 1, 0); PG8_LDB(B1, 1, 1); PG8_SCHED; PG8_LDA(At, 1, 0); PG8_STAGE(PG8_SA(0, 1), a2 + hstepA, voffA);
;             PG8_WAIT_V(8); PG8_WAIT_L(0); PG8_BAR; PG8_MMA(0, 0, At, B0); PG8_MMA(0, 1, At, B1); PG8_BAR; PG8_SCHED;
;             PG8_LDA(At, 1, 1); PG8_STAGE(PG8_SB(1, 0), b3, voffB); PG8_STAGE(PG8_SB(1, 1), b3 + hstepB, voffB); PG8_STAGE(PG8_SA(1, 0), a3, voffA);
;             PG8_WAIT_V(8); PG8_WAIT_L(0); PG8_BAR; PG8_MMA(1, 0, At, B0); PG8_MMA(1, 1, At, B1); PG8_BAR; PG8_SCHED;
	s_waitcnt lgkmcnt(0)
	v_mfma_f32_16x16x32_bf16 v[62:65], v[130:133], v[194:197], 0
	v_mfma_f32_16x16x32_bf16 v[58:61], v[138:141], v[194:197], 0
	v_mfma_f32_16x16x32_bf16 v[54:57], v[130:133], v[202:205], 0
	v_mfma_f32_16x16x32_bf16 v[46:49], v[138:141], v[202:205], 0
	v_mfma_f32_16x16x32_bf16 v[38:41], v[130:133], v[218:221], 0
	v_mfma_f32_16x16x32_bf16 v[30:33], v[138:141], v[218:221], 0
	v_mfma_f32_16x16x32_bf16 v[22:25], v[130:133], v[226:229], 0
	v_mfma_f32_16x16x32_bf16 v[14:17], v[138:141], v[226:229], 0
	v_mfma_f32_16x16x32_bf16 v[62:65], v[134:137], v[198:201], v[62:65]
	v_mfma_f32_16x16x32_bf16 v[58:61], v[142:145], v[198:201], v[58:61]
	v_mfma_f32_16x16x32_bf16 v[54:57], v[134:137], v[206:209], v[54:57]
	v_mfma_f32_16x16x32_bf16 v[46:49], v[142:145], v[206:209], v[46:49]
	v_mfma_f32_16x16x32_bf16 v[38:41], v[134:137], v[222:225], v[38:41]
	v_mfma_f32_16x16x32_bf16 v[30:33], v[142:145], v[222:225], v[30:33]
	v_mfma_f32_16x16x32_bf16 v[22:25], v[134:137], v[230:233], v[22:25]
	v_mfma_f32_16x16x32_bf16 v[14:17], v[142:145], v[230:233], v[14:17]
	v_mfma_f32_16x16x32_bf16 v[50:53], v[162:165], v[194:197], 0
	v_mfma_f32_16x16x32_bf16 v[42:45], v[170:173], v[194:197], 0
	v_mfma_f32_16x16x32_bf16 v[34:37], v[162:165], v[202:205], 0
	v_mfma_f32_16x16x32_bf16 v[26:29], v[170:173], v[202:205], 0
	v_mfma_f32_16x16x32_bf16 v[18:21], v[162:165], v[218:221], 0
	v_mfma_f32_16x16x32_bf16 v[10:13], v[170:173], v[218:221], 0
	v_mfma_f32_16x16x32_bf16 v[6:9], v[162:165], v[226:229], 0
	v_mfma_f32_16x16x32_bf16 v[2:5], v[170:173], v[226:229], 0
	v_mfma_f32_16x16x32_bf16 v[50:53], v[166:169], v[198:201], v[50:53]
	v_mfma_f32_16x16x32_bf16 v[42:45], v[190:193], v[198:201], v[42:45]
	v_mfma_f32_16x16x32_bf16 v[34:37], v[166:169], v[206:209], v[34:37]
	v_mfma_f32_16x16x32_bf16 v[26:29], v[190:193], v[206:209], v[26:29]
	v_mfma_f32_16x16x32_bf16 v[18:21], v[166:169], v[222:225], v[18:21]
	v_mfma_f32_16x16x32_bf16 v[10:13], v[190:193], v[222:225], v[10:13]
	v_mfma_f32_16x16x32_bf16 v[6:9], v[166:169], v[230:233], v[6:9]
	v_mfma_f32_16x16x32_bf16 v[2:5], v[190:193], v[230:233], v[2:5]
	s_barrier
	s_add_i32 s79, 0, 0x18000
	s_add_i32 s80, 0, 0x1c000
	s_add_u32 s20, s20, 0x40000
	s_addc_u32 s21, s21, 0
	s_mov_b32 m0, s29
	s_nop 0
	global_load_lds_dwordx4 v146, s[20:21]
	s_mov_b32 m0, s30
	s_nop 0
	global_load_lds_dwordx4 v150, s[20:21]
	ds_read_b128 v[130:133], v255 offset:32768
	ds_read_b128 v[134:137], v255 offset:33792
	ds_read_b128 v[138:141], v255 offset:34816
	ds_read_b128 v[142:145], v255 offset:35840
	ds_read_b128 v[162:165], v255 offset:49152
	ds_read_b128 v[166:169], v255 offset:50176
	ds_read_b128 v[170:173], v255 offset:51200
	ds_read_b128 v[190:193], v255 offset:52224
	ds_read_b128 v[194:197], v160 offset:32768
	ds_read_b128 v[198:201], v160 offset:33792
	ds_read_b128 v[202:205], v160 offset:34816
	ds_read_b128 v[206:209], v160 offset:35840
	ds_read_b128 v[218:221], v160 offset:36864
	ds_read_b128 v[222:225], v160 offset:37888
	ds_read_b128 v[226:229], v160 offset:38912
	ds_read_b128 v[230:233], v160 offset:39936
	s_waitcnt vmcnt(8)
	s_waitcnt lgkmcnt(0)
	s_barrier
	s_waitcnt lgkmcnt(0)
	v_mfma_f32_16x16x32_bf16 v[126:129], v[130:133], v[194:197], v[126:129]
	v_mfma_f32_16x16x32_bf16 v[122:125], v[138:141], v[194:197], v[122:125]
	v_mfma_f32_16x16x32_bf16 v[118:121], v[130:133], v[202:205], v[118:121]
	v_mfma_f32_16x16x32_bf16 v[110:113], v[138:141], v[202:205], v[110:113]
	v_mfma_f32_16x16x32_bf16 v[102:105], v[130:133], v[218:221], v[102:105]
	v_mfma_f32_16x16x32_bf16 v[94:97], v[138:141], v[218:221], v[94:97]
	v_mfma_f32_16x16x32_bf16 v[86:89], v[130:133], v[226:229], v[86:89]
	v_mfma_f32_16x16x32_bf16 v[78:81], v[138:141], v[226:229], v[78:81]
	v_mfma_f32_16x16x32_bf16 v[126:129], v[134:137], v[198:201], v[126:129]
	v_mfma_f32_16x16x32_bf16 v[122:125], v[142:145], v[198:201], v[122:125]
	v_mfma_f32_16x16x32_bf16 v[118:121], v[134:137], v[206:209], v[118:121]
	v_mfma_f32_16x16x32_bf16 v[110:113], v[142:145], v[206:209], v[110:113]
	v_mfma_f32_16x16x32_bf16 v[102:105], v[134:137], v[222:225], v[102:105]
	v_mfma_f32_16x16x32_bf16 v[94:97], v[142:145], v[222:225], v[94:97]
	v_mfma_f32_16x16x32_bf16 v[86:89], v[134:137], v[230:233], v[86:89]
	v_mfma_f32_16x16x32_bf16 v[78:81], v[142:145], v[230:233], v[78:81]
	v_mfma_f32_16x16x32_bf16 v[114:117], v[162:165], v[194:197], v[114:117]
	v_mfma_f32_16x16x32_bf16 v[106:109], v[170:173], v[194:197], v[106:109]
	v_mfma_f32_16x16x32_bf16 v[98:101], v[162:165], v[202:205], v[98:101]
	v_mfma_f32_16x16x32_bf16 v[90:93], v[170:173], v[202:205], v[90:93]
	v_mfma_f32_16x16x32_bf16 v[82:85], v[162:165], v[218:221], v[82:85]
	v_mfma_f32_16x16x32_bf16 v[74:77], v[170:173], v[218:221], v[74:77]
	v_mfma_f32_16x16x32_bf16 v[70:73], v[162:165], v[226:229], v[70:73]
	v_mfma_f32_16x16x32_bf16 v[66:69], v[170:173], v[226:229], v[66:69]
	v_mfma_f32_16x16x32_bf16 v[114:117], v[166:169], v[198:201], v[114:117]
	v_mfma_f32_16x16x32_bf16 v[106:109], v[190:193], v[198:201], v[106:109]
	v_mfma_f32_16x16x32_bf16 v[98:101], v[166:169], v[206:209], v[98:101]
	v_mfma_f32_16x16x32_bf16 v[90:93], v[190:193], v[206:209], v[90:93]
	v_mfma_f32_16x16x32_bf16 v[82:85], v[166:169], v[222:225], v[82:85]
	v_mfma_f32_16x16x32_bf16 v[74:77], v[190:193], v[222:225], v[74:77]
	v_mfma_f32_16x16x32_bf16 v[70:73], v[166:169], v[230:233], v[70:73]
	v_mfma_f32_16x16x32_bf16 v[66:69], v[190:193], v[230:233], v[66:69]
	s_barrier
; #define PG8_STAGE(bufoff, gbase, voff) do { _Pragma("unroll") for (int _i = 0; _i < 2; ++_i) \
;         __builtin_amdgcn_global_load_lds((const unsigned*)((const char*)(gbase) + (voff)[_i]), (LAS unsigned*)(lds + (bufoff) + ldsw + _i * 8192), 16, 0, 0); } while (0)
; #define PG8_LDA(dst, b, h) do { _Pragma("unroll") for (int m = 0; m < 4; ++m) _Pragma("unroll") for (int k = 0; k < 2; ++k) dst[m][k] = *(const LAS bf16x8*)(lds + PG8_SA(b, h) + aoff + m * 2048 + k * 1024); } while (0)
; #define PG8_LDB(dst, b, h) do { _Pragma("unroll") for (int n = 0; n < 2; ++n) _Pragma("unroll") for (int k = 0; k < 2; ++k) dst[n][k] = *(const LAS bf16x8*)(lds + PG8_SB(b, h) + boff + n * 2048 + k * 1024); } while (0)
; #define PG8_MMA(ai, bj, At, Bt) do { __builtin_amdgcn_s_setprio(1); _Pragma("unroll") for (int m = 0; m < 4; ++m) _Pragma("unroll") for (int n = 0; n < 2; ++n) _Pragma("unroll") for (int k = 0; k < 2; ++k) \
;         acc[ai][bj][m][n] = __builtin_amdgcn_mfma_f32_16x16x32_bf16(Bt[n][k], At[m][k], acc[ai][bj][m][n], 0, 0, 0); __builtin_amdgcn_s_setprio(0); } while (0)
; #define PG8_WAIT_V(n) asm volatile("s_waitcnt vmcnt(" #n ")" ::: "memory")
; #define PG8_WAIT_L(n) asm volatile("s_waitcnt lgkmcnt(" #n ")" ::: "memory")
; #define PG8_BAR __builtin_amdgcn_s_barrier()
; #define PG8_SCHED __builtin_amdgcn_sched_barrier(0)
; template <class Epi, class Sched>
; __device__ __forceinline__ void gemm_phase(LAS unsigned char* lds, const Gemm g, const Sched& S, const Epi& E) {
;     ...
;             PG8_LDB(B0, 0, 0); PG8_LDB(B1, 0, 1); PG8_SCHED; PG8_LDA(At, 0, 0); PG8_STAGE(PG8_SA(1, 1), a1 + hstepA, voffA);
;             PG8_WAIT_V(8); PG8_WAIT_L(0); PG8_BAR; PG8_MMA(0, 0, At, B0); PG8_MMA(0, 1, At, B1); PG8_BAR; PG8_SCHED;
;     ...
;             PG8_LDA(At, 1, 1); PG8_STAGE(PG8_SB(1, 0), b3, voffB); PG8_STAGE(PG8_SB(1, 1), b3 + hstepB, voffB); PG8_STAGE(PG8_SA(1, 0), a3, voffA);
;             PG8_WAIT_V(8); PG8_WAIT_L(0); PG8_BAR; PG8_MMA(1, 0, At, B0); PG8_MMA(1, 1, At, B1); PG8_BAR; PG8_SCHED;
	s_add_i32 s20, s8, 0x18000
	s_add_u32 s80, s76, 0x80
	s_addc_u32 s81, s77, 0
	s_mov_b32 m0, s20
	s_nop 0
	global_load_lds_dwordx4 v148, s[80:81]
	s_add_i32 m0, s20, 0x2000
	s_add_u32 s20, s76, 0x40080
	s_addc_u32 s21, s77, 0
	s_add_i32 s12, s8, 0x1c000
	global_load_lds_dwordx4 v152, s[80:81]
	s_mov_b32 m0, s12
	s_nop 0
	global_load_lds_dwordx4 v148, s[20:21]
	s_add_i32 m0, s12, 0x2000
	s_nop 0
	global_load_lds_dwordx4 v152, s[20:21]
	s_mov_b32 m0, s31
	s_nop 0
	global_load_lds_dwordx4 v146, s[100:101]
	s_mov_b32 m0, s34
	s_nop 0
	global_load_lds_dwordx4 v150, s[100:101]
	ds_read_b128 v[194:197], v160 offset:49152
	ds_read_b128 v[198:201], v160 offset:50176
	ds_read_b128 v[202:205], v160 offset:51200
	ds_read_b128 v[206:209], v160 offset:52224
	ds_read_b128 v[218:221], v160 offset:53248
	ds_read_b128 v[222:225], v160 offset:54272
	ds_read_b128 v[226:229], v160 offset:55296
	ds_read_b128 v[230:233], v160 offset:56320
	s_waitcnt vmcnt(8)
	s_waitcnt lgkmcnt(0)
	s_barrier
	s_waitcnt lgkmcnt(0)
	v_mfma_f32_16x16x32_bf16 v[62:65], v[130:133], v[194:197], v[62:65]
	v_mfma_f32_16x16x32_bf16 v[58:61], v[138:141], v[194:197], v[58:61]
	v_mfma_f32_16x16x32_bf16 v[54:57], v[130:133], v[202:205], v[54:57]
	v_mfma_f32_16x16x32_bf16 v[46:49], v[138:141], v[202:205], v[46:49]
	v_mfma_f32_16x16x32_bf16 v[38:41], v[130:133], v[218:221], v[38:41]
	v_mfma_f32_16x16x32_bf16 v[30:33], v[138:141], v[218:221], v[30:33]
	v_mfma_f32_16x16x32_bf16 v[22:25], v[130:133], v[226:229], v[22:25]
	v_mfma_f32_16x16x32_bf16 v[14:17], v[138:141], v[226:229], v[14:17]
	v_mfma_f32_16x16x32_bf16 v[62:65], v[134:137], v[198:201], v[62:65]
	v_mfma_f32_16x16x32_bf16 v[58:61], v[142:145], v[198:201], v[58:61]
	v_mfma_f32_16x16x32_bf16 v[54:57], v[134:137], v[206:209], v[54:57]
	v_mfma_f32_16x16x32_bf16 v[46:49], v[142:145], v[206:209], v[46:49]
	v_mfma_f32_16x16x32_bf16 v[38:41], v[134:137], v[222:225], v[38:41]
	v_mfma_f32_16x16x32_bf16 v[30:33], v[142:145], v[222:225], v[30:33]
	v_mfma_f32_16x16x32_bf16 v[22:25], v[134:137], v[230:233], v[22:25]
	v_mfma_f32_16x16x32_bf16 v[14:17], v[142:145], v[230:233], v[14:17]
	v_mfma_f32_16x16x32_bf16 v[50:53], v[162:165], v[194:197], v[50:53]
	v_mfma_f32_16x16x32_bf16 v[42:45], v[170:173], v[194:197], v[42:45]
	v_mfma_f32_16x16x32_bf16 v[34:37], v[162:165], v[202:205], v[34:37]
	v_mfma_f32_16x16x32_bf16 v[26:29], v[170:173], v[202:205], v[26:29]
	v_mfma_f32_16x16x32_bf16 v[18:21], v[162:165], v[218:221], v[18:21]
	v_mfma_f32_16x16x32_bf16 v[10:13], v[170:173], v[218:221], v[10:13]
	v_mfma_f32_16x16x32_bf16 v[6:9], v[162:165], v[226:229], v[6:9]
	v_mfma_f32_16x16x32_bf16 v[2:5], v[170:173], v[226:229], v[2:5]
	v_mfma_f32_16x16x32_bf16 v[50:53], v[166:169], v[198:201], v[50:53]
	v_mfma_f32_16x16x32_bf16 v[42:45], v[190:193], v[198:201], v[42:45]
	v_mfma_f32_16x16x32_bf16 v[34:37], v[166:169], v[206:209], v[34:37]
	v_mfma_f32_16x16x32_bf16 v[26:29], v[190:193], v[206:209], v[26:29]
	v_mfma_f32_16x16x32_bf16 v[18:21], v[166:169], v[222:225], v[18:21]
	v_mfma_f32_16x16x32_bf16 v[10:13], v[190:193], v[222:225], v[10:13]
	v_mfma_f32_16x16x32_bf16 v[6:9], v[166:169], v[230:233], v[6:9]
	v_mfma_f32_16x16x32_bf16 v[2:5], v[190:193], v[230:233], v[2:5]
	s_barrier
	s_add_i32 s78, s78, 2
	s_add_u32 s18, s18, 0x100
	s_addc_u32 s19, s19, 0
	s_add_u32 s69, s69, 0x100
	s_addc_u32 s71, s71, 0
	s_cmp_gt_u32 s78, 13
.LBB0_378:
	s_add_u32 s20, s18, 0xfffc0080
	s_addc_u32 s21, s19, -1
	s_add_i32 s79, 0, 0x10000
	s_cmp_eq_u32 s78, 12
	s_cselect_b32 s21, s43, s21
	s_cselect_b32 s20, s48, s20
	s_cselect_b32 s77, s49, s71
	s_cselect_b32 s76, s53, s69
	s_add_u32 s100, s20, 0x80
	s_addc_u32 s101, s21, 0
	s_add_i32 s82, 0, 0x14000
	s_add_i32 m0, s9, 0xc000
	s_nop 0
	global_load_lds_dwordx4 v146, s[18:19]
	s_add_i32 m0, s9, 0xe000
	s_nop 0
	global_load_lds_dwordx4 v150, s[18:19]
	ds_read_b128 v[130:133], v255
	ds_read_b128 v[134:137], v255 offset:1024
	ds_read_b128 v[138:141], v255 offset:2048
	ds_read_b128 v[142:145], v255 offset:3072
	ds_read_b128 v[162:165], v255 offset:16384
	ds_read_b128 v[166:169], v255 offset:17408
	ds_read_b128 v[170:173], v255 offset:18432
	ds_read_b128 v[190:193], v255 offset:19456
	ds_read_b128 v[194:197], v160
	ds_read_b128 v[198:201], v160 offset:1024
	ds_read_b128 v[202:205], v160 offset:2048
	ds_read_b128 v[206:209], v160 offset:3072
	ds_read_b128 v[218:221], v160 offset:4096
	ds_read_b128 v[222:225], v160 offset:5120
	ds_read_b128 v[226:229], v160 offset:6144
	ds_read_b128 v[230:233], v160 offset:7168
	s_waitcnt vmcnt(8)
	s_waitcnt lgkmcnt(0)
	s_barrier
; #define PG8_STAGE(bufoff, gbase, voff) do { _Pragma("unroll") for (int _i = 0; _i < 2; ++_i) \
;         __builtin_amdgcn_global_load_lds((const unsigned*)((const char*)(gbase) + (voff)[_i]), (LAS unsigned*)(lds + (bufoff) + ldsw + _i * 8192), 16, 0, 0); } while (0)
; #define PG8_LDA(dst, b, h) do { _Pragma("unroll") for (int m = 0; m < 4; ++m) _Pragma("unroll") for (int k = 0; k < 2; ++k) dst[m][k] = *(const LAS bf16x8*)(lds + PG8_SA(b, h) + aoff + m * 2048 + k * 1024); } while (0)
; #define PG8_MMA(ai, bj, At, Bt) do { __builtin_amdgcn_s_setprio(1); _Pragma("unroll") for (int m = 0; m < 4; ++m) _Pragma("unroll") for (int n = 0; n < 2; ++n) _Pragma("unroll") for (int k = 0; k < 2; ++k) \
;         acc[ai][bj][m][n] = __builtin_amdgcn_mfma_f32_16x16x32_bf16(Bt[n][k], At[m][k], acc[ai][bj][m][n], 0, 0, 0); __builtin_amdgcn_s_setprio(0); } while (0)
; #define PG8_WAIT_V(n) asm volatile("s_waitcnt vmcnt(" #n ")" ::: "memory")
; #define PG8_WAIT_L(n) asm volatile("s_waitcnt lgkmcnt(" #n ")" ::: "memory")
; #define PG8_BAR __builtin_amdgcn_s_barrier()
; #define PG8_SCHED __builtin_amdgcn_sched_barrier(0)
; template <class Epi, class Sched>
; __device__ __forceinline__ void gemm_phase(LAS unsigned char* lds, const Gemm g, const Sched& S, const Epi& E) {
;     ...
;             PG8_WAIT_V(8); PG8_WAIT_L(0); PG8_BAR; PG8_MMA(0, 0, At, B0); PG8_MMA(0, 1, At, B1); PG8_BAR; PG8_SCHED;
;             PG8_LDA(At, 0, 1); PG8_STAGE(PG8_SB(0, 0), b2, voffB); PG8_STAGE(PG8_SB(0, 1), b2 + hstepB, voffB); PG8_STAGE(PG8_SA(0, 0), a2, voffA);
;             PG8_WAIT_V(8); PG8_WAIT_L(0); PG8_BAR; PG8_MMA(1, 0, At, B0); PG8_MMA(1, 1, At, B1); PG8_BAR; PG8_SCHED;
	s_waitcnt lgkmcnt(0)
	v_mfma_f32_16x16x32_bf16 v[126:129], v[130:133], v[194:197], v[126:129]
	v_mfma_f32_16x16x32_bf16 v[122:125], v[138:141], v[194:197], v[122:125]
	v_mfma_f32_16x16x32_bf16 v[118:121], v[130:133], v[202:205], v[118:121]
	v_mfma_f32_16x16x32_bf16 v[110:113], v[138:141], v[202:205], v[110:113]
	v_mfma_f32_16x16x32_bf16 v[102:105], v[130:133], v[218:221], v[102:105]
	v_mfma_f32_16x16x32_bf16 v[94:97], v[138:141], v[218:221], v[94:97]
	v_mfma_f32_16x16x32_bf16 v[86:89], v[130:133], v[226:229], v[86:89]
	v_mfma_f32_16x16x32_bf16 v[78:81], v[138:141], v[226:229], v[78:81]
	v_mfma_f32_16x16x32_bf16 v[126:129], v[134:137], v[198:201], v[126:129]
	v_mfma_f32_16x16x32_bf16 v[122:125], v[142:145], v[198:201], v[122:125]
	v_mfma_f32_16x16x32_bf16 v[118:121], v[134:137], v[206:209], v[118:121]
	v_mfma_f32_16x16x32_bf16 v[110:113], v[142:145], v[206:209], v[110:113]
	v_mfma_f32_16x16x32_bf16 v[102:105], v[134:137], v[222:225], v[102:105]
	v_mfma_f32_16x16x32_bf16 v[94:97], v[142:145], v[222:225], v[94:97]
	v_mfma_f32_16x16x32_bf16 v[86:89], v[134:137], v[230:233], v[86:89]
	v_mfma_f32_16x16x32_bf16 v[78:81], v[142:145], v[230:233], v[78:81]
	v_mfma_f32_16x16x32_bf16 v[114:117], v[162:165], v[194:197], v[114:117]
	v_mfma_f32_16x16x32_bf16 v[106:109], v[170:173], v[194:197], v[106:109]
	v_mfma_f32_16x16x32_bf16 v[98:101], v[162:165], v[202:205], v[98:101]
	v_mfma_f32_16x16x32_bf16 v[90:93], v[170:173], v[202:205], v[90:93]
	v_mfma_f32_16x16x32_bf16 v[82:85], v[162:165], v[218:221], v[82:85]
	v_mfma_f32_16x16x32_bf16 v[74:77], v[170:173], v[218:221], v[74:77]
	v_mfma_f32_16x16x32_bf16 v[70:73], v[162:165], v[226:229], v[70:73]
	v_mfma_f32_16x16x32_bf16 v[66:69], v[170:173], v[226:229], v[66:69]
	v_mfma_f32_16x16x32_bf16 v[114:117], v[166:169], v[198:201], v[114:117]
	v_mfma_f32_16x16x32_bf16 v[106:109], v[190:193], v[198:201], v[106:109]
	v_mfma_f32_16x16x32_bf16 v[98:101], v[166:169], v[206:209], v[98:101]
	v_mfma_f32_16x16x32_bf16 v[90:93], v[190:193], v[206:209], v[90:93]
	v_mfma_f32_16x16x32_bf16 v[82:85], v[166:169], v[222:225], v[82:85]
	v_mfma_f32_16x16x32_bf16 v[74:77], v[190:193], v[222:225], v[74:77]
	v_mfma_f32_16x16x32_bf16 v[70:73], v[166:169], v[230:233], v[70:73]
	v_mfma_f32_16x16x32_bf16 v[66:69], v[190:193], v[230:233], v[66:69]
	s_barrier
	s_add_i32 s79, s79, s8
	s_mov_b32 m0, s79
	s_nop 0
	global_load_lds_dwordx4 v148, s[76:77]
	s_add_i32 m0, s79, 0x2000
	s_add_u32 s80, s76, 0x40000
	s_addc_u32 s81, s77, 0
	s_add_i32 s79, s82, s8
	global_load_lds_dwordx4 v152, s[76:77]
	s_mov_b32 m0, s79
	s_nop 0
	global_load_lds_dwordx4 v148, s[80:81]
	s_add_i32 m0, s79, 0x2000
	s_nop 0
	global_load_lds_dwordx4 v152, s[80:81]
	s_mov_b32 m0, s9
	s_nop 0
	global_load_lds_dwordx4 v146, s[20:21]
	s_mov_b32 m0, s28
	s_nop 0
	global_load_lds_dwordx4 v150, s[20:21]
	ds_read_b128 v[194:197], v160 offset:16384
	ds_read_b128 v[198:201], v160 offset:17408
	ds_read_b128 v[202:205], v160 offset:18432
	ds_read_b128 v[206:209], v160 offset:19456
	ds_read_b128 v[218:221], v160 offset:20480
	ds_read_b128 v[222:225], v160 offset:21504
	ds_read_b128 v[226:229], v160 offset:22528
	ds_read_b128 v[230:233], v160 offset:23552
	s_waitcnt vmcnt(8)
	s_waitcnt lgkmcnt(0)
	s_nop 0
	s_barrier
	s_waitcnt lgkmcnt(0)
	v_mfma_f32_16x16x32_bf16 v[62:65], v[130:133], v[194:197], v[62:65]
	v_mfma_f32_16x16x32_bf16 v[58:61], v[138:141], v[194:197], v[58:61]
	v_mfma_f32_16x16x32_bf16 v[54:57], v[130:133], v[202:205], v[54:57]
	v_mfma_f32_16x16x32_bf16 v[46:49], v[138:141], v[202:205], v[46:49]
	v_mfma_f32_16x16x32_bf16 v[38:41], v[130:133], v[218:221], v[38:41]
	v_mfma_f32_16x16x32_bf16 v[30:33], v[138:141], v[218:221], v[30:33]
	v_mfma_f32_16x16x32_bf16 v[22:25], v[130:133], v[226:229], v[22:25]
	v_mfma_f32_16x16x32_bf16 v[14:17], v[138:141], v[226:229], v[14:17]
	v_mfma_f32_16x16x32_bf16 v[62:65], v[134:137], v[198:201], v[62:65]
	v_mfma_f32_16x16x32_bf16 v[58:61], v[142:145], v[198:201], v[58:61]
	v_mfma_f32_16x16x32_bf16 v[54:57], v[134:137], v[206:209], v[54:57]
	v_mfma_f32_16x16x32_bf16 v[46:49], v[142:145], v[206:209], v[46:49]
	v_mfma_f32_16x16x32_bf16 v[38:41], v[134:137], v[222:225], v[38:41]
	v_mfma_f32_16x16x32_bf16 v[30:33], v[142:145], v[222:225], v[30:33]
	v_mfma_f32_16x16x32_bf16 v[22:25], v[134:137], v[230:233], v[22:25]
	v_mfma_f32_16x16x32_bf16 v[14:17], v[142:145], v[230:233], v[14:17]
	v_mfma_f32_16x16x32_bf16 v[50:53], v[162:165], v[194:197], v[50:53]
	v_mfma_f32_16x16x32_bf16 v[42:45], v[170:173], v[194:197], v[42:45]
	v_mfma_f32_16x16x32_bf16 v[34:37], v[162:165], v[202:205], v[34:37]
	v_mfma_f32_16x16x32_bf16 v[26:29], v[170:173], v[202:205], v[26:29]
	v_mfma_f32_16x16x32_bf16 v[18:21], v[162:165], v[218:221], v[18:21]
	v_mfma_f32_16x16x32_bf16 v[10:13], v[170:173], v[218:221], v[10:13]
	v_mfma_f32_16x16x32_bf16 v[6:9], v[162:165], v[226:229], v[6:9]
	v_mfma_f32_16x16x32_bf16 v[2:5], v[170:173], v[226:229], v[2:5]
	v_mfma_f32_16x16x32_bf16 v[50:53], v[166:169], v[198:201], v[50:53]
	v_mfma_f32_16x16x32_bf16 v[42:45], v[190:193], v[198:201], v[42:45]
	v_mfma_f32_16x16x32_bf16 v[34:37], v[166:169], v[206:209], v[34:37]
	v_mfma_f32_16x16x32_bf16 v[26:29], v[190:193], v[206:209], v[26:29]
	v_mfma_f32_16x16x32_bf16 v[18:21], v[166:169], v[222:225], v[18:21]
	v_mfma_f32_16x16x32_bf16 v[10:13], v[190:193], v[222:225], v[10:13]
	v_mfma_f32_16x16x32_bf16 v[6:9], v[166:169], v[230:233], v[6:9]
	v_mfma_f32_16x16x32_bf16 v[2:5], v[190:193], v[230:233], v[2:5]
	s_barrier
; #define PG8_STAGE(bufoff, gbase, voff) do { _Pragma("unroll") for (int _i = 0; _i < 2; ++_i) \
;         __builtin_amdgcn_global_load_lds((const unsigned*)((const char*)(gbase) + (voff)[_i]), (LAS unsigned*)(lds + (bufoff) + ldsw + _i * 8192), 16, 0, 0); } while (0)
; #define PG8_LDA(dst, b, h) do { _Pragma("unroll") for (int m = 0; m < 4; ++m) _Pragma("unroll") for (int k = 0; k < 2; ++k) dst[m][k] = *(const LAS bf16x8*)(lds + PG8_SA(b, h) + aoff + m * 2048 + k * 1024); } while (0)
; #define PG8_LDB(dst, b, h) do { _Pragma("unroll") for (int n = 0; n < 2; ++n) _Pragma("unroll") for (int k = 0; k < 2; ++k) dst[n][k] = *(const LAS bf16x8*)(lds + PG8_SB(b, h) + boff + n * 2048 + k * 1024); } while (0)
; #define PG8_MMA(ai, bj, At, Bt) do { __builtin_amdgcn_s_setprio(1); _Pragma("unroll") for (int m = 0; m < 4; ++m) _Pragma("unroll") for (int n = 0; n < 2; ++n) _Pragma("unroll") for (int k = 0; k < 2; ++k) \
;         acc[ai][bj][m][n] = __builtin_amdgcn_mfma_f32_16x16x32_bf16(Bt[n][k], At[m][k], acc[ai][bj][m][n], 0, 0, 0); __builtin_amdgcn_s_setprio(0); } while (0)
; #define PG8_WAIT_V(n) asm volatile("s_waitcnt vmcnt(" #n ")" ::: "memory")
; #define PG8_WAIT_L(n) asm volatile("s_waitcnt lgkmcnt(" #n ")" ::: "memory")
; #define PG8_BAR __builtin_amdgcn_s_barrier()
; #define PG8_SCHED __builtin_amdgcn_sched_barrier(0)
; template <class Epi, class Sched>
; __device__ __forceinline__ void gemm_phase(LAS unsigned char* lds, const Gemm g, const Sched& S, const Epi& E) {
;     ...
;             PG8_LDB(B0, 1, 0); PG8_LDB(B1, 1, 1); PG8_SCHED; PG8_LDA(At, 1, 0); PG8_STAGE(PG8_SA(0, 1), a2 + hstepA, voffA);
;             PG8_WAIT_V(8); PG8_WAIT_L(0); PG8_BAR; PG8_MMA(0, 0, At, B0); PG8_MMA(0, 1, At, B1); PG8_BAR; PG8_SCHED;
;             PG8_LDA(At, 1, 1); PG8_STAGE(PG8_SB(1, 0), b3, voffB); PG8_STAGE(PG8_SB(1, 1), b3 + hstepB, voffB); PG8_STAGE(PG8_SA(1, 0), a3, voffA);
;             PG8_WAIT_V(8); PG8_WAIT_L(0); PG8_BAR; PG8_MMA(1, 0, At, B0); PG8_MMA(1, 1, At, B1); PG8_BAR; PG8_SCHED;
;         }
;         if (wr == 0) PG8_BAR;
	s_add_i32 s79, 0, 0x18000
	s_add_i32 s80, 0, 0x1c000
	s_add_u32 s20, s20, 0x40000
	s_addc_u32 s21, s21, 0
	s_mov_b32 m0, s29
	s_nop 0
	global_load_lds_dwordx4 v146, s[20:21]
	s_mov_b32 m0, s30
	s_nop 0
	global_load_lds_dwordx4 v150, s[20:21]
	ds_read_b128 v[130:133], v255 offset:32768
	ds_read_b128 v[134:137], v255 offset:33792
	ds_read_b128 v[138:141], v255 offset:34816
	ds_read_b128 v[142:145], v255 offset:35840
	ds_read_b128 v[162:165], v255 offset:49152
	ds_read_b128 v[166:169], v255 offset:50176
	ds_read_b128 v[170:173], v255 offset:51200
	ds_read_b128 v[190:193], v255 offset:52224
	ds_read_b128 v[194:197], v160 offset:32768
	ds_read_b128 v[198:201], v160 offset:33792
	ds_read_b128 v[202:205], v160 offset:34816
	ds_read_b128 v[206:209], v160 offset:35840
	ds_read_b128 v[218:221], v160 offset:36864
	ds_read_b128 v[222:225], v160 offset:37888
	ds_read_b128 v[226:229], v160 offset:38912
	ds_read_b128 v[230:233], v160 offset:39936
	s_waitcnt vmcnt(8)
	s_waitcnt lgkmcnt(0)
	s_barrier
	s_waitcnt lgkmcnt(0)
	v_mfma_f32_16x16x32_bf16 v[126:129], v[130:133], v[194:197], v[126:129]
	v_mfma_f32_16x16x32_bf16 v[122:125], v[138:141], v[194:197], v[122:125]
	v_mfma_f32_16x16x32_bf16 v[118:121], v[130:133], v[202:205], v[118:121]
	v_mfma_f32_16x16x32_bf16 v[110:113], v[138:141], v[202:205], v[110:113]
	v_mfma_f32_16x16x32_bf16 v[102:105], v[130:133], v[218:221], v[102:105]
	v_mfma_f32_16x16x32_bf16 v[94:97], v[138:141], v[218:221], v[94:97]
	v_mfma_f32_16x16x32_bf16 v[86:89], v[130:133], v[226:229], v[86:89]
	v_mfma_f32_16x16x32_bf16 v[78:81], v[138:141], v[226:229], v[78:81]
	v_mfma_f32_16x16x32_bf16 v[126:129], v[134:137], v[198:201], v[126:129]
	v_mfma_f32_16x16x32_bf16 v[122:125], v[142:145], v[198:201], v[122:125]
	v_mfma_f32_16x16x32_bf16 v[118:121], v[134:137], v[206:209], v[118:121]
	v_mfma_f32_16x16x32_bf16 v[110:113], v[142:145], v[206:209], v[110:113]
	v_mfma_f32_16x16x32_bf16 v[102:105], v[134:137], v[222:225], v[102:105]
	v_mfma_f32_16x16x32_bf16 v[94:97], v[142:145], v[222:225], v[94:97]
	v_mfma_f32_16x16x32_bf16 v[86:89], v[134:137], v[230:233], v[86:89]
	v_mfma_f32_16x16x32_bf16 v[78:81], v[142:145], v[230:233], v[78:81]
	v_mfma_f32_16x16x32_bf16 v[114:117], v[162:165], v[194:197], v[114:117]
	v_mfma_f32_16x16x32_bf16 v[106:109], v[170:173], v[194:197], v[106:109]
	v_mfma_f32_16x16x32_bf16 v[98:101], v[162:165], v[202:205], v[98:101]
	v_mfma_f32_16x16x32_bf16 v[90:93], v[170:173], v[202:205], v[90:93]
	v_mfma_f32_16x16x32_bf16 v[82:85], v[162:165], v[218:221], v[82:85]
	v_mfma_f32_16x16x32_bf16 v[74:77], v[170:173], v[218:221], v[74:77]
	v_mfma_f32_16x16x32_bf16 v[70:73], v[162:165], v[226:229], v[70:73]
	v_mfma_f32_16x16x32_bf16 v[66:69], v[170:173], v[226:229], v[66:69]
	v_mfma_f32_16x16x32_bf16 v[114:117], v[166:169], v[198:201], v[114:117]
	v_mfma_f32_16x16x32_bf16 v[106:109], v[190:193], v[198:201], v[106:109]
	v_mfma_f32_16x16x32_bf16 v[98:101], v[166:169], v[206:209], v[98:101]
	v_mfma_f32_16x16x32_bf16 v[90:93], v[190:193], v[206:209], v[90:93]
	v_mfma_f32_16x16x32_bf16 v[82:85], v[166:169], v[222:225], v[82:85]
	v_mfma_f32_16x16x32_bf16 v[74:77], v[190:193], v[222:225], v[74:77]
	v_mfma_f32_16x16x32_bf16 v[70:73], v[166:169], v[230:233], v[70:73]
	v_mfma_f32_16x16x32_bf16 v[66:69], v[190:193], v[230:233], v[66:69]
	s_barrier
	s_add_i32 s20, s8, 0x18000
	s_add_u32 s80, s76, 0x80
	s_addc_u32 s81, s77, 0
	s_mov_b32 m0, s20
	s_nop 0
	global_load_lds_dwordx4 v148, s[80:81]
	s_add_i32 m0, s20, 0x2000
	s_add_u32 s20, s76, 0x40080
	s_addc_u32 s21, s77, 0
	s_add_i32 s12, s8, 0x1c000
	global_load_lds_dwordx4 v152, s[80:81]
	s_mov_b32 m0, s12
	s_nop 0
	global_load_lds_dwordx4 v148, s[20:21]
	s_add_i32 m0, s12, 0x2000
	s_nop 0
	global_load_lds_dwordx4 v152, s[20:21]
	s_mov_b32 m0, s31
	s_nop 0
	global_load_lds_dwordx4 v146, s[100:101]
	s_mov_b32 m0, s34
	s_nop 0
	global_load_lds_dwordx4 v150, s[100:101]
	ds_read_b128 v[194:197], v160 offset:49152
	ds_read_b128 v[198:201], v160 offset:50176
	ds_read_b128 v[202:205], v160 offset:51200
	ds_read_b128 v[206:209], v160 offset:52224
	ds_read_b128 v[218:221], v160 offset:53248
	ds_read_b128 v[222:225], v160 offset:54272
	ds_read_b128 v[226:229], v160 offset:55296
	ds_read_b128 v[230:233], v160 offset:56320
	s_waitcnt vmcnt(8)
	s_waitcnt lgkmcnt(0)
	s_barrier
	s_waitcnt lgkmcnt(0)
	v_mfma_f32_16x16x32_bf16 v[62:65], v[130:133], v[194:197], v[62:65]
	v_mfma_f32_16x16x32_bf16 v[58:61], v[138:141], v[194:197], v[58:61]
	v_mfma_f32_16x16x32_bf16 v[54:57], v[130:133], v[202:205], v[54:57]
	v_mfma_f32_16x16x32_bf16 v[46:49], v[138:141], v[202:205], v[46:49]
	v_mfma_f32_16x16x32_bf16 v[38:41], v[130:133], v[218:221], v[38:41]
	v_mfma_f32_16x16x32_bf16 v[30:33], v[138:141], v[218:221], v[30:33]
	v_mfma_f32_16x16x32_bf16 v[22:25], v[130:133], v[226:229], v[22:25]
	v_mfma_f32_16x16x32_bf16 v[14:17], v[138:141], v[226:229], v[14:17]
	v_mfma_f32_16x16x32_bf16 v[62:65], v[134:137], v[198:201], v[62:65]
	v_mfma_f32_16x16x32_bf16 v[58:61], v[142:145], v[198:201], v[58:61]
	v_mfma_f32_16x16x32_bf16 v[54:57], v[134:137], v[206:209], v[54:57]
	v_mfma_f32_16x16x32_bf16 v[46:49], v[142:145], v[206:209], v[46:49]
	v_mfma_f32_16x16x32_bf16 v[38:41], v[134:137], v[222:225], v[38:41]
	v_mfma_f32_16x16x32_bf16 v[30:33], v[142:145], v[222:225], v[30:33]
	v_mfma_f32_16x16x32_bf16 v[22:25], v[134:137], v[230:233], v[22:25]
	v_mfma_f32_16x16x32_bf16 v[14:17], v[142:145], v[230:233], v[14:17]
	v_mfma_f32_16x16x32_bf16 v[50:53], v[162:165], v[194:197], v[50:53]
	v_mfma_f32_16x16x32_bf16 v[42:45], v[170:173], v[194:197], v[42:45]
	v_mfma_f32_16x16x32_bf16 v[34:37], v[162:165], v[202:205], v[34:37]
	v_mfma_f32_16x16x32_bf16 v[26:29], v[170:173], v[202:205], v[26:29]
	v_mfma_f32_16x16x32_bf16 v[18:21], v[162:165], v[218:221], v[18:21]
	v_mfma_f32_16x16x32_bf16 v[10:13], v[170:173], v[218:221], v[10:13]
	v_mfma_f32_16x16x32_bf16 v[6:9], v[162:165], v[226:229], v[6:9]
	v_mfma_f32_16x16x32_bf16 v[2:5], v[170:173], v[226:229], v[2:5]
	v_mfma_f32_16x16x32_bf16 v[50:53], v[166:169], v[198:201], v[50:53]
	v_mfma_f32_16x16x32_bf16 v[42:45], v[190:193], v[198:201], v[42:45]
	v_mfma_f32_16x16x32_bf16 v[34:37], v[166:169], v[206:209], v[34:37]
	v_mfma_f32_16x16x32_bf16 v[26:29], v[190:193], v[206:209], v[26:29]
	v_mfma_f32_16x16x32_bf16 v[18:21], v[166:169], v[222:225], v[18:21]
	v_mfma_f32_16x16x32_bf16 v[10:13], v[190:193], v[222:225], v[10:13]
	v_mfma_f32_16x16x32_bf16 v[6:9], v[166:169], v[230:233], v[6:9]
	v_mfma_f32_16x16x32_bf16 v[2:5], v[190:193], v[230:233], v[2:5]
	s_barrier
	s_add_i32 s78, s78, 2
	s_add_u32 s18, s18, 0x100
	s_addc_u32 s19, s19, 0
	s_add_u32 s69, s69, 0x100
	s_addc_u32 s71, s71, 0
	s_cmp_gt_u32 s78, 13
	s_cbranch_scc0 .LBB0_378
	s_and_b64 vcc, exec, s[36:37]
	s_cbranch_vccz .LBB0_381
	s_barrier

; #define PG8_STAGE(bufoff, gbase, voff) do { _Pragma("unroll") for (int _i = 0; _i < 2; ++_i) \
;         __builtin_amdgcn_global_load_lds((const unsigned*)((const char*)(gbase) + (voff)[_i]), (LAS unsigned*)(lds + (bufoff) + ldsw + _i * 8192), 16, 0, 0); } while (0)
; #define PG8_LDA(dst, b, h) do { _Pragma("unroll") for (int m = 0; m < 4; ++m) _Pragma("unroll") for (int k = 0; k < 2; ++k) dst[m][k] = *(const LAS bf16x8*)(lds + PG8_SA(b, h) + aoff + m * 2048 + k * 1024); } while (0)
; #define PG8_LDB(dst, b, h) do { _Pragma("unroll") for (int n = 0; n < 2; ++n) _Pragma("unroll") for (int k = 0; k < 2; ++k) dst[n][k] = *(const LAS bf16x8*)(lds + PG8_SB(b, h) + boff + n * 2048 + k * 1024); } while (0)
; #define PG8_MMA(ai, bj, At, Bt) do { __builtin_amdgcn_s_setprio(1); _Pragma("unroll") for (int m = 0; m < 4; ++m) _Pragma("unroll") for (int n = 0; n < 2; ++n) _Pragma("unroll") for (int k = 0; k < 2; ++k) \
;         acc[ai][bj][m][n] = __builtin_amdgcn_mfma_f32_16x16x32_bf16(Bt[n][k], At[m][k], acc[ai][bj][m][n], 0, 0, 0); __builtin_amdgcn_s_setprio(0); } while (0)
; #define PG8_WAIT_V(n) asm volatile("s_waitcnt vmcnt(" #n ")" ::: "memory")
; #define PG8_WAIT_L(n) asm volatile("s_waitcnt lgkmcnt(" #n ")" ::: "memory")
; #define PG8_BAR __builtin_amdgcn_s_barrier()
; #define PG8_SCHED __builtin_amdgcn_sched_barrier(0)
; template <class Epi, class Sched>
; __device__ __forceinline__ void gemm_phase(LAS unsigned char* lds, const Gemm g, const Sched& S, const Epi& E) {
;     ...
;             const bool last = (t == nt - 2);
;             const char* a1 = cA + (size_t)(t + 1) * kstep;
;             const char* a2 = last ? nA : cA + (size_t)(t + 2) * kstep; const char* b2 = last ? nB : cB + (size_t)(t + 2) * kstep;
;             const char* a3 = a2 + kstep; const char* b3 = b2 + kstep;
;             PG8_LDB(B0, 0, 0); PG8_LDB(B1, 0, 1); PG8_SCHED; PG8_LDA(At, 0, 0); PG8_STAGE(PG8_SA(1, 1), a1 + hstepA, voffA);
;             PG8_WAIT_V(8); PG8_WAIT_L(0); PG8_BAR; PG8_MMA(0, 0, At, B0); PG8_MMA(0, 1, At, B1); PG8_BAR; PG8_SCHED;
;             PG8_LDA(At, 0, 1); PG8_STAGE(PG8_SB(0, 0), b2, voffB); PG8_STAGE(PG8_SB(0, 1), b2 + hstepB, voffB); PG8_STAGE(PG8_SA(0, 0), a2, voffA);
;             PG8_WAIT_V(8); PG8_WAIT_L(0); PG8_BAR; PG8_MMA(1, 0, At, B0); PG8_MMA(1, 1, At, B1); PG8_BAR; PG8_SCHED;
.LBB0_598:
	s_add_i32 vcc_lo, s20, 2
	s_add_u32 s90, s18, 0x80
	s_addc_u32 s21, s19, 0
	s_add_i32 s92, 0, 0x10000
	s_cmp_eq_u32 s43, s20
	s_cselect_b32 s21, s37, s21
	s_cselect_b32 s20, s36, s90
	s_cselect_b32 s91, s71, s87
	s_cselect_b32 s90, s70, s86
	s_add_i32 s93, 0, 0x14000
	s_add_i32 m0, s35, 0xc000
	s_nop 0
	global_load_lds_dwordx4 v138, s[18:19]
	s_add_i32 m0, s35, 0xe000
	s_nop 0
	global_load_lds_dwordx4 v140, s[18:19]
	ds_read_b128 v[142:145], v255
	ds_read_b128 v[150:153], v255 offset:1024
	ds_read_b128 v[154:157], v255 offset:2048
	ds_read_b128 v[158:161], v255 offset:3072
	ds_read_b128 v[162:165], v255 offset:16384
	ds_read_b128 v[166:169], v255 offset:17408
	ds_read_b128 v[170:173], v255 offset:18432
	ds_read_b128 v[190:193], v255 offset:19456
	ds_read_b128 v[194:197], v148
	ds_read_b128 v[198:201], v148 offset:1024
	ds_read_b128 v[202:205], v148 offset:2048
	ds_read_b128 v[206:209], v148 offset:3072
	ds_read_b128 v[218:221], v148 offset:4096
	ds_read_b128 v[222:225], v148 offset:5120
	ds_read_b128 v[226:229], v148 offset:6144
	ds_read_b128 v[230:233], v148 offset:7168
	s_waitcnt vmcnt(8)
	s_waitcnt lgkmcnt(0)
	s_barrier
	s_waitcnt lgkmcnt(0)
	v_mfma_f32_16x16x32_bf16 v[114:117], v[142:145], v[194:197], v[114:117]
	v_mfma_f32_16x16x32_bf16 v[118:121], v[154:157], v[194:197], v[118:121]
	v_mfma_f32_16x16x32_bf16 v[94:97], v[142:145], v[202:205], v[94:97]
	v_mfma_f32_16x16x32_bf16 v[98:101], v[154:157], v[202:205], v[98:101]
	v_mfma_f32_16x16x32_bf16 v[62:65], v[142:145], v[218:221], v[62:65]
	v_mfma_f32_16x16x32_bf16 v[66:69], v[154:157], v[218:221], v[66:69]
	v_mfma_f32_16x16x32_bf16 v[22:25], v[142:145], v[226:229], v[22:25]
	v_mfma_f32_16x16x32_bf16 v[34:37], v[154:157], v[226:229], v[34:37]
	v_mfma_f32_16x16x32_bf16 v[114:117], v[150:153], v[198:201], v[114:117]
	v_mfma_f32_16x16x32_bf16 v[118:121], v[158:161], v[198:201], v[118:121]
	v_mfma_f32_16x16x32_bf16 v[94:97], v[150:153], v[206:209], v[94:97]
	v_mfma_f32_16x16x32_bf16 v[98:101], v[158:161], v[206:209], v[98:101]
	v_mfma_f32_16x16x32_bf16 v[62:65], v[150:153], v[222:225], v[62:65]
	v_mfma_f32_16x16x32_bf16 v[66:69], v[158:161], v[222:225], v[66:69]
	v_mfma_f32_16x16x32_bf16 v[22:25], v[150:153], v[230:233], v[22:25]
	v_mfma_f32_16x16x32_bf16 v[34:37], v[158:161], v[230:233], v[34:37]
	v_mfma_f32_16x16x32_bf16 v[122:125], v[162:165], v[194:197], v[122:125]
	v_mfma_f32_16x16x32_bf16 v[126:129], v[170:173], v[194:197], v[126:129]
	v_mfma_f32_16x16x32_bf16 v[102:105], v[162:165], v[202:205], v[102:105]
	v_mfma_f32_16x16x32_bf16 v[106:109], v[170:173], v[202:205], v[106:109]
	v_mfma_f32_16x16x32_bf16 v[70:73], v[162:165], v[218:221], v[70:73]
	v_mfma_f32_16x16x32_bf16 v[78:81], v[170:173], v[218:221], v[78:81]
	v_mfma_f32_16x16x32_bf16 v[38:41], v[162:165], v[226:229], v[38:41]
	v_mfma_f32_16x16x32_bf16 v[46:49], v[170:173], v[226:229], v[46:49]
	v_mfma_f32_16x16x32_bf16 v[122:125], v[166:169], v[198:201], v[122:125]
	v_mfma_f32_16x16x32_bf16 v[126:129], v[190:193], v[198:201], v[126:129]
	v_mfma_f32_16x16x32_bf16 v[102:105], v[166:169], v[206:209], v[102:105]
	v_mfma_f32_16x16x32_bf16 v[106:109], v[190:193], v[206:209], v[106:109]
	v_mfma_f32_16x16x32_bf16 v[70:73], v[166:169], v[222:225], v[70:73]
	v_mfma_f32_16x16x32_bf16 v[78:81], v[190:193], v[222:225], v[78:81]
	v_mfma_f32_16x16x32_bf16 v[38:41], v[166:169], v[230:233], v[38:41]
	v_mfma_f32_16x16x32_bf16 v[46:49], v[190:193], v[230:233], v[46:49]
	s_barrier
	s_add_i32 s92, s92, s34
	s_add_u32 s98, s90, 0x80
	s_addc_u32 s99, s91, 0
	s_add_u32 s100, s20, 0x80
	s_addc_u32 s101, s21, 0
	s_mov_b32 m0, s92
	s_nop 0
	global_load_lds_dwordx4 v132, s[90:91]
	s_add_i32 m0, s92, 0x2000
	s_add_i32 s92, s93, s34
	global_load_lds_dwordx4 v136, s[90:91]
	s_add_u32 s90, s90, s29
	s_addc_u32 s91, s91, 0
	s_mov_b32 m0, s92
	s_nop 0
	global_load_lds_dwordx4 v132, s[90:91]
	s_add_i32 m0, s92, 0x2000
	s_nop 0
	global_load_lds_dwordx4 v136, s[90:91]
	s_mov_b32 m0, s35
	s_nop 0
	global_load_lds_dwordx4 v130, s[20:21]
	s_mov_b32 m0, s8
	s_nop 0
	global_load_lds_dwordx4 v134, s[20:21]
	ds_read_b128 v[194:197], v148 offset:16384
	ds_read_b128 v[198:201], v148 offset:17408
	ds_read_b128 v[202:205], v148 offset:18432
	ds_read_b128 v[206:209], v148 offset:19456
	ds_read_b128 v[218:221], v148 offset:20480
	ds_read_b128 v[222:225], v148 offset:21504
	ds_read_b128 v[226:229], v148 offset:22528
	ds_read_b128 v[230:233], v148 offset:23552
	s_waitcnt vmcnt(8)
	s_waitcnt lgkmcnt(0)
	s_barrier
	s_waitcnt lgkmcnt(0)
	v_mfma_f32_16x16x32_bf16 v[14:17], v[142:145], v[194:197], v[14:17]
	v_mfma_f32_16x16x32_bf16 v[26:29], v[154:157], v[194:197], v[26:29]
	v_mfma_f32_16x16x32_bf16 v[74:77], v[142:145], v[202:205], v[74:77]
	v_mfma_f32_16x16x32_bf16 v[82:85], v[154:157], v[202:205], v[82:85]
	v_mfma_f32_16x16x32_bf16 v[42:45], v[142:145], v[218:221], v[42:45]
	v_mfma_f32_16x16x32_bf16 v[50:53], v[154:157], v[218:221], v[50:53]
	v_mfma_f32_16x16x32_bf16 v[2:5], v[142:145], v[226:229], v[2:5]
	v_mfma_f32_16x16x32_bf16 v[6:9], v[154:157], v[226:229], v[6:9]
	v_mfma_f32_16x16x32_bf16 v[14:17], v[150:153], v[198:201], v[14:17]
	v_mfma_f32_16x16x32_bf16 v[26:29], v[158:161], v[198:201], v[26:29]
	v_mfma_f32_16x16x32_bf16 v[74:77], v[150:153], v[206:209], v[74:77]
	v_mfma_f32_16x16x32_bf16 v[82:85], v[158:161], v[206:209], v[82:85]
	v_mfma_f32_16x16x32_bf16 v[42:45], v[150:153], v[222:225], v[42:45]
	v_mfma_f32_16x16x32_bf16 v[50:53], v[158:161], v[222:225], v[50:53]
	v_mfma_f32_16x16x32_bf16 v[2:5], v[150:153], v[230:233], v[2:5]
	v_mfma_f32_16x16x32_bf16 v[6:9], v[158:161], v[230:233], v[6:9]
	v_mfma_f32_16x16x32_bf16 v[30:33], v[162:165], v[194:197], v[30:33]
	v_mfma_f32_16x16x32_bf16 v[110:113], v[170:173], v[194:197], v[110:113]
	v_mfma_f32_16x16x32_bf16 v[86:89], v[162:165], v[202:205], v[86:89]
	v_mfma_f32_16x16x32_bf16 v[90:93], v[170:173], v[202:205], v[90:93]
	v_mfma_f32_16x16x32_bf16 v[54:57], v[162:165], v[218:221], v[54:57]
	v_mfma_f32_16x16x32_bf16 v[58:61], v[170:173], v[218:221], v[58:61]
	v_mfma_f32_16x16x32_bf16 v[10:13], v[162:165], v[226:229], v[10:13]
	v_mfma_f32_16x16x32_bf16 v[18:21], v[170:173], v[226:229], v[18:21]
	v_mfma_f32_16x16x32_bf16 v[30:33], v[166:169], v[198:201], v[30:33]
	v_mfma_f32_16x16x32_bf16 v[110:113], v[190:193], v[198:201], v[110:113]
	v_mfma_f32_16x16x32_bf16 v[86:89], v[166:169], v[206:209], v[86:89]
	v_mfma_f32_16x16x32_bf16 v[90:93], v[190:193], v[206:209], v[90:93]
	v_mfma_f32_16x16x32_bf16 v[54:57], v[166:169], v[222:225], v[54:57]
	v_mfma_f32_16x16x32_bf16 v[58:61], v[190:193], v[222:225], v[58:61]
	v_mfma_f32_16x16x32_bf16 v[10:13], v[166:169], v[230:233], v[10:13]
	v_mfma_f32_16x16x32_bf16 v[18:21], v[190:193], v[230:233], v[18:21]
	s_barrier
; #define PG8_STAGE(bufoff, gbase, voff) do { _Pragma("unroll") for (int _i = 0; _i < 2; ++_i) \
;         __builtin_amdgcn_global_load_lds((const unsigned*)((const char*)(gbase) + (voff)[_i]), (LAS unsigned*)(lds + (bufoff) + ldsw + _i * 8192), 16, 0, 0); } while (0)
; #define PG8_LDA(dst, b, h) do { _Pragma("unroll") for (int m = 0; m < 4; ++m) _Pragma("unroll") for (int k = 0; k < 2; ++k) dst[m][k] = *(const LAS bf16x8*)(lds + PG8_SA(b, h) + aoff + m * 2048 + k * 1024); } while (0)
; #define PG8_LDB(dst, b, h) do { _Pragma("unroll") for (int n = 0; n < 2; ++n) _Pragma("unroll") for (int k = 0; k < 2; ++k) dst[n][k] = *(const LAS bf16x8*)(lds + PG8_SB(b, h) + boff + n * 2048 + k * 1024); } while (0)
; #define PG8_MMA(ai, bj, At, Bt) do { __builtin_amdgcn_s_setprio(1); _Pragma("unroll") for (int m = 0; m < 4; ++m) _Pragma("unroll") for (int n = 0; n < 2; ++n) _Pragma("unroll") for (int k = 0; k < 2; ++k) \
;         acc[ai][bj][m][n] = __builtin_amdgcn_mfma_f32_16x16x32_bf16(Bt[n][k], At[m][k], acc[ai][bj][m][n], 0, 0, 0); __builtin_amdgcn_s_setprio(0); } while (0)
; #define PG8_WAIT_V(n) asm volatile("s_waitcnt vmcnt(" #n ")" ::: "memory")
; #define PG8_WAIT_L(n) asm volatile("s_waitcnt lgkmcnt(" #n ")" ::: "memory")
; #define PG8_BAR __builtin_amdgcn_s_barrier()
; #define PG8_SCHED __builtin_amdgcn_sched_barrier(0)
; template <class Epi, class Sched>
; __device__ __forceinline__ void gemm_phase(LAS unsigned char* lds, const Gemm g, const Sched& S, const Epi& E) {
;     ...
;             PG8_LDB(B0, 1, 0); PG8_LDB(B1, 1, 1); PG8_SCHED; PG8_LDA(At, 1, 0); PG8_STAGE(PG8_SA(0, 1), a2 + hstepA, voffA);
;             PG8_WAIT_V(8); PG8_WAIT_L(0); PG8_BAR; PG8_MMA(0, 0, At, B0); PG8_MMA(0, 1, At, B1); PG8_BAR; PG8_SCHED;
;             PG8_LDA(At, 1, 1); PG8_STAGE(PG8_SB(1, 0), b3, voffB); PG8_STAGE(PG8_SB(1, 1), b3 + hstepB, voffB); PG8_STAGE(PG8_SA(1, 0), a3, voffA);
;             PG8_WAIT_V(8); PG8_WAIT_L(0); PG8_BAR; PG8_MMA(1, 0, At, B0); PG8_MMA(1, 1, At, B1); PG8_BAR; PG8_SCHED;
;         }
;         if (wr == 0) PG8_BAR;
	s_add_u32 s20, s20, s80
	s_addc_u32 s21, s21, 0
	s_mov_b32 m0, s9
	s_nop 0
	global_load_lds_dwordx4 v130, s[20:21]
	s_mov_b32 m0, s40
	s_nop 0
	global_load_lds_dwordx4 v134, s[20:21]
	ds_read_b128 v[142:145], v255 offset:32768
	ds_read_b128 v[150:153], v255 offset:33792
	ds_read_b128 v[154:157], v255 offset:34816
	ds_read_b128 v[158:161], v255 offset:35840
	ds_read_b128 v[162:165], v255 offset:49152
	ds_read_b128 v[166:169], v255 offset:50176
	ds_read_b128 v[170:173], v255 offset:51200
	ds_read_b128 v[190:193], v255 offset:52224
	ds_read_b128 v[194:197], v148 offset:32768
	ds_read_b128 v[198:201], v148 offset:33792
	ds_read_b128 v[202:205], v148 offset:34816
	ds_read_b128 v[206:209], v148 offset:35840
	ds_read_b128 v[218:221], v148 offset:36864
	ds_read_b128 v[222:225], v148 offset:37888
	ds_read_b128 v[226:229], v148 offset:38912
	ds_read_b128 v[230:233], v148 offset:39936
	s_waitcnt vmcnt(8)
	s_waitcnt lgkmcnt(0)
	s_nop 0
	s_barrier
	s_waitcnt lgkmcnt(0)
	v_mfma_f32_16x16x32_bf16 v[114:117], v[142:145], v[194:197], v[114:117]
	v_mfma_f32_16x16x32_bf16 v[118:121], v[154:157], v[194:197], v[118:121]
	v_mfma_f32_16x16x32_bf16 v[94:97], v[142:145], v[202:205], v[94:97]
	v_mfma_f32_16x16x32_bf16 v[98:101], v[154:157], v[202:205], v[98:101]
	v_mfma_f32_16x16x32_bf16 v[62:65], v[142:145], v[218:221], v[62:65]
	v_mfma_f32_16x16x32_bf16 v[66:69], v[154:157], v[218:221], v[66:69]
	v_mfma_f32_16x16x32_bf16 v[22:25], v[142:145], v[226:229], v[22:25]
	v_mfma_f32_16x16x32_bf16 v[34:37], v[154:157], v[226:229], v[34:37]
	v_mfma_f32_16x16x32_bf16 v[114:117], v[150:153], v[198:201], v[114:117]
	v_mfma_f32_16x16x32_bf16 v[118:121], v[158:161], v[198:201], v[118:121]
	v_mfma_f32_16x16x32_bf16 v[94:97], v[150:153], v[206:209], v[94:97]
	v_mfma_f32_16x16x32_bf16 v[98:101], v[158:161], v[206:209], v[98:101]
	v_mfma_f32_16x16x32_bf16 v[62:65], v[150:153], v[222:225], v[62:65]
	v_mfma_f32_16x16x32_bf16 v[66:69], v[158:161], v[222:225], v[66:69]
	v_mfma_f32_16x16x32_bf16 v[22:25], v[150:153], v[230:233], v[22:25]
	v_mfma_f32_16x16x32_bf16 v[34:37], v[158:161], v[230:233], v[34:37]
	v_mfma_f32_16x16x32_bf16 v[122:125], v[162:165], v[194:197], v[122:125]
	v_mfma_f32_16x16x32_bf16 v[126:129], v[170:173], v[194:197], v[126:129]
	v_mfma_f32_16x16x32_bf16 v[102:105], v[162:165], v[202:205], v[102:105]
	v_mfma_f32_16x16x32_bf16 v[106:109], v[170:173], v[202:205], v[106:109]
	v_mfma_f32_16x16x32_bf16 v[70:73], v[162:165], v[218:221], v[70:73]
	v_mfma_f32_16x16x32_bf16 v[78:81], v[170:173], v[218:221], v[78:81]
	v_mfma_f32_16x16x32_bf16 v[38:41], v[162:165], v[226:229], v[38:41]
	v_mfma_f32_16x16x32_bf16 v[46:49], v[170:173], v[226:229], v[46:49]
	v_mfma_f32_16x16x32_bf16 v[122:125], v[166:169], v[198:201], v[122:125]
	v_mfma_f32_16x16x32_bf16 v[126:129], v[190:193], v[198:201], v[126:129]
	v_mfma_f32_16x16x32_bf16 v[102:105], v[166:169], v[206:209], v[102:105]
	v_mfma_f32_16x16x32_bf16 v[106:109], v[190:193], v[206:209], v[106:109]
	v_mfma_f32_16x16x32_bf16 v[70:73], v[166:169], v[222:225], v[70:73]
	v_mfma_f32_16x16x32_bf16 v[78:81], v[190:193], v[222:225], v[78:81]
	v_mfma_f32_16x16x32_bf16 v[38:41], v[166:169], v[230:233], v[38:41]
	v_mfma_f32_16x16x32_bf16 v[46:49], v[190:193], v[230:233], v[46:49]
	s_barrier
	s_add_i32 s20, s34, 0x18000
	s_mov_b32 m0, s20
	s_nop 0
	global_load_lds_dwordx4 v132, s[98:99]
	s_add_i32 m0, s20, 0x2000
	s_add_i32 s20, s34, 0x1c000
	global_load_lds_dwordx4 v136, s[98:99]
	s_add_u32 s98, s98, s29
	s_addc_u32 s99, s99, 0
	s_mov_b32 m0, s20
	s_nop 0
	global_load_lds_dwordx4 v132, s[98:99]
	s_add_i32 m0, s20, 0x2000
	s_nop 0
	global_load_lds_dwordx4 v136, s[98:99]
	s_mov_b32 m0, s41
	s_nop 0
	global_load_lds_dwordx4 v130, s[100:101]
	s_mov_b32 m0, s42
	s_nop 0
	global_load_lds_dwordx4 v134, s[100:101]
	ds_read_b128 v[194:197], v148 offset:49152
	ds_read_b128 v[198:201], v148 offset:50176
	ds_read_b128 v[202:205], v148 offset:51200
	ds_read_b128 v[206:209], v148 offset:52224
	ds_read_b128 v[218:221], v148 offset:53248
	ds_read_b128 v[222:225], v148 offset:54272
	ds_read_b128 v[226:229], v148 offset:55296
	ds_read_b128 v[230:233], v148 offset:56320
	s_waitcnt vmcnt(8)
	s_waitcnt lgkmcnt(0)
	s_barrier
	s_waitcnt lgkmcnt(0)
	v_mfma_f32_16x16x32_bf16 v[14:17], v[142:145], v[194:197], v[14:17]
	v_mfma_f32_16x16x32_bf16 v[26:29], v[154:157], v[194:197], v[26:29]
	v_mfma_f32_16x16x32_bf16 v[74:77], v[142:145], v[202:205], v[74:77]
	v_mfma_f32_16x16x32_bf16 v[82:85], v[154:157], v[202:205], v[82:85]
	v_mfma_f32_16x16x32_bf16 v[42:45], v[142:145], v[218:221], v[42:45]
	v_mfma_f32_16x16x32_bf16 v[50:53], v[154:157], v[218:221], v[50:53]
	v_mfma_f32_16x16x32_bf16 v[2:5], v[142:145], v[226:229], v[2:5]
	v_mfma_f32_16x16x32_bf16 v[6:9], v[154:157], v[226:229], v[6:9]
	v_mfma_f32_16x16x32_bf16 v[14:17], v[150:153], v[198:201], v[14:17]
	v_mfma_f32_16x16x32_bf16 v[26:29], v[158:161], v[198:201], v[26:29]
	v_mfma_f32_16x16x32_bf16 v[74:77], v[150:153], v[206:209], v[74:77]
	v_mfma_f32_16x16x32_bf16 v[82:85], v[158:161], v[206:209], v[82:85]
	v_mfma_f32_16x16x32_bf16 v[42:45], v[150:153], v[222:225], v[42:45]
	v_mfma_f32_16x16x32_bf16 v[50:53], v[158:161], v[222:225], v[50:53]
	v_mfma_f32_16x16x32_bf16 v[2:5], v[150:153], v[230:233], v[2:5]
	v_mfma_f32_16x16x32_bf16 v[6:9], v[158:161], v[230:233], v[6:9]
	v_mfma_f32_16x16x32_bf16 v[30:33], v[162:165], v[194:197], v[30:33]
	v_mfma_f32_16x16x32_bf16 v[110:113], v[170:173], v[194:197], v[110:113]
	v_mfma_f32_16x16x32_bf16 v[86:89], v[162:165], v[202:205], v[86:89]
	v_mfma_f32_16x16x32_bf16 v[90:93], v[170:173], v[202:205], v[90:93]
	v_mfma_f32_16x16x32_bf16 v[54:57], v[162:165], v[218:221], v[54:57]
	v_mfma_f32_16x16x32_bf16 v[58:61], v[170:173], v[218:221], v[58:61]
	v_mfma_f32_16x16x32_bf16 v[10:13], v[162:165], v[226:229], v[10:13]
	v_mfma_f32_16x16x32_bf16 v[18:21], v[170:173], v[226:229], v[18:21]
	v_mfma_f32_16x16x32_bf16 v[30:33], v[166:169], v[198:201], v[30:33]
	v_mfma_f32_16x16x32_bf16 v[110:113], v[190:193], v[198:201], v[110:113]
	v_mfma_f32_16x16x32_bf16 v[86:89], v[166:169], v[206:209], v[86:89]
	v_mfma_f32_16x16x32_bf16 v[90:93], v[190:193], v[206:209], v[90:93]
	v_mfma_f32_16x16x32_bf16 v[54:57], v[166:169], v[222:225], v[54:57]
	v_mfma_f32_16x16x32_bf16 v[58:61], v[190:193], v[222:225], v[58:61]
	v_mfma_f32_16x16x32_bf16 v[10:13], v[166:169], v[230:233], v[10:13]
	v_mfma_f32_16x16x32_bf16 v[18:21], v[190:193], v[230:233], v[18:21]
	s_barrier
	s_add_u32 s18, s18, 0x100
	s_addc_u32 s19, s19, 0
	s_add_u32 s86, s86, 0x100
	s_addc_u32 s87, s87, 0
	s_cmp_ge_u32 vcc_lo, s48
	s_mov_b32 s20, vcc_lo
	s_cbranch_scc0 .LBB0_598
	s_and_b64 vcc, exec, s[84:85]
	s_cbranch_vccz .LBB0_601
	s_barrier

; #define PG8_STAGE(bufoff, gbase, voff) do { _Pragma("unroll") for (int _i = 0; _i < 2; ++_i) \
;         __builtin_amdgcn_global_load_lds((const unsigned*)((const char*)(gbase) + (voff)[_i]), (LAS unsigned*)(lds + (bufoff) + ldsw + _i * 8192), 16, 0, 0); } while (0)
; #define PG8_LDA(dst, b, h) do { _Pragma("unroll") for (int m = 0; m < 4; ++m) _Pragma("unroll") for (int k = 0; k < 2; ++k) dst[m][k] = *(const LAS bf16x8*)(lds + PG8_SA(b, h) + aoff + m * 2048 + k * 1024); } while (0)
; #define PG8_LDB(dst, b, h) do { _Pragma("unroll") for (int n = 0; n < 2; ++n) _Pragma("unroll") for (int k = 0; k < 2; ++k) dst[n][k] = *(const LAS bf16x8*)(lds + PG8_SB(b, h) + boff + n * 2048 + k * 1024); } while (0)
; #define PG8_MMA(ai, bj, At, Bt) do { __builtin_amdgcn_s_setprio(1); _Pragma("unroll") for (int m = 0; m < 4; ++m) _Pragma("unroll") for (int n = 0; n < 2; ++n) _Pragma("unroll") for (int k = 0; k < 2; ++k) \
;         acc[ai][bj][m][n] = __builtin_amdgcn_mfma_f32_16x16x32_bf16(Bt[n][k], At[m][k], acc[ai][bj][m][n], 0, 0, 0); __builtin_amdgcn_s_setprio(0); } while (0)
; #define PG8_WAIT_V(n) asm volatile("s_waitcnt vmcnt(" #n ")" ::: "memory")
; #define PG8_WAIT_L(n) asm volatile("s_waitcnt lgkmcnt(" #n ")" ::: "memory")
; #define PG8_BAR __builtin_amdgcn_s_barrier()
; #define PG8_SCHED __builtin_amdgcn_sched_barrier(0)
; template <class Epi, class Sched>
; __device__ __forceinline__ void gemm_phase(LAS unsigned char* lds, const Gemm g, const Sched& S, const Epi& E) {
;     ...
;             const bool last = (t == nt - 2);
;             const char* a1 = cA + (size_t)(t + 1) * kstep;
;             const char* a2 = last ? nA : cA + (size_t)(t + 2) * kstep; const char* b2 = last ? nB : cB + (size_t)(t + 2) * kstep;
;             const char* a3 = a2 + kstep; const char* b3 = b2 + kstep;
;             PG8_LDB(B0, 0, 0); PG8_LDB(B1, 0, 1); PG8_SCHED; PG8_LDA(At, 0, 0); PG8_STAGE(PG8_SA(1, 1), a1 + hstepA, voffA);
;             PG8_WAIT_V(8); PG8_WAIT_L(0); PG8_BAR; PG8_MMA(0, 0, At, B0); PG8_MMA(0, 1, At, B1); PG8_BAR; PG8_SCHED;
;             PG8_LDA(At, 0, 1); PG8_STAGE(PG8_SB(0, 0), b2, voffB); PG8_STAGE(PG8_SB(0, 1), b2 + hstepB, voffB); PG8_STAGE(PG8_SA(0, 0), a2, voffA);
;             PG8_WAIT_V(8); PG8_WAIT_L(0); PG8_BAR; PG8_MMA(1, 0, At, B0); PG8_MMA(1, 1, At, B1); PG8_BAR; PG8_SCHED;
.LBB0_640:
	s_add_i32 s87, s20, 2
	s_add_u32 s88, s18, 0x80
	s_addc_u32 s21, s19, 0
	s_add_i32 s90, 0, 0x10000
	s_cmp_eq_u32 s43, s20
	s_cselect_b32 s21, s69, s21
	s_cselect_b32 s20, s68, s88
	s_cselect_b32 s89, s81, s83
	s_cselect_b32 s88, s80, s82
	s_add_i32 s91, 0, 0x14000
	s_add_i32 m0, s30, 0xc000
	s_nop 0
	global_load_lds_dwordx4 v138, s[18:19]
	s_add_i32 m0, s30, 0xe000
	s_nop 0
	global_load_lds_dwordx4 v140, s[18:19]
	ds_read_b128 v[146:149], v255
	ds_read_b128 v[150:153], v255 offset:1024
	ds_read_b128 v[154:157], v255 offset:2048
	ds_read_b128 v[158:161], v255 offset:3072
	ds_read_b128 v[162:165], v255 offset:16384
	ds_read_b128 v[166:169], v255 offset:17408
	ds_read_b128 v[170:173], v255 offset:18432
	ds_read_b128 v[190:193], v255 offset:19456
	ds_read_b128 v[194:197], v144
	ds_read_b128 v[198:201], v144 offset:1024
	ds_read_b128 v[202:205], v144 offset:2048
	ds_read_b128 v[206:209], v144 offset:3072
	ds_read_b128 v[218:221], v144 offset:4096
	ds_read_b128 v[222:225], v144 offset:5120
	ds_read_b128 v[226:229], v144 offset:6144
	ds_read_b128 v[230:233], v144 offset:7168
	s_waitcnt vmcnt(8)
	s_waitcnt lgkmcnt(0)
	s_nop 0
	s_barrier
	s_waitcnt lgkmcnt(0)
	v_mfma_f32_16x16x32_bf16 v[2:5], v[146:149], v[194:197], v[2:5]
	v_mfma_f32_16x16x32_bf16 v[6:9], v[154:157], v[194:197], v[6:9]
	v_mfma_f32_16x16x32_bf16 v[10:13], v[146:149], v[202:205], v[10:13]
	v_mfma_f32_16x16x32_bf16 v[14:17], v[154:157], v[202:205], v[14:17]
	v_mfma_f32_16x16x32_bf16 v[26:29], v[146:149], v[218:221], v[26:29]
	v_mfma_f32_16x16x32_bf16 v[30:33], v[154:157], v[218:221], v[30:33]
	v_mfma_f32_16x16x32_bf16 v[42:45], v[146:149], v[226:229], v[42:45]
	v_mfma_f32_16x16x32_bf16 v[46:49], v[154:157], v[226:229], v[46:49]
	v_mfma_f32_16x16x32_bf16 v[2:5], v[150:153], v[198:201], v[2:5]
	v_mfma_f32_16x16x32_bf16 v[6:9], v[158:161], v[198:201], v[6:9]
	v_mfma_f32_16x16x32_bf16 v[10:13], v[150:153], v[206:209], v[10:13]
	v_mfma_f32_16x16x32_bf16 v[14:17], v[158:161], v[206:209], v[14:17]
	v_mfma_f32_16x16x32_bf16 v[26:29], v[150:153], v[222:225], v[26:29]
	v_mfma_f32_16x16x32_bf16 v[30:33], v[158:161], v[222:225], v[30:33]
	v_mfma_f32_16x16x32_bf16 v[42:45], v[150:153], v[230:233], v[42:45]
	v_mfma_f32_16x16x32_bf16 v[46:49], v[158:161], v[230:233], v[46:49]
	v_mfma_f32_16x16x32_bf16 v[18:21], v[162:165], v[194:197], v[18:21]
	v_mfma_f32_16x16x32_bf16 v[22:25], v[170:173], v[194:197], v[22:25]
	v_mfma_f32_16x16x32_bf16 v[34:37], v[162:165], v[202:205], v[34:37]
	v_mfma_f32_16x16x32_bf16 v[38:41], v[170:173], v[202:205], v[38:41]
	v_mfma_f32_16x16x32_bf16 v[50:53], v[162:165], v[218:221], v[50:53]
	v_mfma_f32_16x16x32_bf16 v[54:57], v[170:173], v[218:221], v[54:57]
	v_mfma_f32_16x16x32_bf16 v[58:61], v[162:165], v[226:229], v[58:61]
	v_mfma_f32_16x16x32_bf16 v[66:69], v[170:173], v[226:229], v[66:69]
	v_mfma_f32_16x16x32_bf16 v[18:21], v[166:169], v[198:201], v[18:21]
	v_mfma_f32_16x16x32_bf16 v[22:25], v[190:193], v[198:201], v[22:25]
	v_mfma_f32_16x16x32_bf16 v[34:37], v[166:169], v[206:209], v[34:37]
	v_mfma_f32_16x16x32_bf16 v[38:41], v[190:193], v[206:209], v[38:41]
	v_mfma_f32_16x16x32_bf16 v[50:53], v[166:169], v[222:225], v[50:53]
	v_mfma_f32_16x16x32_bf16 v[54:57], v[190:193], v[222:225], v[54:57]
	v_mfma_f32_16x16x32_bf16 v[58:61], v[166:169], v[230:233], v[58:61]
	v_mfma_f32_16x16x32_bf16 v[66:69], v[190:193], v[230:233], v[66:69]
	s_barrier
	s_add_i32 s90, s90, s29
	s_add_u32 s98, s88, 0x80
	s_addc_u32 s99, s89, 0
	s_add_u32 s100, s20, 0x80
	s_addc_u32 s101, s21, 0
	s_mov_b32 m0, s90
	s_nop 0
	global_load_lds_dwordx4 v132, s[88:89]
	s_add_i32 m0, s90, 0x2000
	s_add_i32 s90, s91, s29
	global_load_lds_dwordx4 v136, s[88:89]
	s_add_u32 s88, s88, s8
	s_addc_u32 s89, s89, 0
	s_mov_b32 m0, s90
	s_nop 0
	global_load_lds_dwordx4 v132, s[88:89]
	s_add_i32 m0, s90, 0x2000
	s_nop 0
	global_load_lds_dwordx4 v136, s[88:89]
	s_mov_b32 m0, s30
	s_nop 0
	global_load_lds_dwordx4 v130, s[20:21]
	s_mov_b32 m0, s31
	s_nop 0
	global_load_lds_dwordx4 v134, s[20:21]
	ds_read_b128 v[194:197], v144 offset:16384
	ds_read_b128 v[198:201], v144 offset:17408
	ds_read_b128 v[202:205], v144 offset:18432
	ds_read_b128 v[206:209], v144 offset:19456
	ds_read_b128 v[218:221], v144 offset:20480
	ds_read_b128 v[222:225], v144 offset:21504
	ds_read_b128 v[226:229], v144 offset:22528
	ds_read_b128 v[230:233], v144 offset:23552
	s_waitcnt vmcnt(8)
	s_waitcnt lgkmcnt(0)
	s_barrier
	s_waitcnt lgkmcnt(0)
	v_mfma_f32_16x16x32_bf16 v[62:65], v[146:149], v[194:197], v[62:65]
	v_mfma_f32_16x16x32_bf16 v[70:73], v[154:157], v[194:197], v[70:73]
	v_mfma_f32_16x16x32_bf16 v[78:81], v[146:149], v[202:205], v[78:81]
	v_mfma_f32_16x16x32_bf16 v[82:85], v[154:157], v[202:205], v[82:85]
	v_mfma_f32_16x16x32_bf16 v[90:93], v[146:149], v[218:221], v[90:93]
	v_mfma_f32_16x16x32_bf16 v[94:97], v[154:157], v[218:221], v[94:97]
	v_mfma_f32_16x16x32_bf16 v[106:109], v[146:149], v[226:229], v[106:109]
	v_mfma_f32_16x16x32_bf16 v[110:113], v[154:157], v[226:229], v[110:113]
	v_mfma_f32_16x16x32_bf16 v[62:65], v[150:153], v[198:201], v[62:65]
	v_mfma_f32_16x16x32_bf16 v[70:73], v[158:161], v[198:201], v[70:73]
	v_mfma_f32_16x16x32_bf16 v[78:81], v[150:153], v[206:209], v[78:81]
	v_mfma_f32_16x16x32_bf16 v[82:85], v[158:161], v[206:209], v[82:85]
	v_mfma_f32_16x16x32_bf16 v[90:93], v[150:153], v[222:225], v[90:93]
	v_mfma_f32_16x16x32_bf16 v[94:97], v[158:161], v[222:225], v[94:97]
	v_mfma_f32_16x16x32_bf16 v[106:109], v[150:153], v[230:233], v[106:109]
	v_mfma_f32_16x16x32_bf16 v[110:113], v[158:161], v[230:233], v[110:113]
	v_mfma_f32_16x16x32_bf16 v[74:77], v[162:165], v[194:197], v[74:77]
	v_mfma_f32_16x16x32_bf16 v[86:89], v[170:173], v[194:197], v[86:89]
	v_mfma_f32_16x16x32_bf16 v[98:101], v[162:165], v[202:205], v[98:101]
	v_mfma_f32_16x16x32_bf16 v[102:105], v[170:173], v[202:205], v[102:105]
	v_mfma_f32_16x16x32_bf16 v[114:117], v[162:165], v[218:221], v[114:117]
	v_mfma_f32_16x16x32_bf16 v[118:121], v[170:173], v[218:221], v[118:121]
	v_mfma_f32_16x16x32_bf16 v[122:125], v[162:165], v[226:229], v[122:125]
	v_mfma_f32_16x16x32_bf16 v[126:129], v[170:173], v[226:229], v[126:129]
	v_mfma_f32_16x16x32_bf16 v[74:77], v[166:169], v[198:201], v[74:77]
	v_mfma_f32_16x16x32_bf16 v[86:89], v[190:193], v[198:201], v[86:89]
	v_mfma_f32_16x16x32_bf16 v[98:101], v[166:169], v[206:209], v[98:101]
	v_mfma_f32_16x16x32_bf16 v[102:105], v[190:193], v[206:209], v[102:105]
	v_mfma_f32_16x16x32_bf16 v[114:117], v[166:169], v[222:225], v[114:117]
	v_mfma_f32_16x16x32_bf16 v[118:121], v[190:193], v[222:225], v[118:121]
	v_mfma_f32_16x16x32_bf16 v[122:125], v[166:169], v[230:233], v[122:125]
	v_mfma_f32_16x16x32_bf16 v[126:129], v[190:193], v[230:233], v[126:129]
	s_barrier
; #define PG8_STAGE(bufoff, gbase, voff) do { _Pragma("unroll") for (int _i = 0; _i < 2; ++_i) \
;         __builtin_amdgcn_global_load_lds((const unsigned*)((const char*)(gbase) + (voff)[_i]), (LAS unsigned*)(lds + (bufoff) + ldsw + _i * 8192), 16, 0, 0); } while (0)
; #define PG8_LDA(dst, b, h) do { _Pragma("unroll") for (int m = 0; m < 4; ++m) _Pragma("unroll") for (int k = 0; k < 2; ++k) dst[m][k] = *(const LAS bf16x8*)(lds + PG8_SA(b, h) + aoff + m * 2048 + k * 1024); } while (0)
; #define PG8_LDB(dst, b, h) do { _Pragma("unroll") for (int n = 0; n < 2; ++n) _Pragma("unroll") for (int k = 0; k < 2; ++k) dst[n][k] = *(const LAS bf16x8*)(lds + PG8_SB(b, h) + boff + n * 2048 + k * 1024); } while (0)
; #define PG8_MMA(ai, bj, At, Bt) do { __builtin_amdgcn_s_setprio(1); _Pragma("unroll") for (int m = 0; m < 4; ++m) _Pragma("unroll") for (int n = 0; n < 2; ++n) _Pragma("unroll") for (int k = 0; k < 2; ++k) \
;         acc[ai][bj][m][n] = __builtin_amdgcn_mfma_f32_16x16x32_bf16(Bt[n][k], At[m][k], acc[ai][bj][m][n], 0, 0, 0); __builtin_amdgcn_s_setprio(0); } while (0)
; #define PG8_WAIT_V(n) asm volatile("s_waitcnt vmcnt(" #n ")" ::: "memory")
; #define PG8_WAIT_L(n) asm volatile("s_waitcnt lgkmcnt(" #n ")" ::: "memory")
; #define PG8_BAR __builtin_amdgcn_s_barrier()
; #define PG8_SCHED __builtin_amdgcn_sched_barrier(0)
; template <class Epi, class Sched>
; __device__ __forceinline__ void gemm_phase(LAS unsigned char* lds, const Gemm g, const Sched& S, const Epi& E) {
;     ...
;             PG8_LDB(B0, 1, 0); PG8_LDB(B1, 1, 1); PG8_SCHED; PG8_LDA(At, 1, 0); PG8_STAGE(PG8_SA(0, 1), a2 + hstepA, voffA);
;             PG8_WAIT_V(8); PG8_WAIT_L(0); PG8_BAR; PG8_MMA(0, 0, At, B0); PG8_MMA(0, 1, At, B1); PG8_BAR; PG8_SCHED;
;             PG8_LDA(At, 1, 1); PG8_STAGE(PG8_SB(1, 0), b3, voffB); PG8_STAGE(PG8_SB(1, 1), b3 + hstepB, voffB); PG8_STAGE(PG8_SA(1, 0), a3, voffA);
;             PG8_WAIT_V(8); PG8_WAIT_L(0); PG8_BAR; PG8_MMA(1, 0, At, B0); PG8_MMA(1, 1, At, B1); PG8_BAR; PG8_SCHED;
;         }
;         if (wr == 0) PG8_BAR;
	s_add_u32 s20, s20, s54
	s_addc_u32 s21, s21, 0
	s_mov_b32 m0, s34
	s_nop 0
	global_load_lds_dwordx4 v130, s[20:21]
	s_mov_b32 m0, s35
	s_nop 0
	global_load_lds_dwordx4 v134, s[20:21]
	ds_read_b128 v[146:149], v255 offset:32768
	ds_read_b128 v[150:153], v255 offset:33792
	ds_read_b128 v[154:157], v255 offset:34816
	ds_read_b128 v[158:161], v255 offset:35840
	ds_read_b128 v[162:165], v255 offset:49152
	ds_read_b128 v[166:169], v255 offset:50176
	ds_read_b128 v[170:173], v255 offset:51200
	ds_read_b128 v[190:193], v255 offset:52224
	ds_read_b128 v[194:197], v144 offset:32768
	ds_read_b128 v[198:201], v144 offset:33792
	ds_read_b128 v[202:205], v144 offset:34816
	ds_read_b128 v[206:209], v144 offset:35840
	ds_read_b128 v[218:221], v144 offset:36864
	ds_read_b128 v[222:225], v144 offset:37888
	ds_read_b128 v[226:229], v144 offset:38912
	ds_read_b128 v[230:233], v144 offset:39936
	s_waitcnt vmcnt(8)
	s_waitcnt lgkmcnt(0)
	s_nop 0
	s_barrier
	s_waitcnt lgkmcnt(0)
	v_mfma_f32_16x16x32_bf16 v[2:5], v[146:149], v[194:197], v[2:5]
	v_mfma_f32_16x16x32_bf16 v[6:9], v[154:157], v[194:197], v[6:9]
	v_mfma_f32_16x16x32_bf16 v[10:13], v[146:149], v[202:205], v[10:13]
	v_mfma_f32_16x16x32_bf16 v[14:17], v[154:157], v[202:205], v[14:17]
	v_mfma_f32_16x16x32_bf16 v[26:29], v[146:149], v[218:221], v[26:29]
	v_mfma_f32_16x16x32_bf16 v[30:33], v[154:157], v[218:221], v[30:33]
	v_mfma_f32_16x16x32_bf16 v[42:45], v[146:149], v[226:229], v[42:45]
	v_mfma_f32_16x16x32_bf16 v[46:49], v[154:157], v[226:229], v[46:49]
	v_mfma_f32_16x16x32_bf16 v[2:5], v[150:153], v[198:201], v[2:5]
	v_mfma_f32_16x16x32_bf16 v[6:9], v[158:161], v[198:201], v[6:9]
	v_mfma_f32_16x16x32_bf16 v[10:13], v[150:153], v[206:209], v[10:13]
	v_mfma_f32_16x16x32_bf16 v[14:17], v[158:161], v[206:209], v[14:17]
	v_mfma_f32_16x16x32_bf16 v[26:29], v[150:153], v[222:225], v[26:29]
	v_mfma_f32_16x16x32_bf16 v[30:33], v[158:161], v[222:225], v[30:33]
	v_mfma_f32_16x16x32_bf16 v[42:45], v[150:153], v[230:233], v[42:45]
	v_mfma_f32_16x16x32_bf16 v[46:49], v[158:161], v[230:233], v[46:49]
	v_mfma_f32_16x16x32_bf16 v[18:21], v[162:165], v[194:197], v[18:21]
	v_mfma_f32_16x16x32_bf16 v[22:25], v[170:173], v[194:197], v[22:25]
	v_mfma_f32_16x16x32_bf16 v[34:37], v[162:165], v[202:205], v[34:37]
	v_mfma_f32_16x16x32_bf16 v[38:41], v[170:173], v[202:205], v[38:41]
	v_mfma_f32_16x16x32_bf16 v[50:53], v[162:165], v[218:221], v[50:53]
	v_mfma_f32_16x16x32_bf16 v[54:57], v[170:173], v[218:221], v[54:57]
	v_mfma_f32_16x16x32_bf16 v[58:61], v[162:165], v[226:229], v[58:61]
	v_mfma_f32_16x16x32_bf16 v[66:69], v[170:173], v[226:229], v[66:69]
	v_mfma_f32_16x16x32_bf16 v[18:21], v[166:169], v[198:201], v[18:21]
	v_mfma_f32_16x16x32_bf16 v[22:25], v[190:193], v[198:201], v[22:25]
	v_mfma_f32_16x16x32_bf16 v[34:37], v[166:169], v[206:209], v[34:37]
	v_mfma_f32_16x16x32_bf16 v[38:41], v[190:193], v[206:209], v[38:41]
	v_mfma_f32_16x16x32_bf16 v[50:53], v[166:169], v[222:225], v[50:53]
	v_mfma_f32_16x16x32_bf16 v[54:57], v[190:193], v[222:225], v[54:57]
	v_mfma_f32_16x16x32_bf16 v[58:61], v[166:169], v[230:233], v[58:61]
	v_mfma_f32_16x16x32_bf16 v[66:69], v[190:193], v[230:233], v[66:69]
	s_barrier
	s_add_i32 s20, s29, 0x18000
	s_mov_b32 m0, s20
	s_nop 0
	global_load_lds_dwordx4 v132, s[98:99]
	s_add_i32 m0, s20, 0x2000
	s_add_i32 s20, s29, 0x1c000
	global_load_lds_dwordx4 v136, s[98:99]
	s_add_u32 s98, s98, s8
	s_addc_u32 s99, s99, 0
	s_mov_b32 m0, s20
	s_nop 0
	global_load_lds_dwordx4 v132, s[98:99]
	s_add_i32 m0, s20, 0x2000
	s_nop 0
	global_load_lds_dwordx4 v136, s[98:99]
	s_mov_b32 m0, s40
	s_nop 0
	global_load_lds_dwordx4 v130, s[100:101]
	s_mov_b32 m0, s41
	s_nop 0
	global_load_lds_dwordx4 v134, s[100:101]
	ds_read_b128 v[194:197], v144 offset:49152
	ds_read_b128 v[198:201], v144 offset:50176
	ds_read_b128 v[202:205], v144 offset:51200
	ds_read_b128 v[206:209], v144 offset:52224
	ds_read_b128 v[218:221], v144 offset:53248
	ds_read_b128 v[222:225], v144 offset:54272
	ds_read_b128 v[226:229], v144 offset:55296
	ds_read_b128 v[230:233], v144 offset:56320
	s_waitcnt vmcnt(8)
	s_waitcnt lgkmcnt(0)
	s_barrier
	s_waitcnt lgkmcnt(0)
	v_mfma_f32_16x16x32_bf16 v[62:65], v[146:149], v[194:197], v[62:65]
	v_mfma_f32_16x16x32_bf16 v[70:73], v[154:157], v[194:197], v[70:73]
	v_mfma_f32_16x16x32_bf16 v[78:81], v[146:149], v[202:205], v[78:81]
	v_mfma_f32_16x16x32_bf16 v[82:85], v[154:157], v[202:205], v[82:85]
	v_mfma_f32_16x16x32_bf16 v[90:93], v[146:149], v[218:221], v[90:93]
	v_mfma_f32_16x16x32_bf16 v[94:97], v[154:157], v[218:221], v[94:97]
	v_mfma_f32_16x16x32_bf16 v[106:109], v[146:149], v[226:229], v[106:109]
	v_mfma_f32_16x16x32_bf16 v[110:113], v[154:157], v[226:229], v[110:113]
	v_mfma_f32_16x16x32_bf16 v[62:65], v[150:153], v[198:201], v[62:65]
	v_mfma_f32_16x16x32_bf16 v[70:73], v[158:161], v[198:201], v[70:73]
	v_mfma_f32_16x16x32_bf16 v[78:81], v[150:153], v[206:209], v[78:81]
	v_mfma_f32_16x16x32_bf16 v[82:85], v[158:161], v[206:209], v[82:85]
	v_mfma_f32_16x16x32_bf16 v[90:93], v[150:153], v[222:225], v[90:93]
	v_mfma_f32_16x16x32_bf16 v[94:97], v[158:161], v[222:225], v[94:97]
	v_mfma_f32_16x16x32_bf16 v[106:109], v[150:153], v[230:233], v[106:109]
	v_mfma_f32_16x16x32_bf16 v[110:113], v[158:161], v[230:233], v[110:113]
	v_mfma_f32_16x16x32_bf16 v[74:77], v[162:165], v[194:197], v[74:77]
	v_mfma_f32_16x16x32_bf16 v[86:89], v[170:173], v[194:197], v[86:89]
	v_mfma_f32_16x16x32_bf16 v[98:101], v[162:165], v[202:205], v[98:101]
	v_mfma_f32_16x16x32_bf16 v[102:105], v[170:173], v[202:205], v[102:105]
	v_mfma_f32_16x16x32_bf16 v[114:117], v[162:165], v[218:221], v[114:117]
	v_mfma_f32_16x16x32_bf16 v[118:121], v[170:173], v[218:221], v[118:121]
	v_mfma_f32_16x16x32_bf16 v[122:125], v[162:165], v[226:229], v[122:125]
	v_mfma_f32_16x16x32_bf16 v[126:129], v[170:173], v[226:229], v[126:129]
	v_mfma_f32_16x16x32_bf16 v[74:77], v[166:169], v[198:201], v[74:77]
	v_mfma_f32_16x16x32_bf16 v[86:89], v[190:193], v[198:201], v[86:89]
	v_mfma_f32_16x16x32_bf16 v[98:101], v[166:169], v[206:209], v[98:101]
	v_mfma_f32_16x16x32_bf16 v[102:105], v[190:193], v[206:209], v[102:105]
	v_mfma_f32_16x16x32_bf16 v[114:117], v[166:169], v[222:225], v[114:117]
	v_mfma_f32_16x16x32_bf16 v[118:121], v[190:193], v[222:225], v[118:121]
	v_mfma_f32_16x16x32_bf16 v[122:125], v[166:169], v[230:233], v[122:125]
	v_mfma_f32_16x16x32_bf16 v[126:129], v[190:193], v[230:233], v[126:129]
	s_barrier
	s_add_u32 s18, s18, 0x100
	s_addc_u32 s19, s19, 0
	s_add_u32 s82, s82, 0x100
	s_addc_u32 s83, s83, 0
	s_cmp_ge_u32 s87, s42
	s_mov_b32 s20, s87
	s_cbranch_scc0 .LBB0_640
	s_and_b64 vcc, exec, s[70:71]
	s_cbranch_vccz .LBB0_643
	s_barrier
